# speedup vs baseline: 1.0114x; 1.0072x over previous
; __device__ __forceinline__ void gemm_phase(KP p, char* shmc, const u16* __restrict__ A,
;                                            const u16* __restrict__ Bt, const int N, const int K, const int mode,
;                                            const float* __restrict__ xin, const float resw) {
;     ...
;     const int ntix = tix + gridDim.x;
;     int nbrow = 0, nbcol = 0, npn = 0;
;     if (ntix < nwg) {
;       TILE_MAP(ntix, nbrow, nbcol, npn);
.LBB0_47:
	v_mov_b32_e32 v217, v210
	s_waitcnt vmcnt(0)
	s_nop 0
	v_ashrrev_i32_e32 v0, 8, v217
	s_add_i32 s66, s66, s3
	s_cmp_ge_i32 s66, s51
	s_cselect_b64 s[6:7], -1, 0
	s_mov_b32 s26, 0
	s_and_b64 vcc, exec, s[6:7]
	s_mov_b32 s45, 0
	s_mov_b32 s44, 0
	s_cbranch_vccnz .Lmy_nomap
	s_ashr_i32 s8, s66, 31
	s_lshr_b32 s8, s8, 29
	s_add_i32 s8, s66, s8
	s_ashr_i32 s9, s8, 3
	s_and_b32 s8, s8, -8
	s_sub_i32 s8, s66, s8
	s_lshr_b32 s26, s8, 31
	s_or_b32 s26, s26, s68
	s_mul_i32 s8, s26, s8
	s_add_i32 s8, s8, s9
	s_abs_i32 s26, s8
	s_mul_hi_u32 s27, s26, s69
	s_mul_i32 s36, s27, s81
	s_sub_i32 s26, s26, s36
	s_ashr_i32 s9, s8, 31
	s_add_i32 s36, s27, 1
	s_sub_i32 s37, s26, s81
	s_cmp_ge_u32 s26, s81
	s_cselect_b32 s27, s36, s27
	s_cselect_b32 s26, s37, s26
	s_add_i32 s36, s27, 1
	s_cmp_ge_u32 s26, s81
	s_cselect_b32 s26, s36, s27
	s_xor_b32 s26, s26, s9
	s_sub_i32 s9, s26, s9
	s_lshl_b32 s26, s9, 2
	s_sub_i32 s27, 64, s26
	s_min_i32 s27, s27, 4
	s_abs_i32 s36, s27
	v_cvt_f32_u32_e32 v130, s36
	s_sub_i32 s38, 0, s36
	s_mul_i32 s9, s9, s81
	s_sub_i32 s8, s8, s9
	v_rcp_iflag_f32_e32 v130, v130
	s_abs_i32 s37, s8
	s_xor_b32 s9, s8, s27
	s_ashr_i32 s9, s9, 31
	v_mul_f32_e32 v130, 0x4f7ffffe, v130
	v_cvt_u32_f32_e32 v130, v130
	s_nop 0
	v_readfirstlane_b32 s39, v130
	s_mul_i32 s38, s38, s39
	s_mul_hi_u32 s38, s39, s38
	s_add_i32 s39, s39, s38
	s_mul_hi_u32 s38, s37, s39
	s_mul_i32 s39, s38, s36
	s_sub_i32 s37, s37, s39
	s_add_i32 s39, s38, 1
	s_sub_i32 s40, s37, s36
	s_cmp_ge_u32 s37, s36
	s_cselect_b32 s38, s39, s38
	s_cselect_b32 s37, s40, s37
	s_add_i32 s39, s38, 1
	s_cmp_ge_u32 s37, s36
	s_cselect_b32 s36, s39, s38
	s_xor_b32 s36, s36, s9
	s_sub_i32 s44, s36, s9
	s_mul_i32 s9, s44, s27
	s_sub_i32 s8, s8, s9
	s_add_i32 s8, s8, s26
	s_lshl_b32 s45, s44, 8
	s_lshl_b32 s26, s8, 8
.Lmy_nomap:
	v_mov_b32_e32 v248, s26
	v_mov_b32_e32 v249, s45
	v_mov_b32_e32 v250, s44
	v_bfe_i32 v2, v217, 27, 1
	v_lshlrev_b32_e32 v135, 4, v217
	v_lshrrev_b32_e32 v2, 22, v2
	s_add_i32 s6, s24, 0x80
	v_add_u32_e32 v2, v135, v2
	s_mul_hi_i32 s7, s6, s50
	s_mul_i32 s6, s6, s50
	v_and_b32_e32 v2, 0xfffffc00, v2
	s_lshl_b64 s[6:7], s[6:7], 1
	v_sub_u32_e32 v2, v135, v2
	s_add_u32 s8, s12, s6
	s_mul_hi_i32 s27, s28, s50
	s_mul_i32 s26, s28, s50
	v_ashrrev_i32_e32 v1, 31, v217
	v_lshrrev_b32_e32 v3, 4, v2
	s_addc_u32 s9, s13, s7
	s_ashr_i32 s29, s28, 31
	s_lshl_b64 s[26:27], s[26:27], 1
	v_lshrrev_b32_e32 v1, 26, v1
	v_bitop3_b32 v2, v3, v2, 32 bitop3:0x6c
	s_add_u32 s26, s14, s26
	s_mul_hi_i32 s31, s24, s50
	s_mul_i32 s30, s24, s50
	v_add_u32_e32 v1, v217, v1
	v_ashrrev_i32_e32 v4, 31, v2
	s_addc_u32 s27, s15, s27
	s_ashr_i32 s25, s24, 31
	s_lshl_b64 s[30:31], s[30:31], 1
	v_ashrrev_i32_e32 v1, 6, v1
	v_lshrrev_b32_e32 v4, 26, v4
	s_add_u32 s36, s12, s30
	v_lshlrev_b32_e32 v3, 3, v1
	v_add_u32_e32 v4, v2, v4
	s_addc_u32 s37, s13, s31
	s_add_i32 s30, s28, 0x80
	v_and_b32_e32 v3, -16, v3
	v_ashrrev_i32_e32 v5, 6, v4
	s_mul_hi_i32 s31, s30, s50
	s_mul_i32 s30, s30, s50
	v_add_u32_e32 v3, v5, v3
	s_lshl_b64 s[30:31], s[30:31], 1
	v_mul_lo_u32 v138, v3, s50
	v_and_b32_e32 v3, 48, v217
	s_add_u32 s38, s14, s30
	v_lshlrev_b32_e32 v8, 6, v217
	s_movk_i32 s30, 0x3c0
	s_addc_u32 s39, s15, s31
	v_lshlrev_b32_e32 v10, 13, v0
	v_and_or_b32 v0, v8, s30, v3
	s_lshl_b64 s[30:31], s[28:29], 1
	s_add_u32 s40, s30, 0x80
	s_addc_u32 s41, s31, 0
	s_mul_i32 s41, s50, s41
	s_mul_hi_u32 s42, s50, s40
	s_add_i32 s42, s42, s41
	s_mul_i32 s40, s50, s40
	s_add_u32 s40, s14, s40
	s_addc_u32 s41, s15, s42
	s_lshl_b64 s[46:47], s[24:25], 1
	s_add_u32 s42, s46, 0x80
	s_addc_u32 s43, s47, 0
	s_mul_i32 s43, s50, s43
	s_mul_hi_u32 s44, s50, s42
	s_add_i32 s44, s44, s43
	s_mul_i32 s42, s50, s42
	s_add_u32 s42, s12, s42
	s_addc_u32 s43, s13, s44
	s_add_u32 s44, s30, 0x180
	s_addc_u32 s45, s31, 0
	v_lshlrev_b32_e32 v1, 5, v1
	s_mul_i32 s45, s50, s45
	s_mul_hi_u32 vcc_lo, s50, s44
	v_and_b32_e32 v137, 32, v1
	v_and_b32_e32 v1, 0xc0, v4
	s_add_i32 vcc_lo, vcc_lo, s45
	s_mul_i32 s44, s50, s44
	v_sub_u32_e32 v1, v2, v1
	s_add_u32 s44, s14, s44
	v_ashrrev_i16_sdwa v1, v212, sext(v1) dst_sel:DWORD dst_unused:UNUSED_PAD src0_sel:DWORD src1_sel:BYTE_0
	v_and_b32_e32 v2, 15, v217
	s_addc_u32 s45, s15, vcc_lo
	v_bfe_i32 v139, v1, 0, 16
	v_lshlrev_b32_e32 v1, 6, v2
	v_lshlrev_b32_e32 v2, 2, v217
	s_add_u32 s46, s46, 0x180
	v_and_b32_e32 v2, 32, v2
	s_addc_u32 s47, s47, 0
	v_bitop3_b32 v1, v1, v2, v3 bitop3:0x36
	v_xad_u32 v2, v0, v2, 0
	v_add3_u32 v0, v138, v137, v139
	s_mul_i32 s47, s50, s47
	s_mul_hi_u32 vcc_lo, s50, s46
	v_add_u32_e32 v4, s83, v1
	v_add_u32_e32 v5, s84, v1
	v_add_u32_e32 v6, s85, v1
	v_add_u32_e32 v7, s86, v1
	v_add_u32_e32 v11, 0, v1
	v_ashrrev_i32_e32 v1, 31, v0
	s_add_i32 vcc_lo, vcc_lo, s47
	s_mul_i32 s46, s50, s46
	v_and_b32_e32 v9, 0x3000, v8
	v_or_b32_e32 v3, 0x800, v10
	v_or_b32_e32 v8, 0x1000, v10
	v_or_b32_e32 v12, 0x1800, v10
	s_waitcnt lgkmcnt(0)
	v_lshlrev_b64 v[128:129], 1, v[0:1]
	s_add_u32 s46, s12, s46
	v_mov_b32_e32 v0, 0
	s_addc_u32 s47, s13, vcc_lo
	s_mov_b32 vcc_lo, 0
	v_add_u32_e32 v141, v4, v9
	v_add_u32_e32 v133, v11, v10
	v_add_u32_e32 v132, v2, v3
	v_add_u32_e32 v131, v2, v8
	v_add_u32_e32 v130, v2, v12
	v_add_u32_e32 v140, v5, v9
	v_add_u32_e32 v136, v6, v9
	v_add_u32_e32 v134, v7, v9
	v_mov_b32_e32 v234, v133
	v_mov_b32_e32 v235, v141
	v_mov_b32_e32 v236, v128
	v_add_u32_e32 v237, s72, v128
	v_lshrrev_b32_e32 v238, 6, v210
	v_lshlrev_b32_e32 v238, 10, v238
	s_lshr_b32 s41, s50, 7
	s_add_i32 s41, s41, -2
	v_readfirstlane_b32 s40, v238
	v_readfirstlane_b32 s43, v248
	v_readfirstlane_b32 s46, v249
	v_readfirstlane_b32 s47, v250
	s_add_u32 s8, s8, 0x80
	s_addc_u32 s9, s9, 0
	s_bitcmp0_b32 s101, 31
	s_cbranch_scc1 .Lmy_noextra
	s_add_u32 m0, s40, 0xc000
	s_nop 0
	global_load_lds_dwordx4 v236, s[8:9]
	s_add_u32 m0, s40, 0xe000
	s_nop 0
	global_load_lds_dwordx4 v237, s[8:9]
	s_bitset0_b32 s101, 31

; #define STAGE(P, BASE, br, kt) do { const u16* _gb = (BASE) + ((size_t)(br) * K + (size_t)(kt) * BK); \
;     __builtin_amdgcn_global_load_lds((const unsigned*)(_gb + goff0), (unsigned*)((char*)(P) + tid * 16), 16, 0, 0); \
;     __builtin_amdgcn_global_load_lds((const unsigned*)(_gb + (size_t)64 * K + goff0), (unsigned*)((char*)(P) + tid * 16 + 8192), 16, 0, 0); } while (0)
; #define LDA(dst, b, h) _Pragma("unroll") for (int m = 0; m < 4; ++m) _Pragma("unroll") for (int k = 0; k < 2; ++k) \
;     dst[m][k] = *reinterpret_cast<const bf16x8*>((char*)SA(b, h) + lds_byte(wr * 64 + m * 16 + fr, k * 32 + fq * 8))
; #define LDB(dst, b, h) _Pragma("unroll") for (int n = 0; n < 2; ++n) _Pragma("unroll") for (int k = 0; k < 2; ++k) \
;     dst[n][k] = *reinterpret_cast<const bf16x8*>((char*)SB(b, h) + lds_byte(wc * 32 + n * 16 + fr, k * 32 + fq * 8))
; #define WAIT_V(n) asm volatile("s_waitcnt vmcnt(" #n ")" ::: "memory")
; #define WAIT_L(n) asm volatile("s_waitcnt lgkmcnt(" #n ")" ::: "memory")
; #define BAR __builtin_amdgcn_s_barrier()
; #define SCHED __builtin_amdgcn_sched_barrier(0)
; __device__ __forceinline__ void gemm_phase(KP p, char* shmc, const u16* __restrict__ A,
;                                            const u16* __restrict__ Bt, const int N, const int K, const int mode,
;                                            const float* __restrict__ xin, const float resw) {
;     ...
;     for (int t = 0; t < nt - 2; t += 2) {
;       LDB(B0, 0, 0); SCHED; LDA(At, 0, 0); STAGE(SA(1, 1), A, brow + HALF, t + 1);
;       WAIT_L(8); BAR; WAIT_L(0); MMA(0, 0, At, B0); BAR; SCHED;
;       LDB(B1, 0, 1); STAGE(SB(0, 0), Bt, bcol, t + 2);
;       BAR; WAIT_L(0); MMA(0, 1, At, B1); BAR;
;       LDA(At, 0, 1); STAGE(SA(0, 0), A, brow, t + 2);
;       BAR; WAIT_L(0); MMA(1, 0, At, B0); BAR; SCHED;
;       STAGE(SB(0, 1), Bt, bcol + HALF, t + 2);
;       WAIT_V(6); BAR; MMA(1, 1, At, B1); BAR;
;       LDB(B0, 1, 0); SCHED; LDA(At, 1, 0); STAGE(SA(0, 1), A, brow + HALF, t + 2);
;       WAIT_L(8); BAR; WAIT_L(0); MMA(0, 0, At, B0); BAR; SCHED;
;       LDB(B1, 1, 1); STAGE(SB(1, 0), Bt, bcol, t + 3);
;       BAR; WAIT_L(0); MMA(0, 1, At, B1); BAR;
;       LDA(At, 1, 1); STAGE(SA(1, 0), A, brow, t + 3);
;       BAR; WAIT_L(0); MMA(1, 0, At, B0); BAR; SCHED;
;       STAGE(SB(1, 1), Bt, bcol + HALF, t + 3);
;       WAIT_V(6); BAR; MMA(1, 1, At, B1); BAR;
;     }
.Lmy_kloop:
	s_waitcnt vmcnt(12) lgkmcnt(0)
	s_barrier
	v_mfma_f32_16x16x32_bf16 v[120:123], v[194:197], v[128:131], v[120:123]
	v_mfma_f32_16x16x32_bf16 v[112:115], v[202:205], v[128:131], v[112:115]
	ds_read_b128 v[218:221], v235 offset:16384
	v_mfma_f32_16x16x32_bf16 v[104:107], v[194:197], v[136:139], v[104:107]
	ds_read_b128 v[222:225], v235 offset:17408
	v_mfma_f32_16x16x32_bf16 v[96:99], v[202:205], v[136:139], v[96:99]
	ds_read_b128 v[226:229], v235 offset:18432
	s_add_u32 m0, s40, 0x10000
	v_mfma_f32_16x16x32_bf16 v[88:91], v[194:197], v[144:147], v[88:91]
	ds_read_b128 v[230:233], v235 offset:19456
	v_mfma_f32_16x16x32_bf16 v[80:83], v[202:205], v[144:147], v[80:83]
	global_load_lds_dwordx4 v236, s[26:27]
	v_mfma_f32_16x16x32_bf16 v[72:75], v[194:197], v[152:155], v[72:75]
	v_mfma_f32_16x16x32_bf16 v[64:67], v[202:205], v[152:155], v[64:67]
	s_add_u32 m0, s40, 0x12000
	v_mfma_f32_16x16x32_bf16 v[120:123], v[198:201], v[132:135], v[120:123]
	v_mfma_f32_16x16x32_bf16 v[112:115], v[206:209], v[132:135], v[112:115]
	global_load_lds_dwordx4 v237, s[26:27]
	v_mfma_f32_16x16x32_bf16 v[104:107], v[198:201], v[140:143], v[104:107]
	v_mfma_f32_16x16x32_bf16 v[96:99], v[206:209], v[140:143], v[96:99]
	s_add_u32 s26, s26, 0x80
	s_addc_u32 s27, s27, 0
	v_mfma_f32_16x16x32_bf16 v[88:91], v[198:201], v[148:151], v[88:91]
	v_mfma_f32_16x16x32_bf16 v[80:83], v[206:209], v[148:151], v[80:83]
	v_mfma_f32_16x16x32_bf16 v[72:75], v[198:201], v[156:159], v[72:75]
	v_mfma_f32_16x16x32_bf16 v[64:67], v[206:209], v[156:159], v[64:67]
	s_waitcnt vmcnt(12) lgkmcnt(0)
	s_barrier
	v_mfma_f32_16x16x32_bf16 v[124:127], v[218:221], v[128:131], v[124:127]
	v_mfma_f32_16x16x32_bf16 v[116:119], v[226:229], v[128:131], v[116:119]
	ds_read_b128 v[160:163], v234 offset:16384
	v_mfma_f32_16x16x32_bf16 v[108:111], v[218:221], v[136:139], v[108:111]
	ds_read_b128 v[164:167], v234 offset:17408
	v_mfma_f32_16x16x32_bf16 v[100:103], v[226:229], v[136:139], v[100:103]
	ds_read_b128 v[168:171], v234 offset:18432
	s_add_u32 m0, s40, 0x14000
	v_mfma_f32_16x16x32_bf16 v[92:95], v[218:221], v[144:147], v[92:95]
	ds_read_b128 v[172:175], v234 offset:19456
	v_mfma_f32_16x16x32_bf16 v[84:87], v[226:229], v[144:147], v[84:87]
	ds_read_b128 v[176:179], v234 offset:20480
	global_load_lds_dwordx4 v236, s[38:39]
	v_mfma_f32_16x16x32_bf16 v[76:79], v[218:221], v[152:155], v[76:79]
	ds_read_b128 v[180:183], v234 offset:21504
	v_mfma_f32_16x16x32_bf16 v[68:71], v[226:229], v[152:155], v[68:71]
	ds_read_b128 v[184:187], v234 offset:22528
	s_add_u32 m0, s40, 0x16000
	v_mfma_f32_16x16x32_bf16 v[124:127], v[222:225], v[132:135], v[124:127]
	ds_read_b128 v[188:191], v234 offset:23552
	v_mfma_f32_16x16x32_bf16 v[116:119], v[230:233], v[132:135], v[116:119]
	global_load_lds_dwordx4 v237, s[38:39]
	v_mfma_f32_16x16x32_bf16 v[108:111], v[222:225], v[140:143], v[108:111]
	v_mfma_f32_16x16x32_bf16 v[100:103], v[230:233], v[140:143], v[100:103]
	s_add_u32 s38, s38, 0x80
	s_addc_u32 s39, s39, 0
	v_mfma_f32_16x16x32_bf16 v[92:95], v[222:225], v[148:151], v[92:95]
	v_mfma_f32_16x16x32_bf16 v[84:87], v[230:233], v[148:151], v[84:87]
	v_mfma_f32_16x16x32_bf16 v[76:79], v[222:225], v[156:159], v[76:79]
	v_mfma_f32_16x16x32_bf16 v[68:71], v[230:233], v[156:159], v[68:71]
	s_waitcnt vmcnt(12) lgkmcnt(0)
	s_barrier
	v_mfma_f32_16x16x32_bf16 v[56:59], v[194:197], v[160:163], v[56:59]
	v_mfma_f32_16x16x32_bf16 v[48:51], v[202:205], v[160:163], v[48:51]
	ds_read_b128 v[128:131], v234 offset:32768
	v_mfma_f32_16x16x32_bf16 v[40:43], v[194:197], v[168:171], v[40:43]
	ds_read_b128 v[132:135], v234 offset:33792
	v_mfma_f32_16x16x32_bf16 v[32:35], v[202:205], v[168:171], v[32:35]
	ds_read_b128 v[136:139], v234 offset:34816
	s_add_u32 m0, s40, 0x4000
	v_mfma_f32_16x16x32_bf16 v[24:27], v[194:197], v[176:179], v[24:27]
	ds_read_b128 v[140:143], v234 offset:35840
	v_mfma_f32_16x16x32_bf16 v[16:19], v[202:205], v[176:179], v[16:19]
	ds_read_b128 v[144:147], v234 offset:36864
	global_load_lds_dwordx4 v236, s[8:9]
	v_mfma_f32_16x16x32_bf16 v[8:11], v[194:197], v[184:187], v[8:11]
	ds_read_b128 v[148:151], v234 offset:37888
	v_mfma_f32_16x16x32_bf16 v[0:3], v[202:205], v[184:187], v[0:3]
	ds_read_b128 v[152:155], v234 offset:38912
	s_add_u32 m0, s40, 0x6000
	v_mfma_f32_16x16x32_bf16 v[56:59], v[198:201], v[164:167], v[56:59]
	ds_read_b128 v[156:159], v234 offset:39936
	v_mfma_f32_16x16x32_bf16 v[48:51], v[206:209], v[164:167], v[48:51]
	global_load_lds_dwordx4 v237, s[8:9]
	v_mfma_f32_16x16x32_bf16 v[40:43], v[198:201], v[172:175], v[40:43]
	v_mfma_f32_16x16x32_bf16 v[32:35], v[206:209], v[172:175], v[32:35]
	s_add_u32 s8, s8, 0x80
	s_addc_u32 s9, s9, 0
	v_mfma_f32_16x16x32_bf16 v[24:27], v[198:201], v[180:183], v[24:27]
	v_mfma_f32_16x16x32_bf16 v[16:19], v[206:209], v[180:183], v[16:19]
	v_mfma_f32_16x16x32_bf16 v[8:11], v[198:201], v[188:191], v[8:11]
	v_mfma_f32_16x16x32_bf16 v[0:3], v[206:209], v[188:191], v[0:3]
	s_waitcnt vmcnt(12) lgkmcnt(0)
	s_barrier
; #define STAGE(P, BASE, br, kt) do { const u16* _gb = (BASE) + ((size_t)(br) * K + (size_t)(kt) * BK); \
;     __builtin_amdgcn_global_load_lds((const unsigned*)(_gb + goff0), (unsigned*)((char*)(P) + tid * 16), 16, 0, 0); \
;     __builtin_amdgcn_global_load_lds((const unsigned*)(_gb + (size_t)64 * K + goff0), (unsigned*)((char*)(P) + tid * 16 + 8192), 16, 0, 0); } while (0)
; #define LDA(dst, b, h) _Pragma("unroll") for (int m = 0; m < 4; ++m) _Pragma("unroll") for (int k = 0; k < 2; ++k) \
;     dst[m][k] = *reinterpret_cast<const bf16x8*>((char*)SA(b, h) + lds_byte(wr * 64 + m * 16 + fr, k * 32 + fq * 8))
; #define LDB(dst, b, h) _Pragma("unroll") for (int n = 0; n < 2; ++n) _Pragma("unroll") for (int k = 0; k < 2; ++k) \
;     dst[n][k] = *reinterpret_cast<const bf16x8*>((char*)SB(b, h) + lds_byte(wc * 32 + n * 16 + fr, k * 32 + fq * 8))
; #define WAIT_V(n) asm volatile("s_waitcnt vmcnt(" #n ")" ::: "memory")
; #define WAIT_L(n) asm volatile("s_waitcnt lgkmcnt(" #n ")" ::: "memory")
; #define BAR __builtin_amdgcn_s_barrier()
; #define SCHED __builtin_amdgcn_sched_barrier(0)
; __device__ __forceinline__ void gemm_phase(KP p, char* shmc, const u16* __restrict__ A,
;                                            const u16* __restrict__ Bt, const int N, const int K, const int mode,
;                                            const float* __restrict__ xin, const float resw) {
;     ...
;     for (int t = 0; t < nt - 2; t += 2) {
;       LDB(B0, 0, 0); SCHED; LDA(At, 0, 0); STAGE(SA(1, 1), A, brow + HALF, t + 1);
;       WAIT_L(8); BAR; WAIT_L(0); MMA(0, 0, At, B0); BAR; SCHED;
;       LDB(B1, 0, 1); STAGE(SB(0, 0), Bt, bcol, t + 2);
;       BAR; WAIT_L(0); MMA(0, 1, At, B1); BAR;
;       LDA(At, 0, 1); STAGE(SA(0, 0), A, brow, t + 2);
;       BAR; WAIT_L(0); MMA(1, 0, At, B0); BAR; SCHED;
;       STAGE(SB(0, 1), Bt, bcol + HALF, t + 2);
;       WAIT_V(6); BAR; MMA(1, 1, At, B1); BAR;
;       LDB(B0, 1, 0); SCHED; LDA(At, 1, 0); STAGE(SA(0, 1), A, brow + HALF, t + 2);
;       WAIT_L(8); BAR; WAIT_L(0); MMA(0, 0, At, B0); BAR; SCHED;
;       LDB(B1, 1, 1); STAGE(SB(1, 0), Bt, bcol, t + 3);
;       BAR; WAIT_L(0); MMA(0, 1, At, B1); BAR;
;       LDA(At, 1, 1); STAGE(SA(1, 0), A, brow, t + 3);
;       BAR; WAIT_L(0); MMA(1, 0, At, B0); BAR; SCHED;
;       STAGE(SB(1, 1), Bt, bcol + HALF, t + 3);
;       WAIT_V(6); BAR; MMA(1, 1, At, B1); BAR;
;     }
	v_mfma_f32_16x16x32_bf16 v[60:63], v[218:221], v[160:163], v[60:63]
	v_mfma_f32_16x16x32_bf16 v[52:55], v[226:229], v[160:163], v[52:55]
	ds_read_b128 v[194:197], v235 offset:32768
	v_mfma_f32_16x16x32_bf16 v[44:47], v[218:221], v[168:171], v[44:47]
	ds_read_b128 v[198:201], v235 offset:33792
	v_mfma_f32_16x16x32_bf16 v[36:39], v[226:229], v[168:171], v[36:39]
	ds_read_b128 v[202:205], v235 offset:34816
	s_add_u32 m0, s40, 0x8000
	v_mfma_f32_16x16x32_bf16 v[28:31], v[218:221], v[176:179], v[28:31]
	ds_read_b128 v[206:209], v235 offset:35840
	v_mfma_f32_16x16x32_bf16 v[20:23], v[226:229], v[176:179], v[20:23]
	global_load_lds_dwordx4 v236, s[36:37]
	v_mfma_f32_16x16x32_bf16 v[12:15], v[218:221], v[184:187], v[12:15]
	v_mfma_f32_16x16x32_bf16 v[4:7], v[226:229], v[184:187], v[4:7]
	s_add_u32 m0, s40, 0xa000
	v_mfma_f32_16x16x32_bf16 v[60:63], v[222:225], v[164:167], v[60:63]
	v_mfma_f32_16x16x32_bf16 v[52:55], v[230:233], v[164:167], v[52:55]
	global_load_lds_dwordx4 v237, s[36:37]
	v_mfma_f32_16x16x32_bf16 v[44:47], v[222:225], v[172:175], v[44:47]
	v_mfma_f32_16x16x32_bf16 v[36:39], v[230:233], v[172:175], v[36:39]
	s_add_u32 s36, s36, 0x80
	s_addc_u32 s37, s37, 0
	v_mfma_f32_16x16x32_bf16 v[28:31], v[222:225], v[180:183], v[28:31]
	v_mfma_f32_16x16x32_bf16 v[20:23], v[230:233], v[180:183], v[20:23]
	v_mfma_f32_16x16x32_bf16 v[12:15], v[222:225], v[188:191], v[12:15]
	v_mfma_f32_16x16x32_bf16 v[4:7], v[230:233], v[188:191], v[4:7]
	s_waitcnt vmcnt(12) lgkmcnt(0)
	s_barrier
	v_mfma_f32_16x16x32_bf16 v[120:123], v[194:197], v[128:131], v[120:123]
	v_mfma_f32_16x16x32_bf16 v[112:115], v[202:205], v[128:131], v[112:115]
	ds_read_b128 v[218:221], v235 offset:49152
	v_mfma_f32_16x16x32_bf16 v[104:107], v[194:197], v[136:139], v[104:107]
	ds_read_b128 v[222:225], v235 offset:50176
	v_mfma_f32_16x16x32_bf16 v[96:99], v[202:205], v[136:139], v[96:99]
	ds_read_b128 v[226:229], v235 offset:51200
	s_add_u32 m0, s40, 0x18000
	v_mfma_f32_16x16x32_bf16 v[88:91], v[194:197], v[144:147], v[88:91]
	ds_read_b128 v[230:233], v235 offset:52224
	v_mfma_f32_16x16x32_bf16 v[80:83], v[202:205], v[144:147], v[80:83]
	global_load_lds_dwordx4 v236, s[26:27]
	v_mfma_f32_16x16x32_bf16 v[72:75], v[194:197], v[152:155], v[72:75]
	v_mfma_f32_16x16x32_bf16 v[64:67], v[202:205], v[152:155], v[64:67]
	s_add_u32 m0, s40, 0x1a000
	v_mfma_f32_16x16x32_bf16 v[120:123], v[198:201], v[132:135], v[120:123]
	v_mfma_f32_16x16x32_bf16 v[112:115], v[206:209], v[132:135], v[112:115]
	global_load_lds_dwordx4 v237, s[26:27]
	v_mfma_f32_16x16x32_bf16 v[104:107], v[198:201], v[140:143], v[104:107]
	v_mfma_f32_16x16x32_bf16 v[96:99], v[206:209], v[140:143], v[96:99]
	s_add_u32 s26, s26, 0x80
	s_addc_u32 s27, s27, 0
	v_mfma_f32_16x16x32_bf16 v[88:91], v[198:201], v[148:151], v[88:91]
	v_mfma_f32_16x16x32_bf16 v[80:83], v[206:209], v[148:151], v[80:83]
	v_mfma_f32_16x16x32_bf16 v[72:75], v[198:201], v[156:159], v[72:75]
	v_mfma_f32_16x16x32_bf16 v[64:67], v[206:209], v[156:159], v[64:67]
	s_waitcnt vmcnt(12) lgkmcnt(0)
	s_barrier
	v_mfma_f32_16x16x32_bf16 v[124:127], v[218:221], v[128:131], v[124:127]
	v_mfma_f32_16x16x32_bf16 v[116:119], v[226:229], v[128:131], v[116:119]
	ds_read_b128 v[160:163], v234 offset:49152
	v_mfma_f32_16x16x32_bf16 v[108:111], v[218:221], v[136:139], v[108:111]
	ds_read_b128 v[164:167], v234 offset:50176
	v_mfma_f32_16x16x32_bf16 v[100:103], v[226:229], v[136:139], v[100:103]
	ds_read_b128 v[168:171], v234 offset:51200
	s_add_u32 m0, s40, 0x1c000
	v_mfma_f32_16x16x32_bf16 v[92:95], v[218:221], v[144:147], v[92:95]
	ds_read_b128 v[172:175], v234 offset:52224
	v_mfma_f32_16x16x32_bf16 v[84:87], v[226:229], v[144:147], v[84:87]
	ds_read_b128 v[176:179], v234 offset:53248
	global_load_lds_dwordx4 v236, s[38:39]
	v_mfma_f32_16x16x32_bf16 v[76:79], v[218:221], v[152:155], v[76:79]
	ds_read_b128 v[180:183], v234 offset:54272
	v_mfma_f32_16x16x32_bf16 v[68:71], v[226:229], v[152:155], v[68:71]
	ds_read_b128 v[184:187], v234 offset:55296
	s_add_u32 m0, s40, 0x1e000
	v_mfma_f32_16x16x32_bf16 v[124:127], v[222:225], v[132:135], v[124:127]
	ds_read_b128 v[188:191], v234 offset:56320
	v_mfma_f32_16x16x32_bf16 v[116:119], v[230:233], v[132:135], v[116:119]
	global_load_lds_dwordx4 v237, s[38:39]
	v_mfma_f32_16x16x32_bf16 v[108:111], v[222:225], v[140:143], v[108:111]
	v_mfma_f32_16x16x32_bf16 v[100:103], v[230:233], v[140:143], v[100:103]
	s_add_u32 s38, s38, 0x80
	s_addc_u32 s39, s39, 0
	v_mfma_f32_16x16x32_bf16 v[92:95], v[222:225], v[148:151], v[92:95]
	v_mfma_f32_16x16x32_bf16 v[84:87], v[230:233], v[148:151], v[84:87]
	v_mfma_f32_16x16x32_bf16 v[76:79], v[222:225], v[156:159], v[76:79]
	v_mfma_f32_16x16x32_bf16 v[68:71], v[230:233], v[156:159], v[68:71]
	s_waitcnt vmcnt(12) lgkmcnt(0)
	s_barrier
	v_mfma_f32_16x16x32_bf16 v[56:59], v[194:197], v[160:163], v[56:59]
	v_mfma_f32_16x16x32_bf16 v[48:51], v[202:205], v[160:163], v[48:51]
	ds_read_b128 v[128:131], v234 offset:0
	v_mfma_f32_16x16x32_bf16 v[40:43], v[194:197], v[168:171], v[40:43]
	ds_read_b128 v[132:135], v234 offset:1024
	v_mfma_f32_16x16x32_bf16 v[32:35], v[202:205], v[168:171], v[32:35]
	ds_read_b128 v[136:139], v234 offset:2048
	s_add_u32 m0, s40, 0xc000
	v_mfma_f32_16x16x32_bf16 v[24:27], v[194:197], v[176:179], v[24:27]
	ds_read_b128 v[140:143], v234 offset:3072
	v_mfma_f32_16x16x32_bf16 v[16:19], v[202:205], v[176:179], v[16:19]
	ds_read_b128 v[144:147], v234 offset:4096
	global_load_lds_dwordx4 v236, s[8:9]
	v_mfma_f32_16x16x32_bf16 v[8:11], v[194:197], v[184:187], v[8:11]
	ds_read_b128 v[148:151], v234 offset:5120
	v_mfma_f32_16x16x32_bf16 v[0:3], v[202:205], v[184:187], v[0:3]
	ds_read_b128 v[152:155], v234 offset:6144
	s_add_u32 m0, s40, 0xe000
	v_mfma_f32_16x16x32_bf16 v[56:59], v[198:201], v[164:167], v[56:59]
	ds_read_b128 v[156:159], v234 offset:7168
	v_mfma_f32_16x16x32_bf16 v[48:51], v[206:209], v[164:167], v[48:51]
	global_load_lds_dwordx4 v237, s[8:9]
	v_mfma_f32_16x16x32_bf16 v[40:43], v[198:201], v[172:175], v[40:43]
	v_mfma_f32_16x16x32_bf16 v[32:35], v[206:209], v[172:175], v[32:35]
	s_add_u32 s8, s8, 0x80
	s_addc_u32 s9, s9, 0
	v_mfma_f32_16x16x32_bf16 v[24:27], v[198:201], v[180:183], v[24:27]
	v_mfma_f32_16x16x32_bf16 v[16:19], v[206:209], v[180:183], v[16:19]
	v_mfma_f32_16x16x32_bf16 v[8:11], v[198:201], v[188:191], v[8:11]
	v_mfma_f32_16x16x32_bf16 v[0:3], v[206:209], v[188:191], v[0:3]
	s_waitcnt vmcnt(12) lgkmcnt(0)
	s_barrier
; #define STAGE(P, BASE, br, kt) do { const u16* _gb = (BASE) + ((size_t)(br) * K + (size_t)(kt) * BK); \
;     __builtin_amdgcn_global_load_lds((const unsigned*)(_gb + goff0), (unsigned*)((char*)(P) + tid * 16), 16, 0, 0); \
;     __builtin_amdgcn_global_load_lds((const unsigned*)(_gb + (size_t)64 * K + goff0), (unsigned*)((char*)(P) + tid * 16 + 8192), 16, 0, 0); } while (0)
; #define LDA(dst, b, h) _Pragma("unroll") for (int m = 0; m < 4; ++m) _Pragma("unroll") for (int k = 0; k < 2; ++k) \
;     dst[m][k] = *reinterpret_cast<const bf16x8*>((char*)SA(b, h) + lds_byte(wr * 64 + m * 16 + fr, k * 32 + fq * 8))
; #define LDB(dst, b, h) _Pragma("unroll") for (int n = 0; n < 2; ++n) _Pragma("unroll") for (int k = 0; k < 2; ++k) \
;     dst[n][k] = *reinterpret_cast<const bf16x8*>((char*)SB(b, h) + lds_byte(wc * 32 + n * 16 + fr, k * 32 + fq * 8))
; #define WAIT_V(n) asm volatile("s_waitcnt vmcnt(" #n ")" ::: "memory")
; #define WAIT_L(n) asm volatile("s_waitcnt lgkmcnt(" #n ")" ::: "memory")
; #define BAR __builtin_amdgcn_s_barrier()
; #define SCHED __builtin_amdgcn_sched_barrier(0)
; __device__ __forceinline__ void gemm_phase(KP p, char* shmc, const u16* __restrict__ A,
;                                            const u16* __restrict__ Bt, const int N, const int K, const int mode,
;                                            const float* __restrict__ xin, const float resw) {
;     ...
;     for (int t = 0; t < nt - 2; t += 2) {
;       LDB(B0, 0, 0); SCHED; LDA(At, 0, 0); STAGE(SA(1, 1), A, brow + HALF, t + 1);
;       WAIT_L(8); BAR; WAIT_L(0); MMA(0, 0, At, B0); BAR; SCHED;
;       LDB(B1, 0, 1); STAGE(SB(0, 0), Bt, bcol, t + 2);
;       BAR; WAIT_L(0); MMA(0, 1, At, B1); BAR;
;       LDA(At, 0, 1); STAGE(SA(0, 0), A, brow, t + 2);
;       BAR; WAIT_L(0); MMA(1, 0, At, B0); BAR; SCHED;
;       STAGE(SB(0, 1), Bt, bcol + HALF, t + 2);
;       WAIT_V(6); BAR; MMA(1, 1, At, B1); BAR;
;       LDB(B0, 1, 0); SCHED; LDA(At, 1, 0); STAGE(SA(0, 1), A, brow + HALF, t + 2);
;       WAIT_L(8); BAR; WAIT_L(0); MMA(0, 0, At, B0); BAR; SCHED;
;       LDB(B1, 1, 1); STAGE(SB(1, 0), Bt, bcol, t + 3);
;       BAR; WAIT_L(0); MMA(0, 1, At, B1); BAR;
;       LDA(At, 1, 1); STAGE(SA(1, 0), A, brow, t + 3);
;       BAR; WAIT_L(0); MMA(1, 0, At, B0); BAR; SCHED;
;       STAGE(SB(1, 1), Bt, bcol + HALF, t + 3);
;       WAIT_V(6); BAR; MMA(1, 1, At, B1); BAR;
;     }
	v_mfma_f32_16x16x32_bf16 v[60:63], v[218:221], v[160:163], v[60:63]
	v_mfma_f32_16x16x32_bf16 v[52:55], v[226:229], v[160:163], v[52:55]
	ds_read_b128 v[194:197], v235 offset:0
	v_mfma_f32_16x16x32_bf16 v[44:47], v[218:221], v[168:171], v[44:47]
	ds_read_b128 v[198:201], v235 offset:1024
	v_mfma_f32_16x16x32_bf16 v[36:39], v[226:229], v[168:171], v[36:39]
	ds_read_b128 v[202:205], v235 offset:2048
	s_add_u32 m0, s40, 0x0
	v_mfma_f32_16x16x32_bf16 v[28:31], v[218:221], v[176:179], v[28:31]
	ds_read_b128 v[206:209], v235 offset:3072
	v_mfma_f32_16x16x32_bf16 v[20:23], v[226:229], v[176:179], v[20:23]
	global_load_lds_dwordx4 v236, s[36:37]
	v_mfma_f32_16x16x32_bf16 v[12:15], v[218:221], v[184:187], v[12:15]
	v_mfma_f32_16x16x32_bf16 v[4:7], v[226:229], v[184:187], v[4:7]
	s_add_u32 m0, s40, 0x2000
	v_mfma_f32_16x16x32_bf16 v[60:63], v[222:225], v[164:167], v[60:63]
	v_mfma_f32_16x16x32_bf16 v[52:55], v[230:233], v[164:167], v[52:55]
	global_load_lds_dwordx4 v237, s[36:37]
	v_mfma_f32_16x16x32_bf16 v[44:47], v[222:225], v[172:175], v[44:47]
	v_mfma_f32_16x16x32_bf16 v[36:39], v[230:233], v[172:175], v[36:39]
	s_add_u32 s36, s36, 0x80
	s_addc_u32 s37, s37, 0
	v_mfma_f32_16x16x32_bf16 v[28:31], v[222:225], v[180:183], v[28:31]
	v_mfma_f32_16x16x32_bf16 v[20:23], v[230:233], v[180:183], v[20:23]
	v_mfma_f32_16x16x32_bf16 v[12:15], v[222:225], v[188:191], v[12:15]
	v_mfma_f32_16x16x32_bf16 v[4:7], v[230:233], v[188:191], v[4:7]
	s_add_i32 s41, s41, -1
	s_cmp_lg_u32 s41, 0
	s_cbranch_scc1 .Lmy_kloop
	s_waitcnt vmcnt(12) lgkmcnt(0)
	s_barrier
	v_mfma_f32_16x16x32_bf16 v[120:123], v[194:197], v[128:131], v[120:123]
	v_mfma_f32_16x16x32_bf16 v[112:115], v[202:205], v[128:131], v[112:115]
	ds_read_b128 v[218:221], v235 offset:16384
	v_mfma_f32_16x16x32_bf16 v[104:107], v[194:197], v[136:139], v[104:107]
	ds_read_b128 v[222:225], v235 offset:17408
	v_mfma_f32_16x16x32_bf16 v[96:99], v[202:205], v[136:139], v[96:99]
	ds_read_b128 v[226:229], v235 offset:18432
	s_add_u32 m0, s40, 0x10000
	v_mfma_f32_16x16x32_bf16 v[88:91], v[194:197], v[144:147], v[88:91]
	ds_read_b128 v[230:233], v235 offset:19456
	v_mfma_f32_16x16x32_bf16 v[80:83], v[202:205], v[144:147], v[80:83]
	global_load_lds_dwordx4 v236, s[26:27]
	v_mfma_f32_16x16x32_bf16 v[72:75], v[194:197], v[152:155], v[72:75]
	v_mfma_f32_16x16x32_bf16 v[64:67], v[202:205], v[152:155], v[64:67]
	s_add_u32 m0, s40, 0x12000
	v_mfma_f32_16x16x32_bf16 v[120:123], v[198:201], v[132:135], v[120:123]
	v_mfma_f32_16x16x32_bf16 v[112:115], v[206:209], v[132:135], v[112:115]
	global_load_lds_dwordx4 v237, s[26:27]
	v_mfma_f32_16x16x32_bf16 v[104:107], v[198:201], v[140:143], v[104:107]
	v_mfma_f32_16x16x32_bf16 v[96:99], v[206:209], v[140:143], v[96:99]
	s_add_u32 s26, s26, 0x80
	s_addc_u32 s27, s27, 0
	v_mfma_f32_16x16x32_bf16 v[88:91], v[198:201], v[148:151], v[88:91]
	v_mfma_f32_16x16x32_bf16 v[80:83], v[206:209], v[148:151], v[80:83]
	v_mfma_f32_16x16x32_bf16 v[72:75], v[198:201], v[156:159], v[72:75]
	v_mfma_f32_16x16x32_bf16 v[64:67], v[206:209], v[156:159], v[64:67]
	s_waitcnt vmcnt(12) lgkmcnt(0)
	s_barrier
	v_mfma_f32_16x16x32_bf16 v[124:127], v[218:221], v[128:131], v[124:127]
	v_mfma_f32_16x16x32_bf16 v[116:119], v[226:229], v[128:131], v[116:119]
	ds_read_b128 v[160:163], v234 offset:16384
	v_mfma_f32_16x16x32_bf16 v[108:111], v[218:221], v[136:139], v[108:111]
	ds_read_b128 v[164:167], v234 offset:17408
	v_mfma_f32_16x16x32_bf16 v[100:103], v[226:229], v[136:139], v[100:103]
	ds_read_b128 v[168:171], v234 offset:18432
	s_add_u32 m0, s40, 0x14000
	v_mfma_f32_16x16x32_bf16 v[92:95], v[218:221], v[144:147], v[92:95]
	ds_read_b128 v[172:175], v234 offset:19456
	v_mfma_f32_16x16x32_bf16 v[84:87], v[226:229], v[144:147], v[84:87]
	ds_read_b128 v[176:179], v234 offset:20480
	global_load_lds_dwordx4 v236, s[38:39]
	v_mfma_f32_16x16x32_bf16 v[76:79], v[218:221], v[152:155], v[76:79]
	ds_read_b128 v[180:183], v234 offset:21504
	v_mfma_f32_16x16x32_bf16 v[68:71], v[226:229], v[152:155], v[68:71]
	ds_read_b128 v[184:187], v234 offset:22528
	s_add_u32 m0, s40, 0x16000
	v_mfma_f32_16x16x32_bf16 v[124:127], v[222:225], v[132:135], v[124:127]
	ds_read_b128 v[188:191], v234 offset:23552
	v_mfma_f32_16x16x32_bf16 v[116:119], v[230:233], v[132:135], v[116:119]
	global_load_lds_dwordx4 v237, s[38:39]
	v_mfma_f32_16x16x32_bf16 v[108:111], v[222:225], v[140:143], v[108:111]
	v_mfma_f32_16x16x32_bf16 v[100:103], v[230:233], v[140:143], v[100:103]
	s_add_u32 s38, s38, 0x80
	s_addc_u32 s39, s39, 0
	v_mfma_f32_16x16x32_bf16 v[92:95], v[222:225], v[148:151], v[92:95]
	v_mfma_f32_16x16x32_bf16 v[84:87], v[230:233], v[148:151], v[84:87]
	v_mfma_f32_16x16x32_bf16 v[76:79], v[222:225], v[156:159], v[76:79]
	v_mfma_f32_16x16x32_bf16 v[68:71], v[230:233], v[156:159], v[68:71]
	s_waitcnt vmcnt(12) lgkmcnt(0)
	s_barrier
; #define STAGE(P, BASE, br, kt) do { const u16* _gb = (BASE) + ((size_t)(br) * K + (size_t)(kt) * BK); \
;     __builtin_amdgcn_global_load_lds((const unsigned*)(_gb + goff0), (unsigned*)((char*)(P) + tid * 16), 16, 0, 0); \
;     __builtin_amdgcn_global_load_lds((const unsigned*)(_gb + (size_t)64 * K + goff0), (unsigned*)((char*)(P) + tid * 16 + 8192), 16, 0, 0); } while (0)
; #define LDA(dst, b, h) _Pragma("unroll") for (int m = 0; m < 4; ++m) _Pragma("unroll") for (int k = 0; k < 2; ++k) \
;     dst[m][k] = *reinterpret_cast<const bf16x8*>((char*)SA(b, h) + lds_byte(wr * 64 + m * 16 + fr, k * 32 + fq * 8))
; #define LDB(dst, b, h) _Pragma("unroll") for (int n = 0; n < 2; ++n) _Pragma("unroll") for (int k = 0; k < 2; ++k) \
;     dst[n][k] = *reinterpret_cast<const bf16x8*>((char*)SB(b, h) + lds_byte(wc * 32 + n * 16 + fr, k * 32 + fq * 8))
; #define WAIT_V(n) asm volatile("s_waitcnt vmcnt(" #n ")" ::: "memory")
; #define WAIT_L(n) asm volatile("s_waitcnt lgkmcnt(" #n ")" ::: "memory")
; #define BAR __builtin_amdgcn_s_barrier()
; #define SCHED __builtin_amdgcn_sched_barrier(0)
; __device__ __forceinline__ void gemm_phase(KP p, char* shmc, const u16* __restrict__ A,
;                                            const u16* __restrict__ Bt, const int N, const int K, const int mode,
;                                            const float* __restrict__ xin, const float resw) {
;     ...
;     for (int t = 0; t < nt - 2; t += 2) {
;       LDB(B0, 0, 0); SCHED; LDA(At, 0, 0); STAGE(SA(1, 1), A, brow + HALF, t + 1);
;       WAIT_L(8); BAR; WAIT_L(0); MMA(0, 0, At, B0); BAR; SCHED;
;       LDB(B1, 0, 1); STAGE(SB(0, 0), Bt, bcol, t + 2);
;       BAR; WAIT_L(0); MMA(0, 1, At, B1); BAR;
;       LDA(At, 0, 1); STAGE(SA(0, 0), A, brow, t + 2);
;       BAR; WAIT_L(0); MMA(1, 0, At, B0); BAR; SCHED;
;       STAGE(SB(0, 1), Bt, bcol + HALF, t + 2);
;       WAIT_V(6); BAR; MMA(1, 1, At, B1); BAR;
;       LDB(B0, 1, 0); SCHED; LDA(At, 1, 0); STAGE(SA(0, 1), A, brow + HALF, t + 2);
;       WAIT_L(8); BAR; WAIT_L(0); MMA(0, 0, At, B0); BAR; SCHED;
;       LDB(B1, 1, 1); STAGE(SB(1, 0), Bt, bcol, t + 3);
;       BAR; WAIT_L(0); MMA(0, 1, At, B1); BAR;
;       LDA(At, 1, 1); STAGE(SA(1, 0), A, brow, t + 3);
;       BAR; WAIT_L(0); MMA(1, 0, At, B0); BAR; SCHED;
;       STAGE(SB(1, 1), Bt, bcol + HALF, t + 3);
;       WAIT_V(6); BAR; MMA(1, 1, At, B1); BAR;
;     }
	v_mfma_f32_16x16x32_bf16 v[56:59], v[194:197], v[160:163], v[56:59]
	v_mfma_f32_16x16x32_bf16 v[48:51], v[202:205], v[160:163], v[48:51]
	ds_read_b128 v[128:131], v234 offset:32768
	v_mfma_f32_16x16x32_bf16 v[40:43], v[194:197], v[168:171], v[40:43]
	ds_read_b128 v[132:135], v234 offset:33792
	v_mfma_f32_16x16x32_bf16 v[32:35], v[202:205], v[168:171], v[32:35]
	ds_read_b128 v[136:139], v234 offset:34816
	s_add_u32 m0, s40, 0x4000
	v_mfma_f32_16x16x32_bf16 v[24:27], v[194:197], v[176:179], v[24:27]
	ds_read_b128 v[140:143], v234 offset:35840
	v_mfma_f32_16x16x32_bf16 v[16:19], v[202:205], v[176:179], v[16:19]
	ds_read_b128 v[144:147], v234 offset:36864
	global_load_lds_dwordx4 v236, s[8:9]
	v_mfma_f32_16x16x32_bf16 v[8:11], v[194:197], v[184:187], v[8:11]
	ds_read_b128 v[148:151], v234 offset:37888
	v_mfma_f32_16x16x32_bf16 v[0:3], v[202:205], v[184:187], v[0:3]
	ds_read_b128 v[152:155], v234 offset:38912
	s_add_u32 m0, s40, 0x6000
	v_mfma_f32_16x16x32_bf16 v[56:59], v[198:201], v[164:167], v[56:59]
	ds_read_b128 v[156:159], v234 offset:39936
	v_mfma_f32_16x16x32_bf16 v[48:51], v[206:209], v[164:167], v[48:51]
	global_load_lds_dwordx4 v237, s[8:9]
	v_mfma_f32_16x16x32_bf16 v[40:43], v[198:201], v[172:175], v[40:43]
	v_mfma_f32_16x16x32_bf16 v[32:35], v[206:209], v[172:175], v[32:35]
	s_add_u32 s8, s8, 0x80
	s_addc_u32 s9, s9, 0
	v_mfma_f32_16x16x32_bf16 v[24:27], v[198:201], v[180:183], v[24:27]
	v_mfma_f32_16x16x32_bf16 v[16:19], v[206:209], v[180:183], v[16:19]
	v_mfma_f32_16x16x32_bf16 v[8:11], v[198:201], v[188:191], v[8:11]
	v_mfma_f32_16x16x32_bf16 v[0:3], v[206:209], v[188:191], v[0:3]
	s_waitcnt vmcnt(12) lgkmcnt(0)
	s_barrier
	v_mfma_f32_16x16x32_bf16 v[60:63], v[218:221], v[160:163], v[60:63]
	v_mfma_f32_16x16x32_bf16 v[52:55], v[226:229], v[160:163], v[52:55]
	ds_read_b128 v[194:197], v235 offset:32768
	v_mfma_f32_16x16x32_bf16 v[44:47], v[218:221], v[168:171], v[44:47]
	ds_read_b128 v[198:201], v235 offset:33792
	v_mfma_f32_16x16x32_bf16 v[36:39], v[226:229], v[168:171], v[36:39]
	ds_read_b128 v[202:205], v235 offset:34816
	s_add_u32 m0, s40, 0x8000
	v_mfma_f32_16x16x32_bf16 v[28:31], v[218:221], v[176:179], v[28:31]
	ds_read_b128 v[206:209], v235 offset:35840
	v_mfma_f32_16x16x32_bf16 v[20:23], v[226:229], v[176:179], v[20:23]
	global_load_lds_dwordx4 v236, s[36:37]
	v_mfma_f32_16x16x32_bf16 v[12:15], v[218:221], v[184:187], v[12:15]
	v_mfma_f32_16x16x32_bf16 v[4:7], v[226:229], v[184:187], v[4:7]
	s_add_u32 m0, s40, 0xa000
	v_mfma_f32_16x16x32_bf16 v[60:63], v[222:225], v[164:167], v[60:63]
	v_mfma_f32_16x16x32_bf16 v[52:55], v[230:233], v[164:167], v[52:55]
	global_load_lds_dwordx4 v237, s[36:37]
	v_mfma_f32_16x16x32_bf16 v[44:47], v[222:225], v[172:175], v[44:47]
	v_mfma_f32_16x16x32_bf16 v[36:39], v[230:233], v[172:175], v[36:39]
	s_add_u32 s36, s36, 0x80
	s_addc_u32 s37, s37, 0
	v_mfma_f32_16x16x32_bf16 v[28:31], v[222:225], v[180:183], v[28:31]
	v_mfma_f32_16x16x32_bf16 v[20:23], v[230:233], v[180:183], v[20:23]
	v_mfma_f32_16x16x32_bf16 v[12:15], v[222:225], v[188:191], v[12:15]
	v_mfma_f32_16x16x32_bf16 v[4:7], v[230:233], v[188:191], v[4:7]
	s_waitcnt vmcnt(12) lgkmcnt(0)
	s_barrier
	v_mfma_f32_16x16x32_bf16 v[120:123], v[194:197], v[128:131], v[120:123]
	v_mfma_f32_16x16x32_bf16 v[112:115], v[202:205], v[128:131], v[112:115]
	ds_read_b128 v[218:221], v235 offset:49152
	v_mfma_f32_16x16x32_bf16 v[104:107], v[194:197], v[136:139], v[104:107]
	ds_read_b128 v[222:225], v235 offset:50176
	v_mfma_f32_16x16x32_bf16 v[96:99], v[202:205], v[136:139], v[96:99]
	ds_read_b128 v[226:229], v235 offset:51200
	s_add_u32 m0, s40, 0x18000
	v_mfma_f32_16x16x32_bf16 v[88:91], v[194:197], v[144:147], v[88:91]
	ds_read_b128 v[230:233], v235 offset:52224
	v_mfma_f32_16x16x32_bf16 v[80:83], v[202:205], v[144:147], v[80:83]
	global_load_lds_dwordx4 v236, s[26:27]
	v_mfma_f32_16x16x32_bf16 v[72:75], v[194:197], v[152:155], v[72:75]
	v_mfma_f32_16x16x32_bf16 v[64:67], v[202:205], v[152:155], v[64:67]
	s_add_u32 m0, s40, 0x1a000
	v_mfma_f32_16x16x32_bf16 v[120:123], v[198:201], v[132:135], v[120:123]
	v_mfma_f32_16x16x32_bf16 v[112:115], v[206:209], v[132:135], v[112:115]
	global_load_lds_dwordx4 v237, s[26:27]
	v_mfma_f32_16x16x32_bf16 v[104:107], v[198:201], v[140:143], v[104:107]
	v_mfma_f32_16x16x32_bf16 v[96:99], v[206:209], v[140:143], v[96:99]
	s_add_u32 s26, s26, 0x80
	s_addc_u32 s27, s27, 0
	v_mfma_f32_16x16x32_bf16 v[88:91], v[198:201], v[148:151], v[88:91]
	v_mfma_f32_16x16x32_bf16 v[80:83], v[206:209], v[148:151], v[80:83]
	v_mfma_f32_16x16x32_bf16 v[72:75], v[198:201], v[156:159], v[72:75]
	v_mfma_f32_16x16x32_bf16 v[64:67], v[206:209], v[156:159], v[64:67]
	s_waitcnt vmcnt(12) lgkmcnt(0)
	s_barrier
	v_mfma_f32_16x16x32_bf16 v[124:127], v[218:221], v[128:131], v[124:127]
	v_mfma_f32_16x16x32_bf16 v[116:119], v[226:229], v[128:131], v[116:119]
	ds_read_b128 v[160:163], v234 offset:49152
	v_mfma_f32_16x16x32_bf16 v[108:111], v[218:221], v[136:139], v[108:111]
	ds_read_b128 v[164:167], v234 offset:50176
	v_mfma_f32_16x16x32_bf16 v[100:103], v[226:229], v[136:139], v[100:103]
	ds_read_b128 v[168:171], v234 offset:51200
	s_add_u32 m0, s40, 0x1c000
	v_mfma_f32_16x16x32_bf16 v[92:95], v[218:221], v[144:147], v[92:95]
	ds_read_b128 v[172:175], v234 offset:52224
	v_mfma_f32_16x16x32_bf16 v[84:87], v[226:229], v[144:147], v[84:87]
	ds_read_b128 v[176:179], v234 offset:53248
	global_load_lds_dwordx4 v236, s[38:39]
	v_mfma_f32_16x16x32_bf16 v[76:79], v[218:221], v[152:155], v[76:79]
	ds_read_b128 v[180:183], v234 offset:54272
	v_mfma_f32_16x16x32_bf16 v[68:71], v[226:229], v[152:155], v[68:71]
	ds_read_b128 v[184:187], v234 offset:55296
	s_add_u32 m0, s40, 0x1e000
	v_mfma_f32_16x16x32_bf16 v[124:127], v[222:225], v[132:135], v[124:127]
	ds_read_b128 v[188:191], v234 offset:56320
	v_mfma_f32_16x16x32_bf16 v[116:119], v[230:233], v[132:135], v[116:119]
	global_load_lds_dwordx4 v237, s[38:39]
	v_mfma_f32_16x16x32_bf16 v[108:111], v[222:225], v[140:143], v[108:111]
	v_mfma_f32_16x16x32_bf16 v[100:103], v[230:233], v[140:143], v[100:103]
	s_add_u32 s38, s38, 0x80
	s_addc_u32 s39, s39, 0
	v_mfma_f32_16x16x32_bf16 v[92:95], v[222:225], v[148:151], v[92:95]
	v_mfma_f32_16x16x32_bf16 v[84:87], v[230:233], v[148:151], v[84:87]
	v_mfma_f32_16x16x32_bf16 v[76:79], v[222:225], v[156:159], v[76:79]
	v_mfma_f32_16x16x32_bf16 v[68:71], v[230:233], v[156:159], v[68:71]
	s_waitcnt vmcnt(12) lgkmcnt(0)
	s_barrier
; #define STAGE(P, BASE, br, kt) do { const u16* _gb = (BASE) + ((size_t)(br) * K + (size_t)(kt) * BK); \
;     __builtin_amdgcn_global_load_lds((const unsigned*)(_gb + goff0), (unsigned*)((char*)(P) + tid * 16), 16, 0, 0); \
;     __builtin_amdgcn_global_load_lds((const unsigned*)(_gb + (size_t)64 * K + goff0), (unsigned*)((char*)(P) + tid * 16 + 8192), 16, 0, 0); } while (0)
; #define LDA(dst, b, h) _Pragma("unroll") for (int m = 0; m < 4; ++m) _Pragma("unroll") for (int k = 0; k < 2; ++k) \
;     dst[m][k] = *reinterpret_cast<const bf16x8*>((char*)SA(b, h) + lds_byte(wr * 64 + m * 16 + fr, k * 32 + fq * 8))
; #define LDB(dst, b, h) _Pragma("unroll") for (int n = 0; n < 2; ++n) _Pragma("unroll") for (int k = 0; k < 2; ++k) \
;     dst[n][k] = *reinterpret_cast<const bf16x8*>((char*)SB(b, h) + lds_byte(wc * 32 + n * 16 + fr, k * 32 + fq * 8))
; #define MMA(ai, bj, At, Bt_) do { __builtin_amdgcn_s_setprio(1); \
;     _Pragma("unroll") for (int m = 0; m < 4; ++m) _Pragma("unroll") for (int n = 0; n < 2; ++n) _Pragma("unroll") for (int k = 0; k < 2; ++k) \
;       acc[ai][bj][m][n] = __builtin_amdgcn_mfma_f32_16x16x32_bf16(Bt_[n][k], At[m][k], acc[ai][bj][m][n], 0, 0, 0); \
;     __builtin_amdgcn_s_setprio(0); } while (0)
; #define WAIT_V(n) asm volatile("s_waitcnt vmcnt(" #n ")" ::: "memory")
; #define BAR __builtin_amdgcn_s_barrier()
; __device__ __forceinline__ void gemm_phase(KP p, char* shmc, const u16* __restrict__ A,
;                                            const u16* __restrict__ Bt, const int N, const int K, const int mode,
;                                            const float* __restrict__ xin, const float resw) {
;     ...
;     { LDB(B0, 0, 0); LDA(At, 0, 0); STAGE(SA(1, 1), A, brow + HALF, nt - 1);
;       BAR; WAIT_L(0); MMA(0, 0, At, B0); BAR;
;       LDB(B1, 0, 1); BAR; WAIT_L(0); MMA(0, 1, At, B1); BAR;
;       LDA(At, 0, 1); WAIT_V(4); BAR; WAIT_L(0); MMA(1, 0, At, B0); MMA(1, 1, At, B1); BAR; }
;     { LDB(B0, 1, 0); LDA(At, 1, 0); WAIT_V(2); BAR; WAIT_L(0); MMA(0, 0, At, B0); BAR;
;       LDB(B1, 1, 1); WAIT_V(0); BAR; WAIT_L(0); MMA(0, 1, At, B1); BAR;
;       LDA(At, 1, 1); BAR; WAIT_L(0); MMA(1, 0, At, B0); MMA(1, 1, At, B1); BAR; }
;     ...
;     const int ntix = tix + gridDim.x;
;     int nbrow = 0, nbcol = 0, npn = 0;
;     if (ntix < nwg) {
;       TILE_MAP(ntix, nbrow, nbcol, npn);
;       TILE_PREFETCH(nbrow, nbcol, par ^ 1);
;     }
	v_mfma_f32_16x16x32_bf16 v[56:59], v[194:197], v[160:163], v[56:59]
	v_mfma_f32_16x16x32_bf16 v[48:51], v[202:205], v[160:163], v[48:51]
	ds_read_b128 v[128:131], v234 offset:0
	v_mfma_f32_16x16x32_bf16 v[40:43], v[194:197], v[168:171], v[40:43]
	ds_read_b128 v[132:135], v234 offset:1024
	v_mfma_f32_16x16x32_bf16 v[32:35], v[202:205], v[168:171], v[32:35]
	ds_read_b128 v[136:139], v234 offset:2048
	s_add_u32 m0, s40, 0xc000
	v_mfma_f32_16x16x32_bf16 v[24:27], v[194:197], v[176:179], v[24:27]
	ds_read_b128 v[140:143], v234 offset:3072
	v_mfma_f32_16x16x32_bf16 v[16:19], v[202:205], v[176:179], v[16:19]
	ds_read_b128 v[144:147], v234 offset:4096
	global_load_lds_dwordx4 v236, s[8:9]
	v_mfma_f32_16x16x32_bf16 v[8:11], v[194:197], v[184:187], v[8:11]
	ds_read_b128 v[148:151], v234 offset:5120
	v_mfma_f32_16x16x32_bf16 v[0:3], v[202:205], v[184:187], v[0:3]
	ds_read_b128 v[152:155], v234 offset:6144
	s_add_u32 m0, s40, 0xe000
	v_mfma_f32_16x16x32_bf16 v[56:59], v[198:201], v[164:167], v[56:59]
	ds_read_b128 v[156:159], v234 offset:7168
	v_mfma_f32_16x16x32_bf16 v[48:51], v[206:209], v[164:167], v[48:51]
	global_load_lds_dwordx4 v237, s[8:9]
	v_mfma_f32_16x16x32_bf16 v[40:43], v[198:201], v[172:175], v[40:43]
	v_mfma_f32_16x16x32_bf16 v[32:35], v[206:209], v[172:175], v[32:35]
	s_add_u32 s8, s8, 0x80
	s_addc_u32 s9, s9, 0
	v_mfma_f32_16x16x32_bf16 v[24:27], v[198:201], v[180:183], v[24:27]
	v_mfma_f32_16x16x32_bf16 v[16:19], v[206:209], v[180:183], v[16:19]
	v_mfma_f32_16x16x32_bf16 v[8:11], v[198:201], v[188:191], v[8:11]
	v_mfma_f32_16x16x32_bf16 v[0:3], v[206:209], v[188:191], v[0:3]
	s_waitcnt vmcnt(12) lgkmcnt(0)
	s_barrier
	v_mfma_f32_16x16x32_bf16 v[60:63], v[218:221], v[160:163], v[60:63]
	v_mfma_f32_16x16x32_bf16 v[52:55], v[226:229], v[160:163], v[52:55]
	ds_read_b128 v[194:197], v235 offset:0
	v_mfma_f32_16x16x32_bf16 v[44:47], v[218:221], v[168:171], v[44:47]
	ds_read_b128 v[198:201], v235 offset:1024
	v_mfma_f32_16x16x32_bf16 v[36:39], v[226:229], v[168:171], v[36:39]
	ds_read_b128 v[202:205], v235 offset:2048
	v_mfma_f32_16x16x32_bf16 v[28:31], v[218:221], v[176:179], v[28:31]
	ds_read_b128 v[206:209], v235 offset:3072
	v_mfma_f32_16x16x32_bf16 v[20:23], v[226:229], v[176:179], v[20:23]
	v_mfma_f32_16x16x32_bf16 v[12:15], v[218:221], v[184:187], v[12:15]
	v_mfma_f32_16x16x32_bf16 v[4:7], v[226:229], v[184:187], v[4:7]
	v_mfma_f32_16x16x32_bf16 v[60:63], v[222:225], v[164:167], v[60:63]
	v_mfma_f32_16x16x32_bf16 v[52:55], v[230:233], v[164:167], v[52:55]
	v_mfma_f32_16x16x32_bf16 v[44:47], v[222:225], v[172:175], v[44:47]
	v_mfma_f32_16x16x32_bf16 v[36:39], v[230:233], v[172:175], v[36:39]
	v_mfma_f32_16x16x32_bf16 v[28:31], v[222:225], v[180:183], v[28:31]
	v_mfma_f32_16x16x32_bf16 v[20:23], v[230:233], v[180:183], v[20:23]
	v_mfma_f32_16x16x32_bf16 v[12:15], v[222:225], v[188:191], v[12:15]
	v_mfma_f32_16x16x32_bf16 v[4:7], v[230:233], v[188:191], v[4:7]
	s_cmp_ge_i32 s66, s51
	s_cbranch_scc1 .Lmy_kloop_t2plain
	s_mul_hi_i32 s27, s46, s50
	s_mul_i32 s26, s46, s50
	s_lshl_b64 s[26:27], s[26:27], 1
	s_add_u32 s26, s14, s26
	s_addc_u32 s27, s15, s27
	s_mul_hi_i32 s37, s43, s50
	s_mul_i32 s36, s43, s50
	s_lshl_b64 s[36:37], s[36:37], 1
	s_add_u32 s36, s12, s36
	s_addc_u32 s37, s13, s37
	s_lshl_b32 s41, s72, 1
	s_add_u32 s38, s26, s41
	s_addc_u32 s39, s27, 0
	s_add_u32 s8, s36, s41
	s_addc_u32 s9, s37, 0
	s_waitcnt vmcnt(10) lgkmcnt(0)
	s_barrier
	v_mfma_f32_16x16x32_bf16 v[120:123], v[194:197], v[128:131], v[120:123]
	v_mfma_f32_16x16x32_bf16 v[112:115], v[202:205], v[128:131], v[112:115]
	ds_read_b128 v[218:221], v235 offset:16384
	v_mfma_f32_16x16x32_bf16 v[104:107], v[194:197], v[136:139], v[104:107]
	ds_read_b128 v[222:225], v235 offset:17408
	s_add_u32 m0, s40, 0x10000
	v_mfma_f32_16x16x32_bf16 v[96:99], v[202:205], v[136:139], v[96:99]
	ds_read_b128 v[226:229], v235 offset:18432
	global_load_lds_dwordx4 v236, s[26:27]
	v_mfma_f32_16x16x32_bf16 v[88:91], v[194:197], v[144:147], v[88:91]
	ds_read_b128 v[230:233], v235 offset:19456
	s_add_u32 m0, s40, 0x12000
	v_mfma_f32_16x16x32_bf16 v[80:83], v[202:205], v[144:147], v[80:83]
	global_load_lds_dwordx4 v237, s[26:27]
	v_mfma_f32_16x16x32_bf16 v[72:75], v[194:197], v[152:155], v[72:75]
	s_add_u32 s26, s26, 0x80
	s_addc_u32 s27, s27, 0
	v_mfma_f32_16x16x32_bf16 v[64:67], v[202:205], v[152:155], v[64:67]
	s_add_u32 m0, s40, 0x0
	v_mfma_f32_16x16x32_bf16 v[120:123], v[198:201], v[132:135], v[120:123]
	global_load_lds_dwordx4 v236, s[36:37]
	v_mfma_f32_16x16x32_bf16 v[112:115], v[206:209], v[132:135], v[112:115]
	s_add_u32 m0, s40, 0x2000
	v_mfma_f32_16x16x32_bf16 v[104:107], v[198:201], v[140:143], v[104:107]
	global_load_lds_dwordx4 v237, s[36:37]
	v_mfma_f32_16x16x32_bf16 v[96:99], v[206:209], v[140:143], v[96:99]
	s_add_u32 s36, s36, 0x80
	s_addc_u32 s37, s37, 0
	v_mfma_f32_16x16x32_bf16 v[88:91], v[198:201], v[148:151], v[88:91]
	v_mfma_f32_16x16x32_bf16 v[80:83], v[206:209], v[148:151], v[80:83]
	v_mfma_f32_16x16x32_bf16 v[72:75], v[198:201], v[156:159], v[72:75]
	v_mfma_f32_16x16x32_bf16 v[64:67], v[206:209], v[156:159], v[64:67]
	s_waitcnt vmcnt(12) lgkmcnt(0)
	s_barrier
; #define STAGE(P, BASE, br, kt) do { const u16* _gb = (BASE) + ((size_t)(br) * K + (size_t)(kt) * BK); \
;     __builtin_amdgcn_global_load_lds((const unsigned*)(_gb + goff0), (unsigned*)((char*)(P) + tid * 16), 16, 0, 0); \
;     __builtin_amdgcn_global_load_lds((const unsigned*)(_gb + (size_t)64 * K + goff0), (unsigned*)((char*)(P) + tid * 16 + 8192), 16, 0, 0); } while (0)
; #define LDA(dst, b, h) _Pragma("unroll") for (int m = 0; m < 4; ++m) _Pragma("unroll") for (int k = 0; k < 2; ++k) \
;     dst[m][k] = *reinterpret_cast<const bf16x8*>((char*)SA(b, h) + lds_byte(wr * 64 + m * 16 + fr, k * 32 + fq * 8))
; #define LDB(dst, b, h) _Pragma("unroll") for (int n = 0; n < 2; ++n) _Pragma("unroll") for (int k = 0; k < 2; ++k) \
;     dst[n][k] = *reinterpret_cast<const bf16x8*>((char*)SB(b, h) + lds_byte(wc * 32 + n * 16 + fr, k * 32 + fq * 8))
; #define MMA(ai, bj, At, Bt_) do { __builtin_amdgcn_s_setprio(1); \
;     _Pragma("unroll") for (int m = 0; m < 4; ++m) _Pragma("unroll") for (int n = 0; n < 2; ++n) _Pragma("unroll") for (int k = 0; k < 2; ++k) \
;       acc[ai][bj][m][n] = __builtin_amdgcn_mfma_f32_16x16x32_bf16(Bt_[n][k], At[m][k], acc[ai][bj][m][n], 0, 0, 0); \
;     __builtin_amdgcn_s_setprio(0); } while (0)
; #define WAIT_V(n) asm volatile("s_waitcnt vmcnt(" #n ")" ::: "memory")
; #define WAIT_L(n) asm volatile("s_waitcnt lgkmcnt(" #n ")" ::: "memory")
; #define BAR __builtin_amdgcn_s_barrier()
; __device__ __forceinline__ void gemm_phase(KP p, char* shmc, const u16* __restrict__ A,
;                                            const u16* __restrict__ Bt, const int N, const int K, const int mode,
;                                            const float* __restrict__ xin, const float resw) {
;     ...
;     { LDB(B0, 0, 0); LDA(At, 0, 0); STAGE(SA(1, 1), A, brow + HALF, nt - 1);
;       BAR; WAIT_L(0); MMA(0, 0, At, B0); BAR;
;       LDB(B1, 0, 1); BAR; WAIT_L(0); MMA(0, 1, At, B1); BAR;
;       LDA(At, 0, 1); WAIT_V(4); BAR; WAIT_L(0); MMA(1, 0, At, B0); MMA(1, 1, At, B1); BAR; }
;     { LDB(B0, 1, 0); LDA(At, 1, 0); WAIT_V(2); BAR; WAIT_L(0); MMA(0, 0, At, B0); BAR;
;       LDB(B1, 1, 1); WAIT_V(0); BAR; WAIT_L(0); MMA(0, 1, At, B1); BAR;
;       LDA(At, 1, 1); BAR; WAIT_L(0); MMA(1, 0, At, B0); MMA(1, 1, At, B1); BAR; }
	v_mfma_f32_16x16x32_bf16 v[124:127], v[218:221], v[128:131], v[124:127]
	v_mfma_f32_16x16x32_bf16 v[116:119], v[226:229], v[128:131], v[116:119]
	ds_read_b128 v[160:163], v234 offset:16384
	v_mfma_f32_16x16x32_bf16 v[108:111], v[218:221], v[136:139], v[108:111]
	ds_read_b128 v[164:167], v234 offset:17408
	v_mfma_f32_16x16x32_bf16 v[100:103], v[226:229], v[136:139], v[100:103]
	ds_read_b128 v[168:171], v234 offset:18432
	s_add_u32 m0, s40, 0x14000
	v_mfma_f32_16x16x32_bf16 v[92:95], v[218:221], v[144:147], v[92:95]
	ds_read_b128 v[172:175], v234 offset:19456
	v_mfma_f32_16x16x32_bf16 v[84:87], v[226:229], v[144:147], v[84:87]
	ds_read_b128 v[176:179], v234 offset:20480
	global_load_lds_dwordx4 v236, s[38:39]
	v_mfma_f32_16x16x32_bf16 v[76:79], v[218:221], v[152:155], v[76:79]
	ds_read_b128 v[180:183], v234 offset:21504
	v_mfma_f32_16x16x32_bf16 v[68:71], v[226:229], v[152:155], v[68:71]
	ds_read_b128 v[184:187], v234 offset:22528
	s_add_u32 m0, s40, 0x16000
	v_mfma_f32_16x16x32_bf16 v[124:127], v[222:225], v[132:135], v[124:127]
	ds_read_b128 v[188:191], v234 offset:23552
	v_mfma_f32_16x16x32_bf16 v[116:119], v[230:233], v[132:135], v[116:119]
	global_load_lds_dwordx4 v237, s[38:39]
	v_mfma_f32_16x16x32_bf16 v[108:111], v[222:225], v[140:143], v[108:111]
	v_mfma_f32_16x16x32_bf16 v[100:103], v[230:233], v[140:143], v[100:103]
	s_add_u32 s38, s38, 0x80
	s_addc_u32 s39, s39, 0
	v_mfma_f32_16x16x32_bf16 v[92:95], v[222:225], v[148:151], v[92:95]
	v_mfma_f32_16x16x32_bf16 v[84:87], v[230:233], v[148:151], v[84:87]
	v_mfma_f32_16x16x32_bf16 v[76:79], v[222:225], v[156:159], v[76:79]
	v_mfma_f32_16x16x32_bf16 v[68:71], v[230:233], v[156:159], v[68:71]
	s_waitcnt vmcnt(12) lgkmcnt(0)
	s_barrier
	v_mfma_f32_16x16x32_bf16 v[56:59], v[194:197], v[160:163], v[56:59]
	v_mfma_f32_16x16x32_bf16 v[48:51], v[202:205], v[160:163], v[48:51]
	ds_read_b128 v[128:131], v234 offset:32768
	v_mfma_f32_16x16x32_bf16 v[40:43], v[194:197], v[168:171], v[40:43]
	ds_read_b128 v[132:135], v234 offset:33792
	v_mfma_f32_16x16x32_bf16 v[32:35], v[202:205], v[168:171], v[32:35]
	ds_read_b128 v[136:139], v234 offset:34816
	s_add_u32 m0, s40, 0x4000
	v_mfma_f32_16x16x32_bf16 v[24:27], v[194:197], v[176:179], v[24:27]
	ds_read_b128 v[140:143], v234 offset:35840
	v_mfma_f32_16x16x32_bf16 v[16:19], v[202:205], v[176:179], v[16:19]
	ds_read_b128 v[144:147], v234 offset:36864
	global_load_lds_dwordx4 v236, s[8:9]
	v_mfma_f32_16x16x32_bf16 v[8:11], v[194:197], v[184:187], v[8:11]
	ds_read_b128 v[148:151], v234 offset:37888
	v_mfma_f32_16x16x32_bf16 v[0:3], v[202:205], v[184:187], v[0:3]
	ds_read_b128 v[152:155], v234 offset:38912
	s_add_u32 m0, s40, 0x6000
	v_mfma_f32_16x16x32_bf16 v[56:59], v[198:201], v[164:167], v[56:59]
	ds_read_b128 v[156:159], v234 offset:39936
	v_mfma_f32_16x16x32_bf16 v[48:51], v[206:209], v[164:167], v[48:51]
	global_load_lds_dwordx4 v237, s[8:9]
	v_mfma_f32_16x16x32_bf16 v[40:43], v[198:201], v[172:175], v[40:43]
	v_mfma_f32_16x16x32_bf16 v[32:35], v[206:209], v[172:175], v[32:35]
	s_add_u32 s8, s8, 0x80
	s_addc_u32 s9, s9, 0
	v_mfma_f32_16x16x32_bf16 v[24:27], v[198:201], v[180:183], v[24:27]
	v_mfma_f32_16x16x32_bf16 v[16:19], v[206:209], v[180:183], v[16:19]
	v_mfma_f32_16x16x32_bf16 v[8:11], v[198:201], v[188:191], v[8:11]
	v_mfma_f32_16x16x32_bf16 v[0:3], v[206:209], v[188:191], v[0:3]
	s_waitcnt vmcnt(12) lgkmcnt(0)
	s_barrier
	v_mfma_f32_16x16x32_bf16 v[60:63], v[218:221], v[160:163], v[60:63]
	v_mfma_f32_16x16x32_bf16 v[52:55], v[226:229], v[160:163], v[52:55]
	ds_read_b128 v[194:197], v235 offset:32768
	v_mfma_f32_16x16x32_bf16 v[44:47], v[218:221], v[168:171], v[44:47]
	ds_read_b128 v[198:201], v235 offset:33792
	v_mfma_f32_16x16x32_bf16 v[36:39], v[226:229], v[168:171], v[36:39]
	ds_read_b128 v[202:205], v235 offset:34816
	s_add_u32 m0, s40, 0x8000
	v_mfma_f32_16x16x32_bf16 v[28:31], v[218:221], v[176:179], v[28:31]
	ds_read_b128 v[206:209], v235 offset:35840
	v_mfma_f32_16x16x32_bf16 v[20:23], v[226:229], v[176:179], v[20:23]
	global_load_lds_dwordx4 v236, s[36:37]
	v_mfma_f32_16x16x32_bf16 v[12:15], v[218:221], v[184:187], v[12:15]
	v_mfma_f32_16x16x32_bf16 v[4:7], v[226:229], v[184:187], v[4:7]
	s_add_u32 m0, s40, 0xa000
	v_mfma_f32_16x16x32_bf16 v[60:63], v[222:225], v[164:167], v[60:63]
	v_mfma_f32_16x16x32_bf16 v[52:55], v[230:233], v[164:167], v[52:55]
	global_load_lds_dwordx4 v237, s[36:37]
	v_mfma_f32_16x16x32_bf16 v[44:47], v[222:225], v[172:175], v[44:47]
	v_mfma_f32_16x16x32_bf16 v[36:39], v[230:233], v[172:175], v[36:39]
	s_add_u32 s36, s36, 0x80
	s_addc_u32 s37, s37, 0
	v_mfma_f32_16x16x32_bf16 v[28:31], v[222:225], v[180:183], v[28:31]
	v_mfma_f32_16x16x32_bf16 v[20:23], v[230:233], v[180:183], v[20:23]
	v_mfma_f32_16x16x32_bf16 v[12:15], v[222:225], v[188:191], v[12:15]
	v_mfma_f32_16x16x32_bf16 v[4:7], v[230:233], v[188:191], v[4:7]
	s_waitcnt vmcnt(12) lgkmcnt(0)
	s_barrier
; #define STAGE(P, BASE, br, kt) do { const u16* _gb = (BASE) + ((size_t)(br) * K + (size_t)(kt) * BK); \
;     __builtin_amdgcn_global_load_lds((const unsigned*)(_gb + goff0), (unsigned*)((char*)(P) + tid * 16), 16, 0, 0); \
;     __builtin_amdgcn_global_load_lds((const unsigned*)(_gb + (size_t)64 * K + goff0), (unsigned*)((char*)(P) + tid * 16 + 8192), 16, 0, 0); } while (0)
; #define LDA(dst, b, h) _Pragma("unroll") for (int m = 0; m < 4; ++m) _Pragma("unroll") for (int k = 0; k < 2; ++k) \
;     dst[m][k] = *reinterpret_cast<const bf16x8*>((char*)SA(b, h) + lds_byte(wr * 64 + m * 16 + fr, k * 32 + fq * 8))
; #define LDB(dst, b, h) _Pragma("unroll") for (int n = 0; n < 2; ++n) _Pragma("unroll") for (int k = 0; k < 2; ++k) \
;     dst[n][k] = *reinterpret_cast<const bf16x8*>((char*)SB(b, h) + lds_byte(wc * 32 + n * 16 + fr, k * 32 + fq * 8))
; #define MMA(ai, bj, At, Bt_) do { __builtin_amdgcn_s_setprio(1); \
;     _Pragma("unroll") for (int m = 0; m < 4; ++m) _Pragma("unroll") for (int n = 0; n < 2; ++n) _Pragma("unroll") for (int k = 0; k < 2; ++k) \
;       acc[ai][bj][m][n] = __builtin_amdgcn_mfma_f32_16x16x32_bf16(Bt_[n][k], At[m][k], acc[ai][bj][m][n], 0, 0, 0); \
;     __builtin_amdgcn_s_setprio(0); } while (0)
; #define WAIT_V(n) asm volatile("s_waitcnt vmcnt(" #n ")" ::: "memory")
; #define WAIT_L(n) asm volatile("s_waitcnt lgkmcnt(" #n ")" ::: "memory")
; #define BAR __builtin_amdgcn_s_barrier()
; __device__ __forceinline__ void gemm_phase(KP p, char* shmc, const u16* __restrict__ A,
;                                            const u16* __restrict__ Bt, const int N, const int K, const int mode,
;                                            const float* __restrict__ xin, const float resw) {
;     ...
;     { LDB(B0, 0, 0); LDA(At, 0, 0); STAGE(SA(1, 1), A, brow + HALF, nt - 1);
;       BAR; WAIT_L(0); MMA(0, 0, At, B0); BAR;
;       LDB(B1, 0, 1); BAR; WAIT_L(0); MMA(0, 1, At, B1); BAR;
;       LDA(At, 0, 1); WAIT_V(4); BAR; WAIT_L(0); MMA(1, 0, At, B0); MMA(1, 1, At, B1); BAR; }
;     { LDB(B0, 1, 0); LDA(At, 1, 0); WAIT_V(2); BAR; WAIT_L(0); MMA(0, 0, At, B0); BAR;
;       LDB(B1, 1, 1); WAIT_V(0); BAR; WAIT_L(0); MMA(0, 1, At, B1); BAR;
;       LDA(At, 1, 1); BAR; WAIT_L(0); MMA(1, 0, At, B0); MMA(1, 1, At, B1); BAR; }
	v_mfma_f32_16x16x32_bf16 v[120:123], v[194:197], v[128:131], v[120:123]
	v_mfma_f32_16x16x32_bf16 v[112:115], v[202:205], v[128:131], v[112:115]
	ds_read_b128 v[218:221], v235 offset:49152
	v_mfma_f32_16x16x32_bf16 v[104:107], v[194:197], v[136:139], v[104:107]
	ds_read_b128 v[222:225], v235 offset:50176
	v_mfma_f32_16x16x32_bf16 v[96:99], v[202:205], v[136:139], v[96:99]
	ds_read_b128 v[226:229], v235 offset:51200
	s_add_u32 m0, s40, 0x18000
	v_mfma_f32_16x16x32_bf16 v[88:91], v[194:197], v[144:147], v[88:91]
	ds_read_b128 v[230:233], v235 offset:52224
	v_mfma_f32_16x16x32_bf16 v[80:83], v[202:205], v[144:147], v[80:83]
	global_load_lds_dwordx4 v236, s[26:27]
	v_mfma_f32_16x16x32_bf16 v[72:75], v[194:197], v[152:155], v[72:75]
	v_mfma_f32_16x16x32_bf16 v[64:67], v[202:205], v[152:155], v[64:67]
	s_add_u32 m0, s40, 0x1a000
	v_mfma_f32_16x16x32_bf16 v[120:123], v[198:201], v[132:135], v[120:123]
	v_mfma_f32_16x16x32_bf16 v[112:115], v[206:209], v[132:135], v[112:115]
	global_load_lds_dwordx4 v237, s[26:27]
	v_mfma_f32_16x16x32_bf16 v[104:107], v[198:201], v[140:143], v[104:107]
	v_mfma_f32_16x16x32_bf16 v[96:99], v[206:209], v[140:143], v[96:99]
	s_add_u32 s26, s26, 0x80
	s_addc_u32 s27, s27, 0
	v_mfma_f32_16x16x32_bf16 v[88:91], v[198:201], v[148:151], v[88:91]
	v_mfma_f32_16x16x32_bf16 v[80:83], v[206:209], v[148:151], v[80:83]
	v_mfma_f32_16x16x32_bf16 v[72:75], v[198:201], v[156:159], v[72:75]
	v_mfma_f32_16x16x32_bf16 v[64:67], v[206:209], v[156:159], v[64:67]
	s_waitcnt vmcnt(12) lgkmcnt(0)
	s_barrier
	v_mfma_f32_16x16x32_bf16 v[124:127], v[218:221], v[128:131], v[124:127]
	v_mfma_f32_16x16x32_bf16 v[116:119], v[226:229], v[128:131], v[116:119]
	ds_read_b128 v[160:163], v234 offset:49152
	v_mfma_f32_16x16x32_bf16 v[108:111], v[218:221], v[136:139], v[108:111]
	ds_read_b128 v[164:167], v234 offset:50176
	v_mfma_f32_16x16x32_bf16 v[100:103], v[226:229], v[136:139], v[100:103]
	ds_read_b128 v[168:171], v234 offset:51200
	s_add_u32 m0, s40, 0x1c000
	v_mfma_f32_16x16x32_bf16 v[92:95], v[218:221], v[144:147], v[92:95]
	ds_read_b128 v[172:175], v234 offset:52224
	v_mfma_f32_16x16x32_bf16 v[84:87], v[226:229], v[144:147], v[84:87]
	ds_read_b128 v[176:179], v234 offset:53248
	global_load_lds_dwordx4 v236, s[38:39]
	v_mfma_f32_16x16x32_bf16 v[76:79], v[218:221], v[152:155], v[76:79]
	ds_read_b128 v[180:183], v234 offset:54272
	v_mfma_f32_16x16x32_bf16 v[68:71], v[226:229], v[152:155], v[68:71]
	ds_read_b128 v[184:187], v234 offset:55296
	s_add_u32 m0, s40, 0x1e000
	v_mfma_f32_16x16x32_bf16 v[124:127], v[222:225], v[132:135], v[124:127]
	ds_read_b128 v[188:191], v234 offset:56320
	v_mfma_f32_16x16x32_bf16 v[116:119], v[230:233], v[132:135], v[116:119]
	global_load_lds_dwordx4 v237, s[38:39]
	v_mfma_f32_16x16x32_bf16 v[108:111], v[222:225], v[140:143], v[108:111]
	v_mfma_f32_16x16x32_bf16 v[100:103], v[230:233], v[140:143], v[100:103]
	s_add_u32 s38, s38, 0x80
	s_addc_u32 s39, s39, 0
	v_mfma_f32_16x16x32_bf16 v[92:95], v[222:225], v[148:151], v[92:95]
	v_mfma_f32_16x16x32_bf16 v[84:87], v[230:233], v[148:151], v[84:87]
	v_mfma_f32_16x16x32_bf16 v[76:79], v[222:225], v[156:159], v[76:79]
	v_mfma_f32_16x16x32_bf16 v[68:71], v[230:233], v[156:159], v[68:71]
	s_waitcnt lgkmcnt(0)
	s_barrier
	v_mfma_f32_16x16x32_bf16 v[56:59], v[194:197], v[160:163], v[56:59]
	v_mfma_f32_16x16x32_bf16 v[48:51], v[202:205], v[160:163], v[48:51]
	v_mfma_f32_16x16x32_bf16 v[40:43], v[194:197], v[168:171], v[40:43]
	v_mfma_f32_16x16x32_bf16 v[32:35], v[202:205], v[168:171], v[32:35]
	s_add_u32 m0, s40, 0xc000
	v_mfma_f32_16x16x32_bf16 v[24:27], v[194:197], v[176:179], v[24:27]
	v_mfma_f32_16x16x32_bf16 v[16:19], v[202:205], v[176:179], v[16:19]
	global_load_lds_dwordx4 v236, s[8:9]
	v_mfma_f32_16x16x32_bf16 v[8:11], v[194:197], v[184:187], v[8:11]
	v_mfma_f32_16x16x32_bf16 v[0:3], v[202:205], v[184:187], v[0:3]
	s_add_u32 m0, s40, 0xe000
	v_mfma_f32_16x16x32_bf16 v[56:59], v[198:201], v[164:167], v[56:59]
	v_mfma_f32_16x16x32_bf16 v[48:51], v[206:209], v[164:167], v[48:51]
	global_load_lds_dwordx4 v237, s[8:9]
	v_mfma_f32_16x16x32_bf16 v[40:43], v[198:201], v[172:175], v[40:43]
	v_mfma_f32_16x16x32_bf16 v[32:35], v[206:209], v[172:175], v[32:35]
	s_add_u32 s8, s8, 0x80
	s_addc_u32 s9, s9, 0
	v_mfma_f32_16x16x32_bf16 v[24:27], v[198:201], v[180:183], v[24:27]
	v_mfma_f32_16x16x32_bf16 v[16:19], v[206:209], v[180:183], v[16:19]
	v_mfma_f32_16x16x32_bf16 v[8:11], v[198:201], v[188:191], v[8:11]
	v_mfma_f32_16x16x32_bf16 v[0:3], v[206:209], v[188:191], v[0:3]
	v_mfma_f32_16x16x32_bf16 v[60:63], v[218:221], v[160:163], v[60:63]
	v_mfma_f32_16x16x32_bf16 v[52:55], v[226:229], v[160:163], v[52:55]
	v_mfma_f32_16x16x32_bf16 v[44:47], v[218:221], v[168:171], v[44:47]
	v_mfma_f32_16x16x32_bf16 v[36:39], v[226:229], v[168:171], v[36:39]
	v_mfma_f32_16x16x32_bf16 v[28:31], v[218:221], v[176:179], v[28:31]
	v_mfma_f32_16x16x32_bf16 v[20:23], v[226:229], v[176:179], v[20:23]
	v_mfma_f32_16x16x32_bf16 v[12:15], v[218:221], v[184:187], v[12:15]
	v_mfma_f32_16x16x32_bf16 v[4:7], v[226:229], v[184:187], v[4:7]
	v_mfma_f32_16x16x32_bf16 v[60:63], v[222:225], v[164:167], v[60:63]
	v_mfma_f32_16x16x32_bf16 v[52:55], v[230:233], v[164:167], v[52:55]
	v_mfma_f32_16x16x32_bf16 v[44:47], v[222:225], v[172:175], v[44:47]
	v_mfma_f32_16x16x32_bf16 v[36:39], v[230:233], v[172:175], v[36:39]
	v_mfma_f32_16x16x32_bf16 v[28:31], v[222:225], v[180:183], v[28:31]
	v_mfma_f32_16x16x32_bf16 v[20:23], v[230:233], v[180:183], v[20:23]
	v_mfma_f32_16x16x32_bf16 v[12:15], v[222:225], v[188:191], v[12:15]
	v_mfma_f32_16x16x32_bf16 v[4:7], v[230:233], v[188:191], v[4:7]
	s_branch .Lmy_kloop_end
; #define STAGE(P, BASE, br, kt) do { const u16* _gb = (BASE) + ((size_t)(br) * K + (size_t)(kt) * BK); \
;     __builtin_amdgcn_global_load_lds((const unsigned*)(_gb + goff0), (unsigned*)((char*)(P) + tid * 16), 16, 0, 0); \
;     __builtin_amdgcn_global_load_lds((const unsigned*)(_gb + (size_t)64 * K + goff0), (unsigned*)((char*)(P) + tid * 16 + 8192), 16, 0, 0); } while (0)
; #define LDA(dst, b, h) _Pragma("unroll") for (int m = 0; m < 4; ++m) _Pragma("unroll") for (int k = 0; k < 2; ++k) \
;     dst[m][k] = *reinterpret_cast<const bf16x8*>((char*)SA(b, h) + lds_byte(wr * 64 + m * 16 + fr, k * 32 + fq * 8))
; #define LDB(dst, b, h) _Pragma("unroll") for (int n = 0; n < 2; ++n) _Pragma("unroll") for (int k = 0; k < 2; ++k) \
;     dst[n][k] = *reinterpret_cast<const bf16x8*>((char*)SB(b, h) + lds_byte(wc * 32 + n * 16 + fr, k * 32 + fq * 8))
; #define MMA(ai, bj, At, Bt_) do { __builtin_amdgcn_s_setprio(1); \
;     _Pragma("unroll") for (int m = 0; m < 4; ++m) _Pragma("unroll") for (int n = 0; n < 2; ++n) _Pragma("unroll") for (int k = 0; k < 2; ++k) \
;       acc[ai][bj][m][n] = __builtin_amdgcn_mfma_f32_16x16x32_bf16(Bt_[n][k], At[m][k], acc[ai][bj][m][n], 0, 0, 0); \
;     __builtin_amdgcn_s_setprio(0); } while (0)
; #define WAIT_V(n) asm volatile("s_waitcnt vmcnt(" #n ")" ::: "memory")
; #define WAIT_L(n) asm volatile("s_waitcnt lgkmcnt(" #n ")" ::: "memory")
; #define BAR __builtin_amdgcn_s_barrier()
; __device__ __forceinline__ void gemm_phase(KP p, char* shmc, const u16* __restrict__ A,
;                                            const u16* __restrict__ Bt, const int N, const int K, const int mode,
;                                            const float* __restrict__ xin, const float resw) {
;     ...
;     { LDB(B0, 0, 0); LDA(At, 0, 0); STAGE(SA(1, 1), A, brow + HALF, nt - 1);
;       BAR; WAIT_L(0); MMA(0, 0, At, B0); BAR;
;       LDB(B1, 0, 1); BAR; WAIT_L(0); MMA(0, 1, At, B1); BAR;
;       LDA(At, 0, 1); WAIT_V(4); BAR; WAIT_L(0); MMA(1, 0, At, B0); MMA(1, 1, At, B1); BAR; }
;     { LDB(B0, 1, 0); LDA(At, 1, 0); WAIT_V(2); BAR; WAIT_L(0); MMA(0, 0, At, B0); BAR;
;       LDB(B1, 1, 1); WAIT_V(0); BAR; WAIT_L(0); MMA(0, 1, At, B1); BAR;
;       LDA(At, 1, 1); BAR; WAIT_L(0); MMA(1, 0, At, B0); MMA(1, 1, At, B1); BAR; }
.Lmy_kloop_t2plain:
	s_waitcnt vmcnt(10) lgkmcnt(0)
	s_barrier
	v_mfma_f32_16x16x32_bf16 v[120:123], v[194:197], v[128:131], v[120:123]
	v_mfma_f32_16x16x32_bf16 v[112:115], v[202:205], v[128:131], v[112:115]
	ds_read_b128 v[218:221], v235 offset:16384
	v_mfma_f32_16x16x32_bf16 v[104:107], v[194:197], v[136:139], v[104:107]
	ds_read_b128 v[222:225], v235 offset:17408
	v_mfma_f32_16x16x32_bf16 v[96:99], v[202:205], v[136:139], v[96:99]
	ds_read_b128 v[226:229], v235 offset:18432
	v_mfma_f32_16x16x32_bf16 v[88:91], v[194:197], v[144:147], v[88:91]
	ds_read_b128 v[230:233], v235 offset:19456
	v_mfma_f32_16x16x32_bf16 v[80:83], v[202:205], v[144:147], v[80:83]
	v_mfma_f32_16x16x32_bf16 v[72:75], v[194:197], v[152:155], v[72:75]
	v_mfma_f32_16x16x32_bf16 v[64:67], v[202:205], v[152:155], v[64:67]
	v_mfma_f32_16x16x32_bf16 v[120:123], v[198:201], v[132:135], v[120:123]
	v_mfma_f32_16x16x32_bf16 v[112:115], v[206:209], v[132:135], v[112:115]
	v_mfma_f32_16x16x32_bf16 v[104:107], v[198:201], v[140:143], v[104:107]
	v_mfma_f32_16x16x32_bf16 v[96:99], v[206:209], v[140:143], v[96:99]
	v_mfma_f32_16x16x32_bf16 v[88:91], v[198:201], v[148:151], v[88:91]
	v_mfma_f32_16x16x32_bf16 v[80:83], v[206:209], v[148:151], v[80:83]
	v_mfma_f32_16x16x32_bf16 v[72:75], v[198:201], v[156:159], v[72:75]
	v_mfma_f32_16x16x32_bf16 v[64:67], v[206:209], v[156:159], v[64:67]
	s_waitcnt vmcnt(8) lgkmcnt(0)
	s_barrier
	v_mfma_f32_16x16x32_bf16 v[124:127], v[218:221], v[128:131], v[124:127]
	v_mfma_f32_16x16x32_bf16 v[116:119], v[226:229], v[128:131], v[116:119]
	ds_read_b128 v[160:163], v234 offset:16384
	v_mfma_f32_16x16x32_bf16 v[108:111], v[218:221], v[136:139], v[108:111]
	ds_read_b128 v[164:167], v234 offset:17408
	v_mfma_f32_16x16x32_bf16 v[100:103], v[226:229], v[136:139], v[100:103]
	ds_read_b128 v[168:171], v234 offset:18432
	v_mfma_f32_16x16x32_bf16 v[92:95], v[218:221], v[144:147], v[92:95]
	ds_read_b128 v[172:175], v234 offset:19456
	v_mfma_f32_16x16x32_bf16 v[84:87], v[226:229], v[144:147], v[84:87]
	ds_read_b128 v[176:179], v234 offset:20480
	v_mfma_f32_16x16x32_bf16 v[76:79], v[218:221], v[152:155], v[76:79]
	ds_read_b128 v[180:183], v234 offset:21504
	v_mfma_f32_16x16x32_bf16 v[68:71], v[226:229], v[152:155], v[68:71]
	ds_read_b128 v[184:187], v234 offset:22528
	v_mfma_f32_16x16x32_bf16 v[124:127], v[222:225], v[132:135], v[124:127]
	ds_read_b128 v[188:191], v234 offset:23552
	v_mfma_f32_16x16x32_bf16 v[116:119], v[230:233], v[132:135], v[116:119]
	v_mfma_f32_16x16x32_bf16 v[108:111], v[222:225], v[140:143], v[108:111]
	v_mfma_f32_16x16x32_bf16 v[100:103], v[230:233], v[140:143], v[100:103]
	v_mfma_f32_16x16x32_bf16 v[92:95], v[222:225], v[148:151], v[92:95]
	v_mfma_f32_16x16x32_bf16 v[84:87], v[230:233], v[148:151], v[84:87]
	v_mfma_f32_16x16x32_bf16 v[76:79], v[222:225], v[156:159], v[76:79]
	v_mfma_f32_16x16x32_bf16 v[68:71], v[230:233], v[156:159], v[68:71]
	s_waitcnt vmcnt(6) lgkmcnt(0)
	s_barrier
	v_mfma_f32_16x16x32_bf16 v[56:59], v[194:197], v[160:163], v[56:59]
	v_mfma_f32_16x16x32_bf16 v[48:51], v[202:205], v[160:163], v[48:51]
	ds_read_b128 v[128:131], v234 offset:32768
	v_mfma_f32_16x16x32_bf16 v[40:43], v[194:197], v[168:171], v[40:43]
	ds_read_b128 v[132:135], v234 offset:33792
	v_mfma_f32_16x16x32_bf16 v[32:35], v[202:205], v[168:171], v[32:35]
	ds_read_b128 v[136:139], v234 offset:34816
	v_mfma_f32_16x16x32_bf16 v[24:27], v[194:197], v[176:179], v[24:27]
	ds_read_b128 v[140:143], v234 offset:35840
	v_mfma_f32_16x16x32_bf16 v[16:19], v[202:205], v[176:179], v[16:19]
	ds_read_b128 v[144:147], v234 offset:36864
	v_mfma_f32_16x16x32_bf16 v[8:11], v[194:197], v[184:187], v[8:11]
	ds_read_b128 v[148:151], v234 offset:37888
	v_mfma_f32_16x16x32_bf16 v[0:3], v[202:205], v[184:187], v[0:3]
	ds_read_b128 v[152:155], v234 offset:38912
	v_mfma_f32_16x16x32_bf16 v[56:59], v[198:201], v[164:167], v[56:59]
	ds_read_b128 v[156:159], v234 offset:39936
	v_mfma_f32_16x16x32_bf16 v[48:51], v[206:209], v[164:167], v[48:51]
	v_mfma_f32_16x16x32_bf16 v[40:43], v[198:201], v[172:175], v[40:43]
	v_mfma_f32_16x16x32_bf16 v[32:35], v[206:209], v[172:175], v[32:35]
	v_mfma_f32_16x16x32_bf16 v[24:27], v[198:201], v[180:183], v[24:27]
	v_mfma_f32_16x16x32_bf16 v[16:19], v[206:209], v[180:183], v[16:19]
	v_mfma_f32_16x16x32_bf16 v[8:11], v[198:201], v[188:191], v[8:11]
	v_mfma_f32_16x16x32_bf16 v[0:3], v[206:209], v[188:191], v[0:3]
	s_waitcnt vmcnt(4) lgkmcnt(0)
	s_barrier
	v_mfma_f32_16x16x32_bf16 v[60:63], v[218:221], v[160:163], v[60:63]
	v_mfma_f32_16x16x32_bf16 v[52:55], v[226:229], v[160:163], v[52:55]
	ds_read_b128 v[194:197], v235 offset:32768
	v_mfma_f32_16x16x32_bf16 v[44:47], v[218:221], v[168:171], v[44:47]
	ds_read_b128 v[198:201], v235 offset:33792
	v_mfma_f32_16x16x32_bf16 v[36:39], v[226:229], v[168:171], v[36:39]
	ds_read_b128 v[202:205], v235 offset:34816
	v_mfma_f32_16x16x32_bf16 v[28:31], v[218:221], v[176:179], v[28:31]
	ds_read_b128 v[206:209], v235 offset:35840
	v_mfma_f32_16x16x32_bf16 v[20:23], v[226:229], v[176:179], v[20:23]
	v_mfma_f32_16x16x32_bf16 v[12:15], v[218:221], v[184:187], v[12:15]
	v_mfma_f32_16x16x32_bf16 v[4:7], v[226:229], v[184:187], v[4:7]
	v_mfma_f32_16x16x32_bf16 v[60:63], v[222:225], v[164:167], v[60:63]
	v_mfma_f32_16x16x32_bf16 v[52:55], v[230:233], v[164:167], v[52:55]
	v_mfma_f32_16x16x32_bf16 v[44:47], v[222:225], v[172:175], v[44:47]
	v_mfma_f32_16x16x32_bf16 v[36:39], v[230:233], v[172:175], v[36:39]
	v_mfma_f32_16x16x32_bf16 v[28:31], v[222:225], v[180:183], v[28:31]
	v_mfma_f32_16x16x32_bf16 v[20:23], v[230:233], v[180:183], v[20:23]
	v_mfma_f32_16x16x32_bf16 v[12:15], v[222:225], v[188:191], v[12:15]
	v_mfma_f32_16x16x32_bf16 v[4:7], v[230:233], v[188:191], v[4:7]
	s_waitcnt vmcnt(2) lgkmcnt(0)
	s_barrier
; #define STAGE(P, BASE, br, kt) do { const u16* _gb = (BASE) + ((size_t)(br) * K + (size_t)(kt) * BK); \
;     __builtin_amdgcn_global_load_lds((const unsigned*)(_gb + goff0), (unsigned*)((char*)(P) + tid * 16), 16, 0, 0); \
;     __builtin_amdgcn_global_load_lds((const unsigned*)(_gb + (size_t)64 * K + goff0), (unsigned*)((char*)(P) + tid * 16 + 8192), 16, 0, 0); } while (0)
; #define LDA(dst, b, h) _Pragma("unroll") for (int m = 0; m < 4; ++m) _Pragma("unroll") for (int k = 0; k < 2; ++k) \
;     dst[m][k] = *reinterpret_cast<const bf16x8*>((char*)SA(b, h) + lds_byte(wr * 64 + m * 16 + fr, k * 32 + fq * 8))
; #define LDB(dst, b, h) _Pragma("unroll") for (int n = 0; n < 2; ++n) _Pragma("unroll") for (int k = 0; k < 2; ++k) \
;     dst[n][k] = *reinterpret_cast<const bf16x8*>((char*)SB(b, h) + lds_byte(wc * 32 + n * 16 + fr, k * 32 + fq * 8))
; #define MMA(ai, bj, At, Bt_) do { __builtin_amdgcn_s_setprio(1); \
;     _Pragma("unroll") for (int m = 0; m < 4; ++m) _Pragma("unroll") for (int n = 0; n < 2; ++n) _Pragma("unroll") for (int k = 0; k < 2; ++k) \
;       acc[ai][bj][m][n] = __builtin_amdgcn_mfma_f32_16x16x32_bf16(Bt_[n][k], At[m][k], acc[ai][bj][m][n], 0, 0, 0); \
;     __builtin_amdgcn_s_setprio(0); } while (0)
; #define WAIT_V(n) asm volatile("s_waitcnt vmcnt(" #n ")" ::: "memory")
; #define WAIT_L(n) asm volatile("s_waitcnt lgkmcnt(" #n ")" ::: "memory")
; #define BAR __builtin_amdgcn_s_barrier()
; __device__ __forceinline__ void gemm_phase(KP p, char* shmc, const u16* __restrict__ A,
;                                            const u16* __restrict__ Bt, const int N, const int K, const int mode,
;                                            const float* __restrict__ xin, const float resw) {
;     ...
;     { LDB(B0, 0, 0); LDA(At, 0, 0); STAGE(SA(1, 1), A, brow + HALF, nt - 1);
;       BAR; WAIT_L(0); MMA(0, 0, At, B0); BAR;
;       LDB(B1, 0, 1); BAR; WAIT_L(0); MMA(0, 1, At, B1); BAR;
;       LDA(At, 0, 1); WAIT_V(4); BAR; WAIT_L(0); MMA(1, 0, At, B0); MMA(1, 1, At, B1); BAR; }
;     { LDB(B0, 1, 0); LDA(At, 1, 0); WAIT_V(2); BAR; WAIT_L(0); MMA(0, 0, At, B0); BAR;
;       LDB(B1, 1, 1); WAIT_V(0); BAR; WAIT_L(0); MMA(0, 1, At, B1); BAR;
;       LDA(At, 1, 1); BAR; WAIT_L(0); MMA(1, 0, At, B0); MMA(1, 1, At, B1); BAR; }
	v_mfma_f32_16x16x32_bf16 v[120:123], v[194:197], v[128:131], v[120:123]
	v_mfma_f32_16x16x32_bf16 v[112:115], v[202:205], v[128:131], v[112:115]
	ds_read_b128 v[218:221], v235 offset:49152
	v_mfma_f32_16x16x32_bf16 v[104:107], v[194:197], v[136:139], v[104:107]
	ds_read_b128 v[222:225], v235 offset:50176
	v_mfma_f32_16x16x32_bf16 v[96:99], v[202:205], v[136:139], v[96:99]
	ds_read_b128 v[226:229], v235 offset:51200
	v_mfma_f32_16x16x32_bf16 v[88:91], v[194:197], v[144:147], v[88:91]
	ds_read_b128 v[230:233], v235 offset:52224
	v_mfma_f32_16x16x32_bf16 v[80:83], v[202:205], v[144:147], v[80:83]
	v_mfma_f32_16x16x32_bf16 v[72:75], v[194:197], v[152:155], v[72:75]
	v_mfma_f32_16x16x32_bf16 v[64:67], v[202:205], v[152:155], v[64:67]
	v_mfma_f32_16x16x32_bf16 v[120:123], v[198:201], v[132:135], v[120:123]
	v_mfma_f32_16x16x32_bf16 v[112:115], v[206:209], v[132:135], v[112:115]
	v_mfma_f32_16x16x32_bf16 v[104:107], v[198:201], v[140:143], v[104:107]
	v_mfma_f32_16x16x32_bf16 v[96:99], v[206:209], v[140:143], v[96:99]
	v_mfma_f32_16x16x32_bf16 v[88:91], v[198:201], v[148:151], v[88:91]
	v_mfma_f32_16x16x32_bf16 v[80:83], v[206:209], v[148:151], v[80:83]
	v_mfma_f32_16x16x32_bf16 v[72:75], v[198:201], v[156:159], v[72:75]
	v_mfma_f32_16x16x32_bf16 v[64:67], v[206:209], v[156:159], v[64:67]
	s_waitcnt vmcnt(0) lgkmcnt(0)
	s_barrier
	v_mfma_f32_16x16x32_bf16 v[124:127], v[218:221], v[128:131], v[124:127]
	v_mfma_f32_16x16x32_bf16 v[116:119], v[226:229], v[128:131], v[116:119]
	ds_read_b128 v[160:163], v234 offset:49152
	v_mfma_f32_16x16x32_bf16 v[108:111], v[218:221], v[136:139], v[108:111]
	ds_read_b128 v[164:167], v234 offset:50176
	v_mfma_f32_16x16x32_bf16 v[100:103], v[226:229], v[136:139], v[100:103]
	ds_read_b128 v[168:171], v234 offset:51200
	v_mfma_f32_16x16x32_bf16 v[92:95], v[218:221], v[144:147], v[92:95]
	ds_read_b128 v[172:175], v234 offset:52224
	v_mfma_f32_16x16x32_bf16 v[84:87], v[226:229], v[144:147], v[84:87]
	ds_read_b128 v[176:179], v234 offset:53248
	v_mfma_f32_16x16x32_bf16 v[76:79], v[218:221], v[152:155], v[76:79]
	ds_read_b128 v[180:183], v234 offset:54272
	v_mfma_f32_16x16x32_bf16 v[68:71], v[226:229], v[152:155], v[68:71]
	ds_read_b128 v[184:187], v234 offset:55296
	v_mfma_f32_16x16x32_bf16 v[124:127], v[222:225], v[132:135], v[124:127]
	ds_read_b128 v[188:191], v234 offset:56320
	v_mfma_f32_16x16x32_bf16 v[116:119], v[230:233], v[132:135], v[116:119]
	v_mfma_f32_16x16x32_bf16 v[108:111], v[222:225], v[140:143], v[108:111]
	v_mfma_f32_16x16x32_bf16 v[100:103], v[230:233], v[140:143], v[100:103]
	v_mfma_f32_16x16x32_bf16 v[92:95], v[222:225], v[148:151], v[92:95]
	v_mfma_f32_16x16x32_bf16 v[84:87], v[230:233], v[148:151], v[84:87]
	v_mfma_f32_16x16x32_bf16 v[76:79], v[222:225], v[156:159], v[76:79]
	v_mfma_f32_16x16x32_bf16 v[68:71], v[230:233], v[156:159], v[68:71]
	s_waitcnt lgkmcnt(0)
	s_barrier
	v_mfma_f32_16x16x32_bf16 v[56:59], v[194:197], v[160:163], v[56:59]
	v_mfma_f32_16x16x32_bf16 v[48:51], v[202:205], v[160:163], v[48:51]
	v_mfma_f32_16x16x32_bf16 v[40:43], v[194:197], v[168:171], v[40:43]
	v_mfma_f32_16x16x32_bf16 v[32:35], v[202:205], v[168:171], v[32:35]
	v_mfma_f32_16x16x32_bf16 v[24:27], v[194:197], v[176:179], v[24:27]
	v_mfma_f32_16x16x32_bf16 v[16:19], v[202:205], v[176:179], v[16:19]
	v_mfma_f32_16x16x32_bf16 v[8:11], v[194:197], v[184:187], v[8:11]
	v_mfma_f32_16x16x32_bf16 v[0:3], v[202:205], v[184:187], v[0:3]
	v_mfma_f32_16x16x32_bf16 v[56:59], v[198:201], v[164:167], v[56:59]
	v_mfma_f32_16x16x32_bf16 v[48:51], v[206:209], v[164:167], v[48:51]
	v_mfma_f32_16x16x32_bf16 v[40:43], v[198:201], v[172:175], v[40:43]
	v_mfma_f32_16x16x32_bf16 v[32:35], v[206:209], v[172:175], v[32:35]
	v_mfma_f32_16x16x32_bf16 v[24:27], v[198:201], v[180:183], v[24:27]
	v_mfma_f32_16x16x32_bf16 v[16:19], v[206:209], v[180:183], v[16:19]
	v_mfma_f32_16x16x32_bf16 v[8:11], v[198:201], v[188:191], v[8:11]
	v_mfma_f32_16x16x32_bf16 v[0:3], v[206:209], v[188:191], v[0:3]
	v_mfma_f32_16x16x32_bf16 v[60:63], v[218:221], v[160:163], v[60:63]
	v_mfma_f32_16x16x32_bf16 v[52:55], v[226:229], v[160:163], v[52:55]
	v_mfma_f32_16x16x32_bf16 v[44:47], v[218:221], v[168:171], v[44:47]
	v_mfma_f32_16x16x32_bf16 v[36:39], v[226:229], v[168:171], v[36:39]
	v_mfma_f32_16x16x32_bf16 v[28:31], v[218:221], v[176:179], v[28:31]
	v_mfma_f32_16x16x32_bf16 v[20:23], v[226:229], v[176:179], v[20:23]
	v_mfma_f32_16x16x32_bf16 v[12:15], v[218:221], v[184:187], v[12:15]
	v_mfma_f32_16x16x32_bf16 v[4:7], v[226:229], v[184:187], v[4:7]
	v_mfma_f32_16x16x32_bf16 v[60:63], v[222:225], v[164:167], v[60:63]
	v_mfma_f32_16x16x32_bf16 v[52:55], v[230:233], v[164:167], v[52:55]
	v_mfma_f32_16x16x32_bf16 v[44:47], v[222:225], v[172:175], v[44:47]
	v_mfma_f32_16x16x32_bf16 v[36:39], v[230:233], v[172:175], v[36:39]
	v_mfma_f32_16x16x32_bf16 v[28:31], v[222:225], v[180:183], v[28:31]
	v_mfma_f32_16x16x32_bf16 v[20:23], v[230:233], v[180:183], v[20:23]
	v_mfma_f32_16x16x32_bf16 v[12:15], v[222:225], v[188:191], v[12:15]
	v_mfma_f32_16x16x32_bf16 v[4:7], v[230:233], v[188:191], v[4:7]
.Lmy_kloop_end:
	s_branch .Lmy_join
; #define STAGE(P, BASE, br, kt) do { const u16* _gb = (BASE) + ((size_t)(br) * K + (size_t)(kt) * BK); \
;     __builtin_amdgcn_global_load_lds((const unsigned*)(_gb + goff0), (unsigned*)((char*)(P) + tid * 16), 16, 0, 0); \
;     __builtin_amdgcn_global_load_lds((const unsigned*)(_gb + (size_t)64 * K + goff0), (unsigned*)((char*)(P) + tid * 16 + 8192), 16, 0, 0); } while (0)
; #define LDA(dst, b, h) _Pragma("unroll") for (int m = 0; m < 4; ++m) _Pragma("unroll") for (int k = 0; k < 2; ++k) \
;     dst[m][k] = *reinterpret_cast<const bf16x8*>((char*)SA(b, h) + lds_byte(wr * 64 + m * 16 + fr, k * 32 + fq * 8))
; #define LDB(dst, b, h) _Pragma("unroll") for (int n = 0; n < 2; ++n) _Pragma("unroll") for (int k = 0; k < 2; ++k) \
;     dst[n][k] = *reinterpret_cast<const bf16x8*>((char*)SB(b, h) + lds_byte(wc * 32 + n * 16 + fr, k * 32 + fq * 8))
; #define WAIT_V(n) asm volatile("s_waitcnt vmcnt(" #n ")" ::: "memory")
; #define WAIT_L(n) asm volatile("s_waitcnt lgkmcnt(" #n ")" ::: "memory")
; #define BAR __builtin_amdgcn_s_barrier()
; #define SCHED __builtin_amdgcn_sched_barrier(0)
; __device__ __forceinline__ void gemm_phase(KP p, char* shmc, const u16* __restrict__ A,
;                                            const u16* __restrict__ Bt, const int N, const int K, const int mode,
;                                            const float* __restrict__ xin, const float resw) {
;     ...
;     f32x4 acc[2][2][4][2];
; #pragma unroll
;     for (int a = 0; a < 2; ++a)
; #pragma unroll
;       for (int b = 0; b < 2; ++b)
; #pragma unroll
;         for (int m = 0; m < 4; ++m)
; #pragma unroll
;           for (int n = 0; n < 2; ++n) acc[a][b][m][n] = f32x4{0.f, 0.f, 0.f, 0.f};
;     bf16x8 At[4][2], B0[2][2], B1[2][2];
;     WAIT_V(0);
;     if (wr == 1) BAR;
;     BAR;
;     for (int t = 0; t < nt - 2; t += 2) {
;       LDB(B0, 0, 0); SCHED; LDA(At, 0, 0); STAGE(SA(1, 1), A, brow + HALF, t + 1);
;       WAIT_L(8); BAR; WAIT_L(0); MMA(0, 0, At, B0); BAR; SCHED;
;       LDB(B1, 0, 1); STAGE(SB(0, 0), Bt, bcol, t + 2);
;       BAR; WAIT_L(0); MMA(0, 1, At, B1); BAR;
;       LDA(At, 0, 1); STAGE(SA(0, 0), A, brow, t + 2);
;       BAR; WAIT_L(0); MMA(1, 0, At, B0); BAR; SCHED;
;       STAGE(SB(0, 1), Bt, bcol + HALF, t + 2);
;       WAIT_V(6); BAR; MMA(1, 1, At, B1); BAR;
.Lmy_entry_sw:
	s_waitcnt vmcnt(12) lgkmcnt(0)
	s_barrier
	v_mfma_f32_16x16x32_bf16 v[120:123], v[128:131], v[194:197], 0
	v_mfma_f32_16x16x32_bf16 v[112:115], v[128:131], v[202:205], 0
	ds_read_b128 v[218:221], v235 offset:16384
	v_mfma_f32_16x16x32_bf16 v[104:107], v[136:139], v[194:197], 0
	ds_read_b128 v[222:225], v235 offset:17408
	v_mfma_f32_16x16x32_bf16 v[96:99], v[136:139], v[202:205], 0
	ds_read_b128 v[226:229], v235 offset:18432
	s_add_u32 m0, s40, 0x10000
	v_mfma_f32_16x16x32_bf16 v[88:91], v[144:147], v[194:197], 0
	ds_read_b128 v[230:233], v235 offset:19456
	v_mfma_f32_16x16x32_bf16 v[80:83], v[144:147], v[202:205], 0
	global_load_lds_dwordx4 v236, s[26:27]
	v_mfma_f32_16x16x32_bf16 v[72:75], v[152:155], v[194:197], 0
	v_mfma_f32_16x16x32_bf16 v[64:67], v[152:155], v[202:205], 0
	s_add_u32 m0, s40, 0x12000
	v_mfma_f32_16x16x32_bf16 v[120:123], v[132:135], v[198:201], v[120:123]
	v_mfma_f32_16x16x32_bf16 v[112:115], v[132:135], v[206:209], v[112:115]
	global_load_lds_dwordx4 v237, s[26:27]
	v_mfma_f32_16x16x32_bf16 v[104:107], v[140:143], v[198:201], v[104:107]
	v_mfma_f32_16x16x32_bf16 v[96:99], v[140:143], v[206:209], v[96:99]
	s_add_u32 s26, s26, 0x80
	s_addc_u32 s27, s27, 0
	v_mfma_f32_16x16x32_bf16 v[88:91], v[148:151], v[198:201], v[88:91]
	v_mfma_f32_16x16x32_bf16 v[80:83], v[148:151], v[206:209], v[80:83]
	v_mfma_f32_16x16x32_bf16 v[72:75], v[156:159], v[198:201], v[72:75]
	v_mfma_f32_16x16x32_bf16 v[64:67], v[156:159], v[206:209], v[64:67]
	s_waitcnt vmcnt(12) lgkmcnt(0)
	s_barrier
	v_mfma_f32_16x16x32_bf16 v[124:127], v[128:131], v[218:221], 0
	v_mfma_f32_16x16x32_bf16 v[116:119], v[128:131], v[226:229], 0
	ds_read_b128 v[160:163], v234 offset:16384
	v_mfma_f32_16x16x32_bf16 v[108:111], v[136:139], v[218:221], 0
	ds_read_b128 v[164:167], v234 offset:17408
	v_mfma_f32_16x16x32_bf16 v[100:103], v[136:139], v[226:229], 0
	ds_read_b128 v[168:171], v234 offset:18432
	s_add_u32 m0, s40, 0x14000
	v_mfma_f32_16x16x32_bf16 v[92:95], v[144:147], v[218:221], 0
	ds_read_b128 v[172:175], v234 offset:19456
	v_mfma_f32_16x16x32_bf16 v[84:87], v[144:147], v[226:229], 0
	ds_read_b128 v[176:179], v234 offset:20480
	global_load_lds_dwordx4 v236, s[38:39]
	v_mfma_f32_16x16x32_bf16 v[76:79], v[152:155], v[218:221], 0
	ds_read_b128 v[180:183], v234 offset:21504
	v_mfma_f32_16x16x32_bf16 v[68:71], v[152:155], v[226:229], 0
	ds_read_b128 v[184:187], v234 offset:22528
	s_add_u32 m0, s40, 0x16000
	v_mfma_f32_16x16x32_bf16 v[124:127], v[132:135], v[222:225], v[124:127]
	ds_read_b128 v[188:191], v234 offset:23552
	v_mfma_f32_16x16x32_bf16 v[116:119], v[132:135], v[230:233], v[116:119]
	global_load_lds_dwordx4 v237, s[38:39]
	v_mfma_f32_16x16x32_bf16 v[108:111], v[140:143], v[222:225], v[108:111]
	v_mfma_f32_16x16x32_bf16 v[100:103], v[140:143], v[230:233], v[100:103]
	s_add_u32 s38, s38, 0x80
	s_addc_u32 s39, s39, 0
	v_mfma_f32_16x16x32_bf16 v[92:95], v[148:151], v[222:225], v[92:95]
	v_mfma_f32_16x16x32_bf16 v[84:87], v[148:151], v[230:233], v[84:87]
	v_mfma_f32_16x16x32_bf16 v[76:79], v[156:159], v[222:225], v[76:79]
	v_mfma_f32_16x16x32_bf16 v[68:71], v[156:159], v[230:233], v[68:71]
	s_waitcnt vmcnt(12) lgkmcnt(0)
	s_barrier
	v_mfma_f32_16x16x32_bf16 v[56:59], v[160:163], v[194:197], 0
	v_mfma_f32_16x16x32_bf16 v[48:51], v[160:163], v[202:205], 0
	ds_read_b128 v[128:131], v234 offset:32768
	v_mfma_f32_16x16x32_bf16 v[40:43], v[168:171], v[194:197], 0
	ds_read_b128 v[132:135], v234 offset:33792
	v_mfma_f32_16x16x32_bf16 v[32:35], v[168:171], v[202:205], 0
	ds_read_b128 v[136:139], v234 offset:34816
	s_add_u32 m0, s40, 0x4000
	v_mfma_f32_16x16x32_bf16 v[24:27], v[176:179], v[194:197], 0
	ds_read_b128 v[140:143], v234 offset:35840
	v_mfma_f32_16x16x32_bf16 v[16:19], v[176:179], v[202:205], 0
	ds_read_b128 v[144:147], v234 offset:36864
	global_load_lds_dwordx4 v236, s[8:9]
	v_mfma_f32_16x16x32_bf16 v[8:11], v[184:187], v[194:197], 0
	ds_read_b128 v[148:151], v234 offset:37888
	v_mfma_f32_16x16x32_bf16 v[0:3], v[184:187], v[202:205], 0
	ds_read_b128 v[152:155], v234 offset:38912
	s_add_u32 m0, s40, 0x6000
	v_mfma_f32_16x16x32_bf16 v[56:59], v[164:167], v[198:201], v[56:59]
	ds_read_b128 v[156:159], v234 offset:39936
	v_mfma_f32_16x16x32_bf16 v[48:51], v[164:167], v[206:209], v[48:51]
	global_load_lds_dwordx4 v237, s[8:9]
	v_mfma_f32_16x16x32_bf16 v[40:43], v[172:175], v[198:201], v[40:43]
	v_mfma_f32_16x16x32_bf16 v[32:35], v[172:175], v[206:209], v[32:35]
	s_add_u32 s8, s8, 0x80
	s_addc_u32 s9, s9, 0
	v_mfma_f32_16x16x32_bf16 v[24:27], v[180:183], v[198:201], v[24:27]
	v_mfma_f32_16x16x32_bf16 v[16:19], v[180:183], v[206:209], v[16:19]
	v_mfma_f32_16x16x32_bf16 v[8:11], v[188:191], v[198:201], v[8:11]
	v_mfma_f32_16x16x32_bf16 v[0:3], v[188:191], v[206:209], v[0:3]
	s_waitcnt vmcnt(12) lgkmcnt(0)
	s_barrier
	v_mfma_f32_16x16x32_bf16 v[60:63], v[160:163], v[218:221], 0
	v_mfma_f32_16x16x32_bf16 v[52:55], v[160:163], v[226:229], 0
	ds_read_b128 v[194:197], v235 offset:32768
	v_mfma_f32_16x16x32_bf16 v[44:47], v[168:171], v[218:221], 0
	ds_read_b128 v[198:201], v235 offset:33792
	v_mfma_f32_16x16x32_bf16 v[36:39], v[168:171], v[226:229], 0
	ds_read_b128 v[202:205], v235 offset:34816
	s_add_u32 m0, s40, 0x8000
	v_mfma_f32_16x16x32_bf16 v[28:31], v[176:179], v[218:221], 0
	ds_read_b128 v[206:209], v235 offset:35840
	v_mfma_f32_16x16x32_bf16 v[20:23], v[176:179], v[226:229], 0
	global_load_lds_dwordx4 v236, s[36:37]
	v_mfma_f32_16x16x32_bf16 v[12:15], v[184:187], v[218:221], 0
	v_mfma_f32_16x16x32_bf16 v[4:7], v[184:187], v[226:229], 0
	s_add_u32 m0, s40, 0xa000
	v_mfma_f32_16x16x32_bf16 v[60:63], v[164:167], v[222:225], v[60:63]
	v_mfma_f32_16x16x32_bf16 v[52:55], v[164:167], v[230:233], v[52:55]
	global_load_lds_dwordx4 v237, s[36:37]
	v_mfma_f32_16x16x32_bf16 v[44:47], v[172:175], v[222:225], v[44:47]
	v_mfma_f32_16x16x32_bf16 v[36:39], v[172:175], v[230:233], v[36:39]
	s_add_u32 s36, s36, 0x80
	s_addc_u32 s37, s37, 0
	v_mfma_f32_16x16x32_bf16 v[28:31], v[180:183], v[222:225], v[28:31]
	v_mfma_f32_16x16x32_bf16 v[20:23], v[180:183], v[230:233], v[20:23]
	v_mfma_f32_16x16x32_bf16 v[12:15], v[188:191], v[222:225], v[12:15]
	v_mfma_f32_16x16x32_bf16 v[4:7], v[188:191], v[230:233], v[4:7]
	s_waitcnt vmcnt(12) lgkmcnt(0)
	s_barrier
; #define STAGE(P, BASE, br, kt) do { const u16* _gb = (BASE) + ((size_t)(br) * K + (size_t)(kt) * BK); \
;     __builtin_amdgcn_global_load_lds((const unsigned*)(_gb + goff0), (unsigned*)((char*)(P) + tid * 16), 16, 0, 0); \
;     __builtin_amdgcn_global_load_lds((const unsigned*)(_gb + (size_t)64 * K + goff0), (unsigned*)((char*)(P) + tid * 16 + 8192), 16, 0, 0); } while (0)
; #define LDA(dst, b, h) _Pragma("unroll") for (int m = 0; m < 4; ++m) _Pragma("unroll") for (int k = 0; k < 2; ++k) \
;     dst[m][k] = *reinterpret_cast<const bf16x8*>((char*)SA(b, h) + lds_byte(wr * 64 + m * 16 + fr, k * 32 + fq * 8))
; #define LDB(dst, b, h) _Pragma("unroll") for (int n = 0; n < 2; ++n) _Pragma("unroll") for (int k = 0; k < 2; ++k) \
;     dst[n][k] = *reinterpret_cast<const bf16x8*>((char*)SB(b, h) + lds_byte(wc * 32 + n * 16 + fr, k * 32 + fq * 8))
; #define MMA(ai, bj, At, Bt_) do { __builtin_amdgcn_s_setprio(1); \
;     _Pragma("unroll") for (int m = 0; m < 4; ++m) _Pragma("unroll") for (int n = 0; n < 2; ++n) _Pragma("unroll") for (int k = 0; k < 2; ++k) \
;       acc[ai][bj][m][n] = __builtin_amdgcn_mfma_f32_16x16x32_bf16(Bt_[n][k], At[m][k], acc[ai][bj][m][n], 0, 0, 0); \
;     __builtin_amdgcn_s_setprio(0); } while (0)
; #define WAIT_V(n) asm volatile("s_waitcnt vmcnt(" #n ")" ::: "memory")
; #define WAIT_L(n) asm volatile("s_waitcnt lgkmcnt(" #n ")" ::: "memory")
; #define BAR __builtin_amdgcn_s_barrier()
; #define SCHED __builtin_amdgcn_sched_barrier(0)
; __device__ __forceinline__ void gemm_phase(KP p, char* shmc, const u16* __restrict__ A,
;                                            const u16* __restrict__ Bt, const int N, const int K, const int mode,
;                                            const float* __restrict__ xin, const float resw) {
;     ...
;       LDB(B0, 1, 0); SCHED; LDA(At, 1, 0); STAGE(SA(0, 1), A, brow + HALF, t + 2);
;       WAIT_L(8); BAR; WAIT_L(0); MMA(0, 0, At, B0); BAR; SCHED;
;       LDB(B1, 1, 1); STAGE(SB(1, 0), Bt, bcol, t + 3);
;       BAR; WAIT_L(0); MMA(0, 1, At, B1); BAR;
;       LDA(At, 1, 1); STAGE(SA(1, 0), A, brow, t + 3);
;       BAR; WAIT_L(0); MMA(1, 0, At, B0); BAR; SCHED;
;       STAGE(SB(1, 1), Bt, bcol + HALF, t + 3);
;       WAIT_V(6); BAR; MMA(1, 1, At, B1); BAR;
;     }
	v_mfma_f32_16x16x32_bf16 v[120:123], v[128:131], v[194:197], v[120:123]
	v_mfma_f32_16x16x32_bf16 v[112:115], v[128:131], v[202:205], v[112:115]
	ds_read_b128 v[218:221], v235 offset:49152
	v_mfma_f32_16x16x32_bf16 v[104:107], v[136:139], v[194:197], v[104:107]
	ds_read_b128 v[222:225], v235 offset:50176
	v_mfma_f32_16x16x32_bf16 v[96:99], v[136:139], v[202:205], v[96:99]
	ds_read_b128 v[226:229], v235 offset:51200
	s_add_u32 m0, s40, 0x18000
	v_mfma_f32_16x16x32_bf16 v[88:91], v[144:147], v[194:197], v[88:91]
	ds_read_b128 v[230:233], v235 offset:52224
	v_mfma_f32_16x16x32_bf16 v[80:83], v[144:147], v[202:205], v[80:83]
	global_load_lds_dwordx4 v236, s[26:27]
	v_mfma_f32_16x16x32_bf16 v[72:75], v[152:155], v[194:197], v[72:75]
	v_mfma_f32_16x16x32_bf16 v[64:67], v[152:155], v[202:205], v[64:67]
	s_add_u32 m0, s40, 0x1a000
	v_mfma_f32_16x16x32_bf16 v[120:123], v[132:135], v[198:201], v[120:123]
	v_mfma_f32_16x16x32_bf16 v[112:115], v[132:135], v[206:209], v[112:115]
	global_load_lds_dwordx4 v237, s[26:27]
	v_mfma_f32_16x16x32_bf16 v[104:107], v[140:143], v[198:201], v[104:107]
	v_mfma_f32_16x16x32_bf16 v[96:99], v[140:143], v[206:209], v[96:99]
	s_add_u32 s26, s26, 0x80
	s_addc_u32 s27, s27, 0
	v_mfma_f32_16x16x32_bf16 v[88:91], v[148:151], v[198:201], v[88:91]
	v_mfma_f32_16x16x32_bf16 v[80:83], v[148:151], v[206:209], v[80:83]
	v_mfma_f32_16x16x32_bf16 v[72:75], v[156:159], v[198:201], v[72:75]
	v_mfma_f32_16x16x32_bf16 v[64:67], v[156:159], v[206:209], v[64:67]
	s_waitcnt vmcnt(12) lgkmcnt(0)
	s_barrier
	v_mfma_f32_16x16x32_bf16 v[124:127], v[128:131], v[218:221], v[124:127]
	v_mfma_f32_16x16x32_bf16 v[116:119], v[128:131], v[226:229], v[116:119]
	ds_read_b128 v[160:163], v234 offset:49152
	v_mfma_f32_16x16x32_bf16 v[108:111], v[136:139], v[218:221], v[108:111]
	ds_read_b128 v[164:167], v234 offset:50176
	v_mfma_f32_16x16x32_bf16 v[100:103], v[136:139], v[226:229], v[100:103]
	ds_read_b128 v[168:171], v234 offset:51200
	s_add_u32 m0, s40, 0x1c000
	v_mfma_f32_16x16x32_bf16 v[92:95], v[144:147], v[218:221], v[92:95]
	ds_read_b128 v[172:175], v234 offset:52224
	v_mfma_f32_16x16x32_bf16 v[84:87], v[144:147], v[226:229], v[84:87]
	ds_read_b128 v[176:179], v234 offset:53248
	global_load_lds_dwordx4 v236, s[38:39]
	v_mfma_f32_16x16x32_bf16 v[76:79], v[152:155], v[218:221], v[76:79]
	ds_read_b128 v[180:183], v234 offset:54272
	v_mfma_f32_16x16x32_bf16 v[68:71], v[152:155], v[226:229], v[68:71]
	ds_read_b128 v[184:187], v234 offset:55296
	s_add_u32 m0, s40, 0x1e000
	v_mfma_f32_16x16x32_bf16 v[124:127], v[132:135], v[222:225], v[124:127]
	ds_read_b128 v[188:191], v234 offset:56320
	v_mfma_f32_16x16x32_bf16 v[116:119], v[132:135], v[230:233], v[116:119]
	global_load_lds_dwordx4 v237, s[38:39]
	v_mfma_f32_16x16x32_bf16 v[108:111], v[140:143], v[222:225], v[108:111]
	v_mfma_f32_16x16x32_bf16 v[100:103], v[140:143], v[230:233], v[100:103]
	s_add_u32 s38, s38, 0x80
	s_addc_u32 s39, s39, 0
	v_mfma_f32_16x16x32_bf16 v[92:95], v[148:151], v[222:225], v[92:95]
	v_mfma_f32_16x16x32_bf16 v[84:87], v[148:151], v[230:233], v[84:87]
	v_mfma_f32_16x16x32_bf16 v[76:79], v[156:159], v[222:225], v[76:79]
	v_mfma_f32_16x16x32_bf16 v[68:71], v[156:159], v[230:233], v[68:71]
	s_waitcnt vmcnt(12) lgkmcnt(0)
	s_barrier
	v_mfma_f32_16x16x32_bf16 v[56:59], v[160:163], v[194:197], v[56:59]
	v_mfma_f32_16x16x32_bf16 v[48:51], v[160:163], v[202:205], v[48:51]
	ds_read_b128 v[128:131], v234 offset:0
	v_mfma_f32_16x16x32_bf16 v[40:43], v[168:171], v[194:197], v[40:43]
	ds_read_b128 v[132:135], v234 offset:1024
	v_mfma_f32_16x16x32_bf16 v[32:35], v[168:171], v[202:205], v[32:35]
	ds_read_b128 v[136:139], v234 offset:2048
	s_add_u32 m0, s40, 0xc000
	v_mfma_f32_16x16x32_bf16 v[24:27], v[176:179], v[194:197], v[24:27]
	ds_read_b128 v[140:143], v234 offset:3072
	v_mfma_f32_16x16x32_bf16 v[16:19], v[176:179], v[202:205], v[16:19]
	ds_read_b128 v[144:147], v234 offset:4096
	global_load_lds_dwordx4 v236, s[8:9]
	v_mfma_f32_16x16x32_bf16 v[8:11], v[184:187], v[194:197], v[8:11]
	ds_read_b128 v[148:151], v234 offset:5120
	v_mfma_f32_16x16x32_bf16 v[0:3], v[184:187], v[202:205], v[0:3]
	ds_read_b128 v[152:155], v234 offset:6144
	s_add_u32 m0, s40, 0xe000
	v_mfma_f32_16x16x32_bf16 v[56:59], v[164:167], v[198:201], v[56:59]
	ds_read_b128 v[156:159], v234 offset:7168
	v_mfma_f32_16x16x32_bf16 v[48:51], v[164:167], v[206:209], v[48:51]
	global_load_lds_dwordx4 v237, s[8:9]
	v_mfma_f32_16x16x32_bf16 v[40:43], v[172:175], v[198:201], v[40:43]
	v_mfma_f32_16x16x32_bf16 v[32:35], v[172:175], v[206:209], v[32:35]
	s_add_u32 s8, s8, 0x80
	s_addc_u32 s9, s9, 0
	v_mfma_f32_16x16x32_bf16 v[24:27], v[180:183], v[198:201], v[24:27]
	v_mfma_f32_16x16x32_bf16 v[16:19], v[180:183], v[206:209], v[16:19]
	v_mfma_f32_16x16x32_bf16 v[8:11], v[188:191], v[198:201], v[8:11]
	v_mfma_f32_16x16x32_bf16 v[0:3], v[188:191], v[206:209], v[0:3]
	s_waitcnt vmcnt(12) lgkmcnt(0)
	s_barrier
	v_mfma_f32_16x16x32_bf16 v[60:63], v[160:163], v[218:221], v[60:63]
	v_mfma_f32_16x16x32_bf16 v[52:55], v[160:163], v[226:229], v[52:55]
	ds_read_b128 v[194:197], v235 offset:0
	v_mfma_f32_16x16x32_bf16 v[44:47], v[168:171], v[218:221], v[44:47]
	ds_read_b128 v[198:201], v235 offset:1024
	v_mfma_f32_16x16x32_bf16 v[36:39], v[168:171], v[226:229], v[36:39]
	ds_read_b128 v[202:205], v235 offset:2048
	s_add_u32 m0, s40, 0x0
	v_mfma_f32_16x16x32_bf16 v[28:31], v[176:179], v[218:221], v[28:31]
	ds_read_b128 v[206:209], v235 offset:3072
	v_mfma_f32_16x16x32_bf16 v[20:23], v[176:179], v[226:229], v[20:23]
	global_load_lds_dwordx4 v236, s[36:37]
	v_mfma_f32_16x16x32_bf16 v[12:15], v[184:187], v[218:221], v[12:15]
	v_mfma_f32_16x16x32_bf16 v[4:7], v[184:187], v[226:229], v[4:7]
	s_add_u32 m0, s40, 0x2000
	v_mfma_f32_16x16x32_bf16 v[60:63], v[164:167], v[222:225], v[60:63]
	v_mfma_f32_16x16x32_bf16 v[52:55], v[164:167], v[230:233], v[52:55]
	global_load_lds_dwordx4 v237, s[36:37]
	v_mfma_f32_16x16x32_bf16 v[44:47], v[172:175], v[222:225], v[44:47]
	v_mfma_f32_16x16x32_bf16 v[36:39], v[172:175], v[230:233], v[36:39]
	s_add_u32 s36, s36, 0x80
	s_addc_u32 s37, s37, 0
	v_mfma_f32_16x16x32_bf16 v[28:31], v[180:183], v[222:225], v[28:31]
	v_mfma_f32_16x16x32_bf16 v[20:23], v[180:183], v[230:233], v[20:23]
	v_mfma_f32_16x16x32_bf16 v[12:15], v[188:191], v[222:225], v[12:15]
	v_mfma_f32_16x16x32_bf16 v[4:7], v[188:191], v[230:233], v[4:7]
	s_add_i32 s41, s41, -1
; #define STAGE(P, BASE, br, kt) do { const u16* _gb = (BASE) + ((size_t)(br) * K + (size_t)(kt) * BK); \
;     __builtin_amdgcn_global_load_lds((const unsigned*)(_gb + goff0), (unsigned*)((char*)(P) + tid * 16), 16, 0, 0); \
;     __builtin_amdgcn_global_load_lds((const unsigned*)(_gb + (size_t)64 * K + goff0), (unsigned*)((char*)(P) + tid * 16 + 8192), 16, 0, 0); } while (0)
; #define LDA(dst, b, h) _Pragma("unroll") for (int m = 0; m < 4; ++m) _Pragma("unroll") for (int k = 0; k < 2; ++k) \
;     dst[m][k] = *reinterpret_cast<const bf16x8*>((char*)SA(b, h) + lds_byte(wr * 64 + m * 16 + fr, k * 32 + fq * 8))
; #define LDB(dst, b, h) _Pragma("unroll") for (int n = 0; n < 2; ++n) _Pragma("unroll") for (int k = 0; k < 2; ++k) \
;     dst[n][k] = *reinterpret_cast<const bf16x8*>((char*)SB(b, h) + lds_byte(wc * 32 + n * 16 + fr, k * 32 + fq * 8))
; #define WAIT_V(n) asm volatile("s_waitcnt vmcnt(" #n ")" ::: "memory")
; #define WAIT_L(n) asm volatile("s_waitcnt lgkmcnt(" #n ")" ::: "memory")
; #define BAR __builtin_amdgcn_s_barrier()
; #define SCHED __builtin_amdgcn_sched_barrier(0)
; __device__ __forceinline__ void gemm_phase(KP p, char* shmc, const u16* __restrict__ A,
;                                            const u16* __restrict__ Bt, const int N, const int K, const int mode,
;                                            const float* __restrict__ xin, const float resw) {
;     ...
;     for (int t = 0; t < nt - 2; t += 2) {
;       LDB(B0, 0, 0); SCHED; LDA(At, 0, 0); STAGE(SA(1, 1), A, brow + HALF, t + 1);
;       WAIT_L(8); BAR; WAIT_L(0); MMA(0, 0, At, B0); BAR; SCHED;
;       LDB(B1, 0, 1); STAGE(SB(0, 0), Bt, bcol, t + 2);
;       BAR; WAIT_L(0); MMA(0, 1, At, B1); BAR;
;       LDA(At, 0, 1); STAGE(SA(0, 0), A, brow, t + 2);
;       BAR; WAIT_L(0); MMA(1, 0, At, B0); BAR; SCHED;
;       STAGE(SB(0, 1), Bt, bcol + HALF, t + 2);
;       WAIT_V(6); BAR; MMA(1, 1, At, B1); BAR;
;       LDB(B0, 1, 0); SCHED; LDA(At, 1, 0); STAGE(SA(0, 1), A, brow + HALF, t + 2);
;       WAIT_L(8); BAR; WAIT_L(0); MMA(0, 0, At, B0); BAR; SCHED;
;       LDB(B1, 1, 1); STAGE(SB(1, 0), Bt, bcol, t + 3);
;       BAR; WAIT_L(0); MMA(0, 1, At, B1); BAR;
;       LDA(At, 1, 1); STAGE(SA(1, 0), A, brow, t + 3);
;       BAR; WAIT_L(0); MMA(1, 0, At, B0); BAR; SCHED;
;       STAGE(SB(1, 1), Bt, bcol + HALF, t + 3);
;       WAIT_V(6); BAR; MMA(1, 1, At, B1); BAR;
;     }
.Lmy_kloop_sw:
	s_waitcnt vmcnt(12) lgkmcnt(0)
	s_barrier
	v_mfma_f32_16x16x32_bf16 v[120:123], v[128:131], v[194:197], v[120:123]
	v_mfma_f32_16x16x32_bf16 v[112:115], v[128:131], v[202:205], v[112:115]
	ds_read_b128 v[218:221], v235 offset:16384
	v_mfma_f32_16x16x32_bf16 v[104:107], v[136:139], v[194:197], v[104:107]
	ds_read_b128 v[222:225], v235 offset:17408
	v_mfma_f32_16x16x32_bf16 v[96:99], v[136:139], v[202:205], v[96:99]
	ds_read_b128 v[226:229], v235 offset:18432
	s_add_u32 m0, s40, 0x10000
	v_mfma_f32_16x16x32_bf16 v[88:91], v[144:147], v[194:197], v[88:91]
	ds_read_b128 v[230:233], v235 offset:19456
	v_mfma_f32_16x16x32_bf16 v[80:83], v[144:147], v[202:205], v[80:83]
	global_load_lds_dwordx4 v236, s[26:27]
	v_mfma_f32_16x16x32_bf16 v[72:75], v[152:155], v[194:197], v[72:75]
	v_mfma_f32_16x16x32_bf16 v[64:67], v[152:155], v[202:205], v[64:67]
	s_add_u32 m0, s40, 0x12000
	v_mfma_f32_16x16x32_bf16 v[120:123], v[132:135], v[198:201], v[120:123]
	v_mfma_f32_16x16x32_bf16 v[112:115], v[132:135], v[206:209], v[112:115]
	global_load_lds_dwordx4 v237, s[26:27]
	v_mfma_f32_16x16x32_bf16 v[104:107], v[140:143], v[198:201], v[104:107]
	v_mfma_f32_16x16x32_bf16 v[96:99], v[140:143], v[206:209], v[96:99]
	s_add_u32 s26, s26, 0x80
	s_addc_u32 s27, s27, 0
	v_mfma_f32_16x16x32_bf16 v[88:91], v[148:151], v[198:201], v[88:91]
	v_mfma_f32_16x16x32_bf16 v[80:83], v[148:151], v[206:209], v[80:83]
	v_mfma_f32_16x16x32_bf16 v[72:75], v[156:159], v[198:201], v[72:75]
	v_mfma_f32_16x16x32_bf16 v[64:67], v[156:159], v[206:209], v[64:67]
	s_waitcnt vmcnt(12) lgkmcnt(0)
	s_barrier
	v_mfma_f32_16x16x32_bf16 v[124:127], v[128:131], v[218:221], v[124:127]
	v_mfma_f32_16x16x32_bf16 v[116:119], v[128:131], v[226:229], v[116:119]
	ds_read_b128 v[160:163], v234 offset:16384
	v_mfma_f32_16x16x32_bf16 v[108:111], v[136:139], v[218:221], v[108:111]
	ds_read_b128 v[164:167], v234 offset:17408
	v_mfma_f32_16x16x32_bf16 v[100:103], v[136:139], v[226:229], v[100:103]
	ds_read_b128 v[168:171], v234 offset:18432
	s_add_u32 m0, s40, 0x14000
	v_mfma_f32_16x16x32_bf16 v[92:95], v[144:147], v[218:221], v[92:95]
	ds_read_b128 v[172:175], v234 offset:19456
	v_mfma_f32_16x16x32_bf16 v[84:87], v[144:147], v[226:229], v[84:87]
	ds_read_b128 v[176:179], v234 offset:20480
	global_load_lds_dwordx4 v236, s[38:39]
	v_mfma_f32_16x16x32_bf16 v[76:79], v[152:155], v[218:221], v[76:79]
	ds_read_b128 v[180:183], v234 offset:21504
	v_mfma_f32_16x16x32_bf16 v[68:71], v[152:155], v[226:229], v[68:71]
	ds_read_b128 v[184:187], v234 offset:22528
	s_add_u32 m0, s40, 0x16000
	v_mfma_f32_16x16x32_bf16 v[124:127], v[132:135], v[222:225], v[124:127]
	ds_read_b128 v[188:191], v234 offset:23552
	v_mfma_f32_16x16x32_bf16 v[116:119], v[132:135], v[230:233], v[116:119]
	global_load_lds_dwordx4 v237, s[38:39]
	v_mfma_f32_16x16x32_bf16 v[108:111], v[140:143], v[222:225], v[108:111]
	v_mfma_f32_16x16x32_bf16 v[100:103], v[140:143], v[230:233], v[100:103]
	s_add_u32 s38, s38, 0x80
	s_addc_u32 s39, s39, 0
	v_mfma_f32_16x16x32_bf16 v[92:95], v[148:151], v[222:225], v[92:95]
	v_mfma_f32_16x16x32_bf16 v[84:87], v[148:151], v[230:233], v[84:87]
	v_mfma_f32_16x16x32_bf16 v[76:79], v[156:159], v[222:225], v[76:79]
	v_mfma_f32_16x16x32_bf16 v[68:71], v[156:159], v[230:233], v[68:71]
	s_waitcnt vmcnt(12) lgkmcnt(0)
	s_barrier
	v_mfma_f32_16x16x32_bf16 v[56:59], v[160:163], v[194:197], v[56:59]
	v_mfma_f32_16x16x32_bf16 v[48:51], v[160:163], v[202:205], v[48:51]
	ds_read_b128 v[128:131], v234 offset:32768
	v_mfma_f32_16x16x32_bf16 v[40:43], v[168:171], v[194:197], v[40:43]
	ds_read_b128 v[132:135], v234 offset:33792
	v_mfma_f32_16x16x32_bf16 v[32:35], v[168:171], v[202:205], v[32:35]
	ds_read_b128 v[136:139], v234 offset:34816
	s_add_u32 m0, s40, 0x4000
	v_mfma_f32_16x16x32_bf16 v[24:27], v[176:179], v[194:197], v[24:27]
	ds_read_b128 v[140:143], v234 offset:35840
	v_mfma_f32_16x16x32_bf16 v[16:19], v[176:179], v[202:205], v[16:19]
	ds_read_b128 v[144:147], v234 offset:36864
	global_load_lds_dwordx4 v236, s[8:9]
	v_mfma_f32_16x16x32_bf16 v[8:11], v[184:187], v[194:197], v[8:11]
	ds_read_b128 v[148:151], v234 offset:37888
	v_mfma_f32_16x16x32_bf16 v[0:3], v[184:187], v[202:205], v[0:3]
	ds_read_b128 v[152:155], v234 offset:38912
	s_add_u32 m0, s40, 0x6000
	v_mfma_f32_16x16x32_bf16 v[56:59], v[164:167], v[198:201], v[56:59]
	ds_read_b128 v[156:159], v234 offset:39936
	v_mfma_f32_16x16x32_bf16 v[48:51], v[164:167], v[206:209], v[48:51]
	global_load_lds_dwordx4 v237, s[8:9]
	v_mfma_f32_16x16x32_bf16 v[40:43], v[172:175], v[198:201], v[40:43]
	v_mfma_f32_16x16x32_bf16 v[32:35], v[172:175], v[206:209], v[32:35]
	s_add_u32 s8, s8, 0x80
	s_addc_u32 s9, s9, 0
	v_mfma_f32_16x16x32_bf16 v[24:27], v[180:183], v[198:201], v[24:27]
	v_mfma_f32_16x16x32_bf16 v[16:19], v[180:183], v[206:209], v[16:19]
	v_mfma_f32_16x16x32_bf16 v[8:11], v[188:191], v[198:201], v[8:11]
	v_mfma_f32_16x16x32_bf16 v[0:3], v[188:191], v[206:209], v[0:3]
	s_waitcnt vmcnt(12) lgkmcnt(0)
	s_barrier
; #define STAGE(P, BASE, br, kt) do { const u16* _gb = (BASE) + ((size_t)(br) * K + (size_t)(kt) * BK); \
;     __builtin_amdgcn_global_load_lds((const unsigned*)(_gb + goff0), (unsigned*)((char*)(P) + tid * 16), 16, 0, 0); \
;     __builtin_amdgcn_global_load_lds((const unsigned*)(_gb + (size_t)64 * K + goff0), (unsigned*)((char*)(P) + tid * 16 + 8192), 16, 0, 0); } while (0)
; #define LDA(dst, b, h) _Pragma("unroll") for (int m = 0; m < 4; ++m) _Pragma("unroll") for (int k = 0; k < 2; ++k) \
;     dst[m][k] = *reinterpret_cast<const bf16x8*>((char*)SA(b, h) + lds_byte(wr * 64 + m * 16 + fr, k * 32 + fq * 8))
; #define LDB(dst, b, h) _Pragma("unroll") for (int n = 0; n < 2; ++n) _Pragma("unroll") for (int k = 0; k < 2; ++k) \
;     dst[n][k] = *reinterpret_cast<const bf16x8*>((char*)SB(b, h) + lds_byte(wc * 32 + n * 16 + fr, k * 32 + fq * 8))
; #define WAIT_V(n) asm volatile("s_waitcnt vmcnt(" #n ")" ::: "memory")
; #define WAIT_L(n) asm volatile("s_waitcnt lgkmcnt(" #n ")" ::: "memory")
; #define BAR __builtin_amdgcn_s_barrier()
; #define SCHED __builtin_amdgcn_sched_barrier(0)
; __device__ __forceinline__ void gemm_phase(KP p, char* shmc, const u16* __restrict__ A,
;                                            const u16* __restrict__ Bt, const int N, const int K, const int mode,
;                                            const float* __restrict__ xin, const float resw) {
;     ...
;     for (int t = 0; t < nt - 2; t += 2) {
;       LDB(B0, 0, 0); SCHED; LDA(At, 0, 0); STAGE(SA(1, 1), A, brow + HALF, t + 1);
;       WAIT_L(8); BAR; WAIT_L(0); MMA(0, 0, At, B0); BAR; SCHED;
;       LDB(B1, 0, 1); STAGE(SB(0, 0), Bt, bcol, t + 2);
;       BAR; WAIT_L(0); MMA(0, 1, At, B1); BAR;
;       LDA(At, 0, 1); STAGE(SA(0, 0), A, brow, t + 2);
;       BAR; WAIT_L(0); MMA(1, 0, At, B0); BAR; SCHED;
;       STAGE(SB(0, 1), Bt, bcol + HALF, t + 2);
;       WAIT_V(6); BAR; MMA(1, 1, At, B1); BAR;
;       LDB(B0, 1, 0); SCHED; LDA(At, 1, 0); STAGE(SA(0, 1), A, brow + HALF, t + 2);
;       WAIT_L(8); BAR; WAIT_L(0); MMA(0, 0, At, B0); BAR; SCHED;
;       LDB(B1, 1, 1); STAGE(SB(1, 0), Bt, bcol, t + 3);
;       BAR; WAIT_L(0); MMA(0, 1, At, B1); BAR;
;       LDA(At, 1, 1); STAGE(SA(1, 0), A, brow, t + 3);
;       BAR; WAIT_L(0); MMA(1, 0, At, B0); BAR; SCHED;
;       STAGE(SB(1, 1), Bt, bcol + HALF, t + 3);
;       WAIT_V(6); BAR; MMA(1, 1, At, B1); BAR;
;     }
	v_mfma_f32_16x16x32_bf16 v[60:63], v[160:163], v[218:221], v[60:63]
	v_mfma_f32_16x16x32_bf16 v[52:55], v[160:163], v[226:229], v[52:55]
	ds_read_b128 v[194:197], v235 offset:32768
	v_mfma_f32_16x16x32_bf16 v[44:47], v[168:171], v[218:221], v[44:47]
	ds_read_b128 v[198:201], v235 offset:33792
	v_mfma_f32_16x16x32_bf16 v[36:39], v[168:171], v[226:229], v[36:39]
	ds_read_b128 v[202:205], v235 offset:34816
	s_add_u32 m0, s40, 0x8000
	v_mfma_f32_16x16x32_bf16 v[28:31], v[176:179], v[218:221], v[28:31]
	ds_read_b128 v[206:209], v235 offset:35840
	v_mfma_f32_16x16x32_bf16 v[20:23], v[176:179], v[226:229], v[20:23]
	global_load_lds_dwordx4 v236, s[36:37]
	v_mfma_f32_16x16x32_bf16 v[12:15], v[184:187], v[218:221], v[12:15]
	v_mfma_f32_16x16x32_bf16 v[4:7], v[184:187], v[226:229], v[4:7]
	s_add_u32 m0, s40, 0xa000
	v_mfma_f32_16x16x32_bf16 v[60:63], v[164:167], v[222:225], v[60:63]
	v_mfma_f32_16x16x32_bf16 v[52:55], v[164:167], v[230:233], v[52:55]
	global_load_lds_dwordx4 v237, s[36:37]
	v_mfma_f32_16x16x32_bf16 v[44:47], v[172:175], v[222:225], v[44:47]
	v_mfma_f32_16x16x32_bf16 v[36:39], v[172:175], v[230:233], v[36:39]
	s_add_u32 s36, s36, 0x80
	s_addc_u32 s37, s37, 0
	v_mfma_f32_16x16x32_bf16 v[28:31], v[180:183], v[222:225], v[28:31]
	v_mfma_f32_16x16x32_bf16 v[20:23], v[180:183], v[230:233], v[20:23]
	v_mfma_f32_16x16x32_bf16 v[12:15], v[188:191], v[222:225], v[12:15]
	v_mfma_f32_16x16x32_bf16 v[4:7], v[188:191], v[230:233], v[4:7]
	s_waitcnt vmcnt(12) lgkmcnt(0)
	s_barrier
	v_mfma_f32_16x16x32_bf16 v[120:123], v[128:131], v[194:197], v[120:123]
	v_mfma_f32_16x16x32_bf16 v[112:115], v[128:131], v[202:205], v[112:115]
	ds_read_b128 v[218:221], v235 offset:49152
	v_mfma_f32_16x16x32_bf16 v[104:107], v[136:139], v[194:197], v[104:107]
	ds_read_b128 v[222:225], v235 offset:50176
	v_mfma_f32_16x16x32_bf16 v[96:99], v[136:139], v[202:205], v[96:99]
	ds_read_b128 v[226:229], v235 offset:51200
	s_add_u32 m0, s40, 0x18000
	v_mfma_f32_16x16x32_bf16 v[88:91], v[144:147], v[194:197], v[88:91]
	ds_read_b128 v[230:233], v235 offset:52224
	v_mfma_f32_16x16x32_bf16 v[80:83], v[144:147], v[202:205], v[80:83]
	global_load_lds_dwordx4 v236, s[26:27]
	v_mfma_f32_16x16x32_bf16 v[72:75], v[152:155], v[194:197], v[72:75]
	v_mfma_f32_16x16x32_bf16 v[64:67], v[152:155], v[202:205], v[64:67]
	s_add_u32 m0, s40, 0x1a000
	v_mfma_f32_16x16x32_bf16 v[120:123], v[132:135], v[198:201], v[120:123]
	v_mfma_f32_16x16x32_bf16 v[112:115], v[132:135], v[206:209], v[112:115]
	global_load_lds_dwordx4 v237, s[26:27]
	v_mfma_f32_16x16x32_bf16 v[104:107], v[140:143], v[198:201], v[104:107]
	v_mfma_f32_16x16x32_bf16 v[96:99], v[140:143], v[206:209], v[96:99]
	s_add_u32 s26, s26, 0x80
	s_addc_u32 s27, s27, 0
	v_mfma_f32_16x16x32_bf16 v[88:91], v[148:151], v[198:201], v[88:91]
	v_mfma_f32_16x16x32_bf16 v[80:83], v[148:151], v[206:209], v[80:83]
	v_mfma_f32_16x16x32_bf16 v[72:75], v[156:159], v[198:201], v[72:75]
	v_mfma_f32_16x16x32_bf16 v[64:67], v[156:159], v[206:209], v[64:67]
	s_waitcnt vmcnt(12) lgkmcnt(0)
	s_barrier
	v_mfma_f32_16x16x32_bf16 v[124:127], v[128:131], v[218:221], v[124:127]
	v_mfma_f32_16x16x32_bf16 v[116:119], v[128:131], v[226:229], v[116:119]
	ds_read_b128 v[160:163], v234 offset:49152
	v_mfma_f32_16x16x32_bf16 v[108:111], v[136:139], v[218:221], v[108:111]
	ds_read_b128 v[164:167], v234 offset:50176
	v_mfma_f32_16x16x32_bf16 v[100:103], v[136:139], v[226:229], v[100:103]
	ds_read_b128 v[168:171], v234 offset:51200
	s_add_u32 m0, s40, 0x1c000
	v_mfma_f32_16x16x32_bf16 v[92:95], v[144:147], v[218:221], v[92:95]
	ds_read_b128 v[172:175], v234 offset:52224
	v_mfma_f32_16x16x32_bf16 v[84:87], v[144:147], v[226:229], v[84:87]
	ds_read_b128 v[176:179], v234 offset:53248
	global_load_lds_dwordx4 v236, s[38:39]
	v_mfma_f32_16x16x32_bf16 v[76:79], v[152:155], v[218:221], v[76:79]
	ds_read_b128 v[180:183], v234 offset:54272
	v_mfma_f32_16x16x32_bf16 v[68:71], v[152:155], v[226:229], v[68:71]
	ds_read_b128 v[184:187], v234 offset:55296
	s_add_u32 m0, s40, 0x1e000
	v_mfma_f32_16x16x32_bf16 v[124:127], v[132:135], v[222:225], v[124:127]
	ds_read_b128 v[188:191], v234 offset:56320
	v_mfma_f32_16x16x32_bf16 v[116:119], v[132:135], v[230:233], v[116:119]
	global_load_lds_dwordx4 v237, s[38:39]
	v_mfma_f32_16x16x32_bf16 v[108:111], v[140:143], v[222:225], v[108:111]
	v_mfma_f32_16x16x32_bf16 v[100:103], v[140:143], v[230:233], v[100:103]
	s_add_u32 s38, s38, 0x80
	s_addc_u32 s39, s39, 0
	v_mfma_f32_16x16x32_bf16 v[92:95], v[148:151], v[222:225], v[92:95]
	v_mfma_f32_16x16x32_bf16 v[84:87], v[148:151], v[230:233], v[84:87]
	v_mfma_f32_16x16x32_bf16 v[76:79], v[156:159], v[222:225], v[76:79]
	v_mfma_f32_16x16x32_bf16 v[68:71], v[156:159], v[230:233], v[68:71]
	s_waitcnt vmcnt(12) lgkmcnt(0)
	s_barrier
	v_mfma_f32_16x16x32_bf16 v[56:59], v[160:163], v[194:197], v[56:59]
	v_mfma_f32_16x16x32_bf16 v[48:51], v[160:163], v[202:205], v[48:51]
	ds_read_b128 v[128:131], v234 offset:0
	v_mfma_f32_16x16x32_bf16 v[40:43], v[168:171], v[194:197], v[40:43]
	ds_read_b128 v[132:135], v234 offset:1024
	v_mfma_f32_16x16x32_bf16 v[32:35], v[168:171], v[202:205], v[32:35]
	ds_read_b128 v[136:139], v234 offset:2048
	s_add_u32 m0, s40, 0xc000
	v_mfma_f32_16x16x32_bf16 v[24:27], v[176:179], v[194:197], v[24:27]
	ds_read_b128 v[140:143], v234 offset:3072
	v_mfma_f32_16x16x32_bf16 v[16:19], v[176:179], v[202:205], v[16:19]
	ds_read_b128 v[144:147], v234 offset:4096
	global_load_lds_dwordx4 v236, s[8:9]
	v_mfma_f32_16x16x32_bf16 v[8:11], v[184:187], v[194:197], v[8:11]
	ds_read_b128 v[148:151], v234 offset:5120
	v_mfma_f32_16x16x32_bf16 v[0:3], v[184:187], v[202:205], v[0:3]
	ds_read_b128 v[152:155], v234 offset:6144
	s_add_u32 m0, s40, 0xe000
	v_mfma_f32_16x16x32_bf16 v[56:59], v[164:167], v[198:201], v[56:59]
	ds_read_b128 v[156:159], v234 offset:7168
	v_mfma_f32_16x16x32_bf16 v[48:51], v[164:167], v[206:209], v[48:51]
	global_load_lds_dwordx4 v237, s[8:9]
	v_mfma_f32_16x16x32_bf16 v[40:43], v[172:175], v[198:201], v[40:43]
	v_mfma_f32_16x16x32_bf16 v[32:35], v[172:175], v[206:209], v[32:35]
	s_add_u32 s8, s8, 0x80
	s_addc_u32 s9, s9, 0
	v_mfma_f32_16x16x32_bf16 v[24:27], v[180:183], v[198:201], v[24:27]
	v_mfma_f32_16x16x32_bf16 v[16:19], v[180:183], v[206:209], v[16:19]
	v_mfma_f32_16x16x32_bf16 v[8:11], v[188:191], v[198:201], v[8:11]
	v_mfma_f32_16x16x32_bf16 v[0:3], v[188:191], v[206:209], v[0:3]
	s_waitcnt vmcnt(12) lgkmcnt(0)
	s_barrier
; #define STAGE(P, BASE, br, kt) do { const u16* _gb = (BASE) + ((size_t)(br) * K + (size_t)(kt) * BK); \
;     __builtin_amdgcn_global_load_lds((const unsigned*)(_gb + goff0), (unsigned*)((char*)(P) + tid * 16), 16, 0, 0); \
;     __builtin_amdgcn_global_load_lds((const unsigned*)(_gb + (size_t)64 * K + goff0), (unsigned*)((char*)(P) + tid * 16 + 8192), 16, 0, 0); } while (0)
; #define LDA(dst, b, h) _Pragma("unroll") for (int m = 0; m < 4; ++m) _Pragma("unroll") for (int k = 0; k < 2; ++k) \
;     dst[m][k] = *reinterpret_cast<const bf16x8*>((char*)SA(b, h) + lds_byte(wr * 64 + m * 16 + fr, k * 32 + fq * 8))
; #define LDB(dst, b, h) _Pragma("unroll") for (int n = 0; n < 2; ++n) _Pragma("unroll") for (int k = 0; k < 2; ++k) \
;     dst[n][k] = *reinterpret_cast<const bf16x8*>((char*)SB(b, h) + lds_byte(wc * 32 + n * 16 + fr, k * 32 + fq * 8))
; #define WAIT_V(n) asm volatile("s_waitcnt vmcnt(" #n ")" ::: "memory")
; #define WAIT_L(n) asm volatile("s_waitcnt lgkmcnt(" #n ")" ::: "memory")
; #define BAR __builtin_amdgcn_s_barrier()
; #define SCHED __builtin_amdgcn_sched_barrier(0)
; __device__ __forceinline__ void gemm_phase(KP p, char* shmc, const u16* __restrict__ A,
;                                            const u16* __restrict__ Bt, const int N, const int K, const int mode,
;                                            const float* __restrict__ xin, const float resw) {
;     ...
;     for (int t = 0; t < nt - 2; t += 2) {
;       LDB(B0, 0, 0); SCHED; LDA(At, 0, 0); STAGE(SA(1, 1), A, brow + HALF, t + 1);
;       WAIT_L(8); BAR; WAIT_L(0); MMA(0, 0, At, B0); BAR; SCHED;
;       LDB(B1, 0, 1); STAGE(SB(0, 0), Bt, bcol, t + 2);
;       BAR; WAIT_L(0); MMA(0, 1, At, B1); BAR;
;       LDA(At, 0, 1); STAGE(SA(0, 0), A, brow, t + 2);
;       BAR; WAIT_L(0); MMA(1, 0, At, B0); BAR; SCHED;
;       STAGE(SB(0, 1), Bt, bcol + HALF, t + 2);
;       WAIT_V(6); BAR; MMA(1, 1, At, B1); BAR;
;       LDB(B0, 1, 0); SCHED; LDA(At, 1, 0); STAGE(SA(0, 1), A, brow + HALF, t + 2);
;       WAIT_L(8); BAR; WAIT_L(0); MMA(0, 0, At, B0); BAR; SCHED;
;       LDB(B1, 1, 1); STAGE(SB(1, 0), Bt, bcol, t + 3);
;       BAR; WAIT_L(0); MMA(0, 1, At, B1); BAR;
;       LDA(At, 1, 1); STAGE(SA(1, 0), A, brow, t + 3);
;       BAR; WAIT_L(0); MMA(1, 0, At, B0); BAR; SCHED;
;       STAGE(SB(1, 1), Bt, bcol + HALF, t + 3);
;       WAIT_V(6); BAR; MMA(1, 1, At, B1); BAR;
;     }
	v_mfma_f32_16x16x32_bf16 v[60:63], v[160:163], v[218:221], v[60:63]
	v_mfma_f32_16x16x32_bf16 v[52:55], v[160:163], v[226:229], v[52:55]
	ds_read_b128 v[194:197], v235 offset:0
	v_mfma_f32_16x16x32_bf16 v[44:47], v[168:171], v[218:221], v[44:47]
	ds_read_b128 v[198:201], v235 offset:1024
	v_mfma_f32_16x16x32_bf16 v[36:39], v[168:171], v[226:229], v[36:39]
	ds_read_b128 v[202:205], v235 offset:2048
	s_add_u32 m0, s40, 0x0
	v_mfma_f32_16x16x32_bf16 v[28:31], v[176:179], v[218:221], v[28:31]
	ds_read_b128 v[206:209], v235 offset:3072
	v_mfma_f32_16x16x32_bf16 v[20:23], v[176:179], v[226:229], v[20:23]
	global_load_lds_dwordx4 v236, s[36:37]
	v_mfma_f32_16x16x32_bf16 v[12:15], v[184:187], v[218:221], v[12:15]
	v_mfma_f32_16x16x32_bf16 v[4:7], v[184:187], v[226:229], v[4:7]
	s_add_u32 m0, s40, 0x2000
	v_mfma_f32_16x16x32_bf16 v[60:63], v[164:167], v[222:225], v[60:63]
	v_mfma_f32_16x16x32_bf16 v[52:55], v[164:167], v[230:233], v[52:55]
	global_load_lds_dwordx4 v237, s[36:37]
	v_mfma_f32_16x16x32_bf16 v[44:47], v[172:175], v[222:225], v[44:47]
	v_mfma_f32_16x16x32_bf16 v[36:39], v[172:175], v[230:233], v[36:39]
	s_add_u32 s36, s36, 0x80
	s_addc_u32 s37, s37, 0
	v_mfma_f32_16x16x32_bf16 v[28:31], v[180:183], v[222:225], v[28:31]
	v_mfma_f32_16x16x32_bf16 v[20:23], v[180:183], v[230:233], v[20:23]
	v_mfma_f32_16x16x32_bf16 v[12:15], v[188:191], v[222:225], v[12:15]
	v_mfma_f32_16x16x32_bf16 v[4:7], v[188:191], v[230:233], v[4:7]
	s_add_i32 s41, s41, -1
	s_cmp_lg_u32 s41, 0
	s_cbranch_scc1 .Lmy_kloop_sw
	s_waitcnt vmcnt(12) lgkmcnt(0)
	s_barrier
	v_mfma_f32_16x16x32_bf16 v[120:123], v[128:131], v[194:197], v[120:123]
	v_mfma_f32_16x16x32_bf16 v[112:115], v[128:131], v[202:205], v[112:115]
	ds_read_b128 v[218:221], v235 offset:16384
	v_mfma_f32_16x16x32_bf16 v[104:107], v[136:139], v[194:197], v[104:107]
	ds_read_b128 v[222:225], v235 offset:17408
	v_mfma_f32_16x16x32_bf16 v[96:99], v[136:139], v[202:205], v[96:99]
	ds_read_b128 v[226:229], v235 offset:18432
	s_add_u32 m0, s40, 0x10000
	v_mfma_f32_16x16x32_bf16 v[88:91], v[144:147], v[194:197], v[88:91]
	ds_read_b128 v[230:233], v235 offset:19456
	v_mfma_f32_16x16x32_bf16 v[80:83], v[144:147], v[202:205], v[80:83]
	global_load_lds_dwordx4 v236, s[26:27]
	v_mfma_f32_16x16x32_bf16 v[72:75], v[152:155], v[194:197], v[72:75]
	v_mfma_f32_16x16x32_bf16 v[64:67], v[152:155], v[202:205], v[64:67]
	s_add_u32 m0, s40, 0x12000
	v_mfma_f32_16x16x32_bf16 v[120:123], v[132:135], v[198:201], v[120:123]
	v_mfma_f32_16x16x32_bf16 v[112:115], v[132:135], v[206:209], v[112:115]
	global_load_lds_dwordx4 v237, s[26:27]
	v_mfma_f32_16x16x32_bf16 v[104:107], v[140:143], v[198:201], v[104:107]
	v_mfma_f32_16x16x32_bf16 v[96:99], v[140:143], v[206:209], v[96:99]
	s_add_u32 s26, s26, 0x80
	s_addc_u32 s27, s27, 0
	v_mfma_f32_16x16x32_bf16 v[88:91], v[148:151], v[198:201], v[88:91]
	v_mfma_f32_16x16x32_bf16 v[80:83], v[148:151], v[206:209], v[80:83]
	v_mfma_f32_16x16x32_bf16 v[72:75], v[156:159], v[198:201], v[72:75]
	v_mfma_f32_16x16x32_bf16 v[64:67], v[156:159], v[206:209], v[64:67]
	s_waitcnt vmcnt(12) lgkmcnt(0)
	s_barrier
	v_mfma_f32_16x16x32_bf16 v[124:127], v[128:131], v[218:221], v[124:127]
	v_mfma_f32_16x16x32_bf16 v[116:119], v[128:131], v[226:229], v[116:119]
	ds_read_b128 v[160:163], v234 offset:16384
	v_mfma_f32_16x16x32_bf16 v[108:111], v[136:139], v[218:221], v[108:111]
	ds_read_b128 v[164:167], v234 offset:17408
	v_mfma_f32_16x16x32_bf16 v[100:103], v[136:139], v[226:229], v[100:103]
	ds_read_b128 v[168:171], v234 offset:18432
	s_add_u32 m0, s40, 0x14000
	v_mfma_f32_16x16x32_bf16 v[92:95], v[144:147], v[218:221], v[92:95]
	ds_read_b128 v[172:175], v234 offset:19456
	v_mfma_f32_16x16x32_bf16 v[84:87], v[144:147], v[226:229], v[84:87]
	ds_read_b128 v[176:179], v234 offset:20480
	global_load_lds_dwordx4 v236, s[38:39]
	v_mfma_f32_16x16x32_bf16 v[76:79], v[152:155], v[218:221], v[76:79]
	ds_read_b128 v[180:183], v234 offset:21504
	v_mfma_f32_16x16x32_bf16 v[68:71], v[152:155], v[226:229], v[68:71]
	ds_read_b128 v[184:187], v234 offset:22528
	s_add_u32 m0, s40, 0x16000
	v_mfma_f32_16x16x32_bf16 v[124:127], v[132:135], v[222:225], v[124:127]
	ds_read_b128 v[188:191], v234 offset:23552
	v_mfma_f32_16x16x32_bf16 v[116:119], v[132:135], v[230:233], v[116:119]
	global_load_lds_dwordx4 v237, s[38:39]
	v_mfma_f32_16x16x32_bf16 v[108:111], v[140:143], v[222:225], v[108:111]
	v_mfma_f32_16x16x32_bf16 v[100:103], v[140:143], v[230:233], v[100:103]
	s_add_u32 s38, s38, 0x80
	s_addc_u32 s39, s39, 0
	v_mfma_f32_16x16x32_bf16 v[92:95], v[148:151], v[222:225], v[92:95]
	v_mfma_f32_16x16x32_bf16 v[84:87], v[148:151], v[230:233], v[84:87]
	v_mfma_f32_16x16x32_bf16 v[76:79], v[156:159], v[222:225], v[76:79]
	v_mfma_f32_16x16x32_bf16 v[68:71], v[156:159], v[230:233], v[68:71]
	s_waitcnt vmcnt(12) lgkmcnt(0)
	s_barrier
; #define STAGE(P, BASE, br, kt) do { const u16* _gb = (BASE) + ((size_t)(br) * K + (size_t)(kt) * BK); \
;     __builtin_amdgcn_global_load_lds((const unsigned*)(_gb + goff0), (unsigned*)((char*)(P) + tid * 16), 16, 0, 0); \
;     __builtin_amdgcn_global_load_lds((const unsigned*)(_gb + (size_t)64 * K + goff0), (unsigned*)((char*)(P) + tid * 16 + 8192), 16, 0, 0); } while (0)
; #define LDA(dst, b, h) _Pragma("unroll") for (int m = 0; m < 4; ++m) _Pragma("unroll") for (int k = 0; k < 2; ++k) \
;     dst[m][k] = *reinterpret_cast<const bf16x8*>((char*)SA(b, h) + lds_byte(wr * 64 + m * 16 + fr, k * 32 + fq * 8))
; #define LDB(dst, b, h) _Pragma("unroll") for (int n = 0; n < 2; ++n) _Pragma("unroll") for (int k = 0; k < 2; ++k) \
;     dst[n][k] = *reinterpret_cast<const bf16x8*>((char*)SB(b, h) + lds_byte(wc * 32 + n * 16 + fr, k * 32 + fq * 8))
; #define WAIT_V(n) asm volatile("s_waitcnt vmcnt(" #n ")" ::: "memory")
; #define WAIT_L(n) asm volatile("s_waitcnt lgkmcnt(" #n ")" ::: "memory")
; #define BAR __builtin_amdgcn_s_barrier()
; #define SCHED __builtin_amdgcn_sched_barrier(0)
; __device__ __forceinline__ void gemm_phase(KP p, char* shmc, const u16* __restrict__ A,
;                                            const u16* __restrict__ Bt, const int N, const int K, const int mode,
;                                            const float* __restrict__ xin, const float resw) {
;     ...
;     for (int t = 0; t < nt - 2; t += 2) {
;       LDB(B0, 0, 0); SCHED; LDA(At, 0, 0); STAGE(SA(1, 1), A, brow + HALF, t + 1);
;       WAIT_L(8); BAR; WAIT_L(0); MMA(0, 0, At, B0); BAR; SCHED;
;       LDB(B1, 0, 1); STAGE(SB(0, 0), Bt, bcol, t + 2);
;       BAR; WAIT_L(0); MMA(0, 1, At, B1); BAR;
;       LDA(At, 0, 1); STAGE(SA(0, 0), A, brow, t + 2);
;       BAR; WAIT_L(0); MMA(1, 0, At, B0); BAR; SCHED;
;       STAGE(SB(0, 1), Bt, bcol + HALF, t + 2);
;       WAIT_V(6); BAR; MMA(1, 1, At, B1); BAR;
;       LDB(B0, 1, 0); SCHED; LDA(At, 1, 0); STAGE(SA(0, 1), A, brow + HALF, t + 2);
;       WAIT_L(8); BAR; WAIT_L(0); MMA(0, 0, At, B0); BAR; SCHED;
;       LDB(B1, 1, 1); STAGE(SB(1, 0), Bt, bcol, t + 3);
;       BAR; WAIT_L(0); MMA(0, 1, At, B1); BAR;
;       LDA(At, 1, 1); STAGE(SA(1, 0), A, brow, t + 3);
;       BAR; WAIT_L(0); MMA(1, 0, At, B0); BAR; SCHED;
;       STAGE(SB(1, 1), Bt, bcol + HALF, t + 3);
;       WAIT_V(6); BAR; MMA(1, 1, At, B1); BAR;
;     }
	v_mfma_f32_16x16x32_bf16 v[56:59], v[160:163], v[194:197], v[56:59]
	v_mfma_f32_16x16x32_bf16 v[48:51], v[160:163], v[202:205], v[48:51]
	ds_read_b128 v[128:131], v234 offset:32768
	v_mfma_f32_16x16x32_bf16 v[40:43], v[168:171], v[194:197], v[40:43]
	ds_read_b128 v[132:135], v234 offset:33792
	v_mfma_f32_16x16x32_bf16 v[32:35], v[168:171], v[202:205], v[32:35]
	ds_read_b128 v[136:139], v234 offset:34816
	s_add_u32 m0, s40, 0x4000
	v_mfma_f32_16x16x32_bf16 v[24:27], v[176:179], v[194:197], v[24:27]
	ds_read_b128 v[140:143], v234 offset:35840
	v_mfma_f32_16x16x32_bf16 v[16:19], v[176:179], v[202:205], v[16:19]
	ds_read_b128 v[144:147], v234 offset:36864
	global_load_lds_dwordx4 v236, s[8:9]
	v_mfma_f32_16x16x32_bf16 v[8:11], v[184:187], v[194:197], v[8:11]
	ds_read_b128 v[148:151], v234 offset:37888
	v_mfma_f32_16x16x32_bf16 v[0:3], v[184:187], v[202:205], v[0:3]
	ds_read_b128 v[152:155], v234 offset:38912
	s_add_u32 m0, s40, 0x6000
	v_mfma_f32_16x16x32_bf16 v[56:59], v[164:167], v[198:201], v[56:59]
	ds_read_b128 v[156:159], v234 offset:39936
	v_mfma_f32_16x16x32_bf16 v[48:51], v[164:167], v[206:209], v[48:51]
	global_load_lds_dwordx4 v237, s[8:9]
	v_mfma_f32_16x16x32_bf16 v[40:43], v[172:175], v[198:201], v[40:43]
	v_mfma_f32_16x16x32_bf16 v[32:35], v[172:175], v[206:209], v[32:35]
	s_add_u32 s8, s8, 0x80
	s_addc_u32 s9, s9, 0
	v_mfma_f32_16x16x32_bf16 v[24:27], v[180:183], v[198:201], v[24:27]
	v_mfma_f32_16x16x32_bf16 v[16:19], v[180:183], v[206:209], v[16:19]
	v_mfma_f32_16x16x32_bf16 v[8:11], v[188:191], v[198:201], v[8:11]
	v_mfma_f32_16x16x32_bf16 v[0:3], v[188:191], v[206:209], v[0:3]
	s_waitcnt vmcnt(12) lgkmcnt(0)
	s_barrier
	v_mfma_f32_16x16x32_bf16 v[60:63], v[160:163], v[218:221], v[60:63]
	v_mfma_f32_16x16x32_bf16 v[52:55], v[160:163], v[226:229], v[52:55]
	ds_read_b128 v[194:197], v235 offset:32768
	v_mfma_f32_16x16x32_bf16 v[44:47], v[168:171], v[218:221], v[44:47]
	ds_read_b128 v[198:201], v235 offset:33792
	v_mfma_f32_16x16x32_bf16 v[36:39], v[168:171], v[226:229], v[36:39]
	ds_read_b128 v[202:205], v235 offset:34816
	s_add_u32 m0, s40, 0x8000
	v_mfma_f32_16x16x32_bf16 v[28:31], v[176:179], v[218:221], v[28:31]
	ds_read_b128 v[206:209], v235 offset:35840
	v_mfma_f32_16x16x32_bf16 v[20:23], v[176:179], v[226:229], v[20:23]
	global_load_lds_dwordx4 v236, s[36:37]
	v_mfma_f32_16x16x32_bf16 v[12:15], v[184:187], v[218:221], v[12:15]
	v_mfma_f32_16x16x32_bf16 v[4:7], v[184:187], v[226:229], v[4:7]
	s_add_u32 m0, s40, 0xa000
	v_mfma_f32_16x16x32_bf16 v[60:63], v[164:167], v[222:225], v[60:63]
	v_mfma_f32_16x16x32_bf16 v[52:55], v[164:167], v[230:233], v[52:55]
	global_load_lds_dwordx4 v237, s[36:37]
	v_mfma_f32_16x16x32_bf16 v[44:47], v[172:175], v[222:225], v[44:47]
	v_mfma_f32_16x16x32_bf16 v[36:39], v[172:175], v[230:233], v[36:39]
	s_add_u32 s36, s36, 0x80
	s_addc_u32 s37, s37, 0
	v_mfma_f32_16x16x32_bf16 v[28:31], v[180:183], v[222:225], v[28:31]
	v_mfma_f32_16x16x32_bf16 v[20:23], v[180:183], v[230:233], v[20:23]
	v_mfma_f32_16x16x32_bf16 v[12:15], v[188:191], v[222:225], v[12:15]
	v_mfma_f32_16x16x32_bf16 v[4:7], v[188:191], v[230:233], v[4:7]
	s_waitcnt vmcnt(12) lgkmcnt(0)
	s_barrier
	v_mfma_f32_16x16x32_bf16 v[120:123], v[128:131], v[194:197], v[120:123]
	v_mfma_f32_16x16x32_bf16 v[112:115], v[128:131], v[202:205], v[112:115]
	ds_read_b128 v[218:221], v235 offset:49152
	v_mfma_f32_16x16x32_bf16 v[104:107], v[136:139], v[194:197], v[104:107]
	ds_read_b128 v[222:225], v235 offset:50176
	v_mfma_f32_16x16x32_bf16 v[96:99], v[136:139], v[202:205], v[96:99]
	ds_read_b128 v[226:229], v235 offset:51200
	s_add_u32 m0, s40, 0x18000
	v_mfma_f32_16x16x32_bf16 v[88:91], v[144:147], v[194:197], v[88:91]
	ds_read_b128 v[230:233], v235 offset:52224
	v_mfma_f32_16x16x32_bf16 v[80:83], v[144:147], v[202:205], v[80:83]
	global_load_lds_dwordx4 v236, s[26:27]
	v_mfma_f32_16x16x32_bf16 v[72:75], v[152:155], v[194:197], v[72:75]
	v_mfma_f32_16x16x32_bf16 v[64:67], v[152:155], v[202:205], v[64:67]
	s_add_u32 m0, s40, 0x1a000
	v_mfma_f32_16x16x32_bf16 v[120:123], v[132:135], v[198:201], v[120:123]
	v_mfma_f32_16x16x32_bf16 v[112:115], v[132:135], v[206:209], v[112:115]
	global_load_lds_dwordx4 v237, s[26:27]
	v_mfma_f32_16x16x32_bf16 v[104:107], v[140:143], v[198:201], v[104:107]
	v_mfma_f32_16x16x32_bf16 v[96:99], v[140:143], v[206:209], v[96:99]
	s_add_u32 s26, s26, 0x80
	s_addc_u32 s27, s27, 0
	v_mfma_f32_16x16x32_bf16 v[88:91], v[148:151], v[198:201], v[88:91]
	v_mfma_f32_16x16x32_bf16 v[80:83], v[148:151], v[206:209], v[80:83]
	v_mfma_f32_16x16x32_bf16 v[72:75], v[156:159], v[198:201], v[72:75]
	v_mfma_f32_16x16x32_bf16 v[64:67], v[156:159], v[206:209], v[64:67]
	s_waitcnt vmcnt(12) lgkmcnt(0)
	s_barrier
	v_mfma_f32_16x16x32_bf16 v[124:127], v[128:131], v[218:221], v[124:127]
	v_mfma_f32_16x16x32_bf16 v[116:119], v[128:131], v[226:229], v[116:119]
	ds_read_b128 v[160:163], v234 offset:49152
	v_mfma_f32_16x16x32_bf16 v[108:111], v[136:139], v[218:221], v[108:111]
	ds_read_b128 v[164:167], v234 offset:50176
	v_mfma_f32_16x16x32_bf16 v[100:103], v[136:139], v[226:229], v[100:103]
	ds_read_b128 v[168:171], v234 offset:51200
	s_add_u32 m0, s40, 0x1c000
	v_mfma_f32_16x16x32_bf16 v[92:95], v[144:147], v[218:221], v[92:95]
	ds_read_b128 v[172:175], v234 offset:52224
	v_mfma_f32_16x16x32_bf16 v[84:87], v[144:147], v[226:229], v[84:87]
	ds_read_b128 v[176:179], v234 offset:53248
	global_load_lds_dwordx4 v236, s[38:39]
	v_mfma_f32_16x16x32_bf16 v[76:79], v[152:155], v[218:221], v[76:79]
	ds_read_b128 v[180:183], v234 offset:54272
	v_mfma_f32_16x16x32_bf16 v[68:71], v[152:155], v[226:229], v[68:71]
	ds_read_b128 v[184:187], v234 offset:55296
	s_add_u32 m0, s40, 0x1e000
	v_mfma_f32_16x16x32_bf16 v[124:127], v[132:135], v[222:225], v[124:127]
	ds_read_b128 v[188:191], v234 offset:56320
	v_mfma_f32_16x16x32_bf16 v[116:119], v[132:135], v[230:233], v[116:119]
	global_load_lds_dwordx4 v237, s[38:39]
	v_mfma_f32_16x16x32_bf16 v[108:111], v[140:143], v[222:225], v[108:111]
	v_mfma_f32_16x16x32_bf16 v[100:103], v[140:143], v[230:233], v[100:103]
	s_add_u32 s38, s38, 0x80
	s_addc_u32 s39, s39, 0
	v_mfma_f32_16x16x32_bf16 v[92:95], v[148:151], v[222:225], v[92:95]
	v_mfma_f32_16x16x32_bf16 v[84:87], v[148:151], v[230:233], v[84:87]
	v_mfma_f32_16x16x32_bf16 v[76:79], v[156:159], v[222:225], v[76:79]
	v_mfma_f32_16x16x32_bf16 v[68:71], v[156:159], v[230:233], v[68:71]
	s_waitcnt vmcnt(12) lgkmcnt(0)
	s_barrier
; #define STAGE(P, BASE, br, kt) do { const u16* _gb = (BASE) + ((size_t)(br) * K + (size_t)(kt) * BK); \
;     __builtin_amdgcn_global_load_lds((const unsigned*)(_gb + goff0), (unsigned*)((char*)(P) + tid * 16), 16, 0, 0); \
;     __builtin_amdgcn_global_load_lds((const unsigned*)(_gb + (size_t)64 * K + goff0), (unsigned*)((char*)(P) + tid * 16 + 8192), 16, 0, 0); } while (0)
; #define LDA(dst, b, h) _Pragma("unroll") for (int m = 0; m < 4; ++m) _Pragma("unroll") for (int k = 0; k < 2; ++k) \
;     dst[m][k] = *reinterpret_cast<const bf16x8*>((char*)SA(b, h) + lds_byte(wr * 64 + m * 16 + fr, k * 32 + fq * 8))
; #define LDB(dst, b, h) _Pragma("unroll") for (int n = 0; n < 2; ++n) _Pragma("unroll") for (int k = 0; k < 2; ++k) \
;     dst[n][k] = *reinterpret_cast<const bf16x8*>((char*)SB(b, h) + lds_byte(wc * 32 + n * 16 + fr, k * 32 + fq * 8))
; #define MMA(ai, bj, At, Bt_) do { __builtin_amdgcn_s_setprio(1); \
;     _Pragma("unroll") for (int m = 0; m < 4; ++m) _Pragma("unroll") for (int n = 0; n < 2; ++n) _Pragma("unroll") for (int k = 0; k < 2; ++k) \
;       acc[ai][bj][m][n] = __builtin_amdgcn_mfma_f32_16x16x32_bf16(Bt_[n][k], At[m][k], acc[ai][bj][m][n], 0, 0, 0); \
;     __builtin_amdgcn_s_setprio(0); } while (0)
; #define WAIT_V(n) asm volatile("s_waitcnt vmcnt(" #n ")" ::: "memory")
; __device__ __forceinline__ void gemm_phase(KP p, char* shmc, const u16* __restrict__ A,
;                                            const u16* __restrict__ Bt, const int N, const int K, const int mode,
;                                            const float* __restrict__ xin, const float resw) {
;     ...
;     { LDB(B0, 0, 0); LDA(At, 0, 0); STAGE(SA(1, 1), A, brow + HALF, nt - 1);
;       BAR; WAIT_L(0); MMA(0, 0, At, B0); BAR;
;       LDB(B1, 0, 1); BAR; WAIT_L(0); MMA(0, 1, At, B1); BAR;
;       LDA(At, 0, 1); WAIT_V(4); BAR; WAIT_L(0); MMA(1, 0, At, B0); MMA(1, 1, At, B1); BAR; }
;     { LDB(B0, 1, 0); LDA(At, 1, 0); WAIT_V(2); BAR; WAIT_L(0); MMA(0, 0, At, B0); BAR;
;       LDB(B1, 1, 1); WAIT_V(0); BAR; WAIT_L(0); MMA(0, 1, At, B1); BAR;
;       LDA(At, 1, 1); BAR; WAIT_L(0); MMA(1, 0, At, B0); MMA(1, 1, At, B1); BAR; }
;     if (wr == 0) BAR;
;     const int ntix = tix + gridDim.x;
;     int nbrow = 0, nbcol = 0, npn = 0;
;     if (ntix < nwg) {
;       TILE_MAP(ntix, nbrow, nbcol, npn);
;       TILE_PREFETCH(nbrow, nbcol, par ^ 1);
	v_mfma_f32_16x16x32_bf16 v[56:59], v[160:163], v[194:197], v[56:59]
	v_mfma_f32_16x16x32_bf16 v[48:51], v[160:163], v[202:205], v[48:51]
	ds_read_b128 v[128:131], v234 offset:0
	v_mfma_f32_16x16x32_bf16 v[40:43], v[168:171], v[194:197], v[40:43]
	ds_read_b128 v[132:135], v234 offset:1024
	v_mfma_f32_16x16x32_bf16 v[32:35], v[168:171], v[202:205], v[32:35]
	ds_read_b128 v[136:139], v234 offset:2048
	s_add_u32 m0, s40, 0xc000
	v_mfma_f32_16x16x32_bf16 v[24:27], v[176:179], v[194:197], v[24:27]
	ds_read_b128 v[140:143], v234 offset:3072
	v_mfma_f32_16x16x32_bf16 v[16:19], v[176:179], v[202:205], v[16:19]
	ds_read_b128 v[144:147], v234 offset:4096
	global_load_lds_dwordx4 v236, s[8:9]
	v_mfma_f32_16x16x32_bf16 v[8:11], v[184:187], v[194:197], v[8:11]
	ds_read_b128 v[148:151], v234 offset:5120
	v_mfma_f32_16x16x32_bf16 v[0:3], v[184:187], v[202:205], v[0:3]
	ds_read_b128 v[152:155], v234 offset:6144
	s_add_u32 m0, s40, 0xe000
	v_mfma_f32_16x16x32_bf16 v[56:59], v[164:167], v[198:201], v[56:59]
	ds_read_b128 v[156:159], v234 offset:7168
	v_mfma_f32_16x16x32_bf16 v[48:51], v[164:167], v[206:209], v[48:51]
	global_load_lds_dwordx4 v237, s[8:9]
	v_mfma_f32_16x16x32_bf16 v[40:43], v[172:175], v[198:201], v[40:43]
	v_mfma_f32_16x16x32_bf16 v[32:35], v[172:175], v[206:209], v[32:35]
	s_add_u32 s8, s8, 0x80
	s_addc_u32 s9, s9, 0
	v_mfma_f32_16x16x32_bf16 v[24:27], v[180:183], v[198:201], v[24:27]
	v_mfma_f32_16x16x32_bf16 v[16:19], v[180:183], v[206:209], v[16:19]
	v_mfma_f32_16x16x32_bf16 v[8:11], v[188:191], v[198:201], v[8:11]
	v_mfma_f32_16x16x32_bf16 v[0:3], v[188:191], v[206:209], v[0:3]
	s_waitcnt vmcnt(12) lgkmcnt(0)
	s_barrier
	v_mfma_f32_16x16x32_bf16 v[60:63], v[160:163], v[218:221], v[60:63]
	v_mfma_f32_16x16x32_bf16 v[52:55], v[160:163], v[226:229], v[52:55]
	ds_read_b128 v[194:197], v235 offset:0
	v_mfma_f32_16x16x32_bf16 v[44:47], v[168:171], v[218:221], v[44:47]
	ds_read_b128 v[198:201], v235 offset:1024
	v_mfma_f32_16x16x32_bf16 v[36:39], v[168:171], v[226:229], v[36:39]
	ds_read_b128 v[202:205], v235 offset:2048
	v_mfma_f32_16x16x32_bf16 v[28:31], v[176:179], v[218:221], v[28:31]
	ds_read_b128 v[206:209], v235 offset:3072
	v_mfma_f32_16x16x32_bf16 v[20:23], v[176:179], v[226:229], v[20:23]
	v_mfma_f32_16x16x32_bf16 v[12:15], v[184:187], v[218:221], v[12:15]
	v_mfma_f32_16x16x32_bf16 v[4:7], v[184:187], v[226:229], v[4:7]
	v_mfma_f32_16x16x32_bf16 v[60:63], v[164:167], v[222:225], v[60:63]
	v_mfma_f32_16x16x32_bf16 v[52:55], v[164:167], v[230:233], v[52:55]
	v_mfma_f32_16x16x32_bf16 v[44:47], v[172:175], v[222:225], v[44:47]
	v_mfma_f32_16x16x32_bf16 v[36:39], v[172:175], v[230:233], v[36:39]
	v_mfma_f32_16x16x32_bf16 v[28:31], v[180:183], v[222:225], v[28:31]
	v_mfma_f32_16x16x32_bf16 v[20:23], v[180:183], v[230:233], v[20:23]
	v_mfma_f32_16x16x32_bf16 v[12:15], v[188:191], v[222:225], v[12:15]
	v_mfma_f32_16x16x32_bf16 v[4:7], v[188:191], v[230:233], v[4:7]
	s_cmp_ge_i32 s66, s51
	s_cbranch_scc1 .Lmy_kloop_sw_t2plain
	s_mul_hi_i32 s27, s46, s50
	s_mul_i32 s26, s46, s50
	s_lshl_b64 s[26:27], s[26:27], 1
	s_add_u32 s26, s14, s26
	s_addc_u32 s27, s15, s27
	s_mul_hi_i32 s37, s43, s50
	s_mul_i32 s36, s43, s50
	s_lshl_b64 s[36:37], s[36:37], 1
	s_add_u32 s36, s12, s36
	s_addc_u32 s37, s13, s37
	s_lshl_b32 s41, s72, 1
	s_add_u32 s38, s26, s41
	s_addc_u32 s39, s27, 0
	s_add_u32 s8, s36, s41
	s_addc_u32 s9, s37, 0
	s_waitcnt vmcnt(10) lgkmcnt(0)
	s_barrier
	v_mfma_f32_16x16x32_bf16 v[120:123], v[128:131], v[194:197], v[120:123]
	v_mfma_f32_16x16x32_bf16 v[112:115], v[128:131], v[202:205], v[112:115]
	ds_read_b128 v[218:221], v235 offset:16384
	v_mfma_f32_16x16x32_bf16 v[104:107], v[136:139], v[194:197], v[104:107]
	ds_read_b128 v[222:225], v235 offset:17408
	s_add_u32 m0, s40, 0x10000
	v_mfma_f32_16x16x32_bf16 v[96:99], v[136:139], v[202:205], v[96:99]
	ds_read_b128 v[226:229], v235 offset:18432
	global_load_lds_dwordx4 v236, s[26:27]
	v_mfma_f32_16x16x32_bf16 v[88:91], v[144:147], v[194:197], v[88:91]
	ds_read_b128 v[230:233], v235 offset:19456
	s_add_u32 m0, s40, 0x12000
	v_mfma_f32_16x16x32_bf16 v[80:83], v[144:147], v[202:205], v[80:83]
	global_load_lds_dwordx4 v237, s[26:27]
	v_mfma_f32_16x16x32_bf16 v[72:75], v[152:155], v[194:197], v[72:75]
	s_add_u32 s26, s26, 0x80
	s_addc_u32 s27, s27, 0
	v_mfma_f32_16x16x32_bf16 v[64:67], v[152:155], v[202:205], v[64:67]
	s_add_u32 m0, s40, 0x0
	v_mfma_f32_16x16x32_bf16 v[120:123], v[132:135], v[198:201], v[120:123]
	global_load_lds_dwordx4 v236, s[36:37]
	v_mfma_f32_16x16x32_bf16 v[112:115], v[132:135], v[206:209], v[112:115]
	s_add_u32 m0, s40, 0x2000
	v_mfma_f32_16x16x32_bf16 v[104:107], v[140:143], v[198:201], v[104:107]
	global_load_lds_dwordx4 v237, s[36:37]
	v_mfma_f32_16x16x32_bf16 v[96:99], v[140:143], v[206:209], v[96:99]
	s_add_u32 s36, s36, 0x80
	s_addc_u32 s37, s37, 0
	v_mfma_f32_16x16x32_bf16 v[88:91], v[148:151], v[198:201], v[88:91]
	v_mfma_f32_16x16x32_bf16 v[80:83], v[148:151], v[206:209], v[80:83]
	v_mfma_f32_16x16x32_bf16 v[72:75], v[156:159], v[198:201], v[72:75]
	v_mfma_f32_16x16x32_bf16 v[64:67], v[156:159], v[206:209], v[64:67]
	s_waitcnt vmcnt(12) lgkmcnt(0)
	s_barrier
; #define STAGE(P, BASE, br, kt) do { const u16* _gb = (BASE) + ((size_t)(br) * K + (size_t)(kt) * BK); \
;     __builtin_amdgcn_global_load_lds((const unsigned*)(_gb + goff0), (unsigned*)((char*)(P) + tid * 16), 16, 0, 0); \
;     __builtin_amdgcn_global_load_lds((const unsigned*)(_gb + (size_t)64 * K + goff0), (unsigned*)((char*)(P) + tid * 16 + 8192), 16, 0, 0); } while (0)
; #define LDA(dst, b, h) _Pragma("unroll") for (int m = 0; m < 4; ++m) _Pragma("unroll") for (int k = 0; k < 2; ++k) \
;     dst[m][k] = *reinterpret_cast<const bf16x8*>((char*)SA(b, h) + lds_byte(wr * 64 + m * 16 + fr, k * 32 + fq * 8))
; #define LDB(dst, b, h) _Pragma("unroll") for (int n = 0; n < 2; ++n) _Pragma("unroll") for (int k = 0; k < 2; ++k) \
;     dst[n][k] = *reinterpret_cast<const bf16x8*>((char*)SB(b, h) + lds_byte(wc * 32 + n * 16 + fr, k * 32 + fq * 8))
; #define MMA(ai, bj, At, Bt_) do { __builtin_amdgcn_s_setprio(1); \
;     _Pragma("unroll") for (int m = 0; m < 4; ++m) _Pragma("unroll") for (int n = 0; n < 2; ++n) _Pragma("unroll") for (int k = 0; k < 2; ++k) \
;       acc[ai][bj][m][n] = __builtin_amdgcn_mfma_f32_16x16x32_bf16(Bt_[n][k], At[m][k], acc[ai][bj][m][n], 0, 0, 0); \
;     __builtin_amdgcn_s_setprio(0); } while (0)
; #define WAIT_V(n) asm volatile("s_waitcnt vmcnt(" #n ")" ::: "memory")
; #define WAIT_L(n) asm volatile("s_waitcnt lgkmcnt(" #n ")" ::: "memory")
; #define BAR __builtin_amdgcn_s_barrier()
; __device__ __forceinline__ void gemm_phase(KP p, char* shmc, const u16* __restrict__ A,
;                                            const u16* __restrict__ Bt, const int N, const int K, const int mode,
;                                            const float* __restrict__ xin, const float resw) {
;     ...
;     { LDB(B0, 0, 0); LDA(At, 0, 0); STAGE(SA(1, 1), A, brow + HALF, nt - 1);
;       BAR; WAIT_L(0); MMA(0, 0, At, B0); BAR;
;       LDB(B1, 0, 1); BAR; WAIT_L(0); MMA(0, 1, At, B1); BAR;
;       LDA(At, 0, 1); WAIT_V(4); BAR; WAIT_L(0); MMA(1, 0, At, B0); MMA(1, 1, At, B1); BAR; }
;     { LDB(B0, 1, 0); LDA(At, 1, 0); WAIT_V(2); BAR; WAIT_L(0); MMA(0, 0, At, B0); BAR;
;       LDB(B1, 1, 1); WAIT_V(0); BAR; WAIT_L(0); MMA(0, 1, At, B1); BAR;
;       LDA(At, 1, 1); BAR; WAIT_L(0); MMA(1, 0, At, B0); MMA(1, 1, At, B1); BAR; }
	v_mfma_f32_16x16x32_bf16 v[124:127], v[128:131], v[218:221], v[124:127]
	v_mfma_f32_16x16x32_bf16 v[116:119], v[128:131], v[226:229], v[116:119]
	ds_read_b128 v[160:163], v234 offset:16384
	v_mfma_f32_16x16x32_bf16 v[108:111], v[136:139], v[218:221], v[108:111]
	ds_read_b128 v[164:167], v234 offset:17408
	v_mfma_f32_16x16x32_bf16 v[100:103], v[136:139], v[226:229], v[100:103]
	ds_read_b128 v[168:171], v234 offset:18432
	s_add_u32 m0, s40, 0x14000
	v_mfma_f32_16x16x32_bf16 v[92:95], v[144:147], v[218:221], v[92:95]
	ds_read_b128 v[172:175], v234 offset:19456
	v_mfma_f32_16x16x32_bf16 v[84:87], v[144:147], v[226:229], v[84:87]
	ds_read_b128 v[176:179], v234 offset:20480
	global_load_lds_dwordx4 v236, s[38:39]
	v_mfma_f32_16x16x32_bf16 v[76:79], v[152:155], v[218:221], v[76:79]
	ds_read_b128 v[180:183], v234 offset:21504
	v_mfma_f32_16x16x32_bf16 v[68:71], v[152:155], v[226:229], v[68:71]
	ds_read_b128 v[184:187], v234 offset:22528
	s_add_u32 m0, s40, 0x16000
	v_mfma_f32_16x16x32_bf16 v[124:127], v[132:135], v[222:225], v[124:127]
	ds_read_b128 v[188:191], v234 offset:23552
	v_mfma_f32_16x16x32_bf16 v[116:119], v[132:135], v[230:233], v[116:119]
	global_load_lds_dwordx4 v237, s[38:39]
	v_mfma_f32_16x16x32_bf16 v[108:111], v[140:143], v[222:225], v[108:111]
	v_mfma_f32_16x16x32_bf16 v[100:103], v[140:143], v[230:233], v[100:103]
	s_add_u32 s38, s38, 0x80
	s_addc_u32 s39, s39, 0
	v_mfma_f32_16x16x32_bf16 v[92:95], v[148:151], v[222:225], v[92:95]
	v_mfma_f32_16x16x32_bf16 v[84:87], v[148:151], v[230:233], v[84:87]
	v_mfma_f32_16x16x32_bf16 v[76:79], v[156:159], v[222:225], v[76:79]
	v_mfma_f32_16x16x32_bf16 v[68:71], v[156:159], v[230:233], v[68:71]
	s_waitcnt vmcnt(12) lgkmcnt(0)
	s_barrier
	v_mfma_f32_16x16x32_bf16 v[56:59], v[160:163], v[194:197], v[56:59]
	v_mfma_f32_16x16x32_bf16 v[48:51], v[160:163], v[202:205], v[48:51]
	ds_read_b128 v[128:131], v234 offset:32768
	v_mfma_f32_16x16x32_bf16 v[40:43], v[168:171], v[194:197], v[40:43]
	ds_read_b128 v[132:135], v234 offset:33792
	v_mfma_f32_16x16x32_bf16 v[32:35], v[168:171], v[202:205], v[32:35]
	ds_read_b128 v[136:139], v234 offset:34816
	s_add_u32 m0, s40, 0x4000
	v_mfma_f32_16x16x32_bf16 v[24:27], v[176:179], v[194:197], v[24:27]
	ds_read_b128 v[140:143], v234 offset:35840
	v_mfma_f32_16x16x32_bf16 v[16:19], v[176:179], v[202:205], v[16:19]
	ds_read_b128 v[144:147], v234 offset:36864
	global_load_lds_dwordx4 v236, s[8:9]
	v_mfma_f32_16x16x32_bf16 v[8:11], v[184:187], v[194:197], v[8:11]
	ds_read_b128 v[148:151], v234 offset:37888
	v_mfma_f32_16x16x32_bf16 v[0:3], v[184:187], v[202:205], v[0:3]
	ds_read_b128 v[152:155], v234 offset:38912
	s_add_u32 m0, s40, 0x6000
	v_mfma_f32_16x16x32_bf16 v[56:59], v[164:167], v[198:201], v[56:59]
	ds_read_b128 v[156:159], v234 offset:39936
	v_mfma_f32_16x16x32_bf16 v[48:51], v[164:167], v[206:209], v[48:51]
	global_load_lds_dwordx4 v237, s[8:9]
	v_mfma_f32_16x16x32_bf16 v[40:43], v[172:175], v[198:201], v[40:43]
	v_mfma_f32_16x16x32_bf16 v[32:35], v[172:175], v[206:209], v[32:35]
	s_add_u32 s8, s8, 0x80
	s_addc_u32 s9, s9, 0
	v_mfma_f32_16x16x32_bf16 v[24:27], v[180:183], v[198:201], v[24:27]
	v_mfma_f32_16x16x32_bf16 v[16:19], v[180:183], v[206:209], v[16:19]
	v_mfma_f32_16x16x32_bf16 v[8:11], v[188:191], v[198:201], v[8:11]
	v_mfma_f32_16x16x32_bf16 v[0:3], v[188:191], v[206:209], v[0:3]
	s_waitcnt vmcnt(12) lgkmcnt(0)
	s_barrier
	v_mfma_f32_16x16x32_bf16 v[60:63], v[160:163], v[218:221], v[60:63]
	v_mfma_f32_16x16x32_bf16 v[52:55], v[160:163], v[226:229], v[52:55]
	ds_read_b128 v[194:197], v235 offset:32768
	v_mfma_f32_16x16x32_bf16 v[44:47], v[168:171], v[218:221], v[44:47]
	ds_read_b128 v[198:201], v235 offset:33792
	v_mfma_f32_16x16x32_bf16 v[36:39], v[168:171], v[226:229], v[36:39]
	ds_read_b128 v[202:205], v235 offset:34816
	s_add_u32 m0, s40, 0x8000
	v_mfma_f32_16x16x32_bf16 v[28:31], v[176:179], v[218:221], v[28:31]
	ds_read_b128 v[206:209], v235 offset:35840
	v_mfma_f32_16x16x32_bf16 v[20:23], v[176:179], v[226:229], v[20:23]
	global_load_lds_dwordx4 v236, s[36:37]
	v_mfma_f32_16x16x32_bf16 v[12:15], v[184:187], v[218:221], v[12:15]
	v_mfma_f32_16x16x32_bf16 v[4:7], v[184:187], v[226:229], v[4:7]
	s_add_u32 m0, s40, 0xa000
	v_mfma_f32_16x16x32_bf16 v[60:63], v[164:167], v[222:225], v[60:63]
	v_mfma_f32_16x16x32_bf16 v[52:55], v[164:167], v[230:233], v[52:55]
	global_load_lds_dwordx4 v237, s[36:37]
	v_mfma_f32_16x16x32_bf16 v[44:47], v[172:175], v[222:225], v[44:47]
	v_mfma_f32_16x16x32_bf16 v[36:39], v[172:175], v[230:233], v[36:39]
	s_add_u32 s36, s36, 0x80
	s_addc_u32 s37, s37, 0
	v_mfma_f32_16x16x32_bf16 v[28:31], v[180:183], v[222:225], v[28:31]
	v_mfma_f32_16x16x32_bf16 v[20:23], v[180:183], v[230:233], v[20:23]
	v_mfma_f32_16x16x32_bf16 v[12:15], v[188:191], v[222:225], v[12:15]
	v_mfma_f32_16x16x32_bf16 v[4:7], v[188:191], v[230:233], v[4:7]
	s_waitcnt vmcnt(12) lgkmcnt(0)
	s_barrier
; #define STAGE(P, BASE, br, kt) do { const u16* _gb = (BASE) + ((size_t)(br) * K + (size_t)(kt) * BK); \
;     __builtin_amdgcn_global_load_lds((const unsigned*)(_gb + goff0), (unsigned*)((char*)(P) + tid * 16), 16, 0, 0); \
;     __builtin_amdgcn_global_load_lds((const unsigned*)(_gb + (size_t)64 * K + goff0), (unsigned*)((char*)(P) + tid * 16 + 8192), 16, 0, 0); } while (0)
; #define LDA(dst, b, h) _Pragma("unroll") for (int m = 0; m < 4; ++m) _Pragma("unroll") for (int k = 0; k < 2; ++k) \
;     dst[m][k] = *reinterpret_cast<const bf16x8*>((char*)SA(b, h) + lds_byte(wr * 64 + m * 16 + fr, k * 32 + fq * 8))
; #define LDB(dst, b, h) _Pragma("unroll") for (int n = 0; n < 2; ++n) _Pragma("unroll") for (int k = 0; k < 2; ++k) \
;     dst[n][k] = *reinterpret_cast<const bf16x8*>((char*)SB(b, h) + lds_byte(wc * 32 + n * 16 + fr, k * 32 + fq * 8))
; #define MMA(ai, bj, At, Bt_) do { __builtin_amdgcn_s_setprio(1); \
;     _Pragma("unroll") for (int m = 0; m < 4; ++m) _Pragma("unroll") for (int n = 0; n < 2; ++n) _Pragma("unroll") for (int k = 0; k < 2; ++k) \
;       acc[ai][bj][m][n] = __builtin_amdgcn_mfma_f32_16x16x32_bf16(Bt_[n][k], At[m][k], acc[ai][bj][m][n], 0, 0, 0); \
;     __builtin_amdgcn_s_setprio(0); } while (0)
; #define WAIT_V(n) asm volatile("s_waitcnt vmcnt(" #n ")" ::: "memory")
; __device__ __forceinline__ void gemm_phase(KP p, char* shmc, const u16* __restrict__ A,
;                                            const u16* __restrict__ Bt, const int N, const int K, const int mode,
;                                            const float* __restrict__ xin, const float resw) {
;     ...
;     { LDB(B0, 0, 0); LDA(At, 0, 0); STAGE(SA(1, 1), A, brow + HALF, nt - 1);
;       BAR; WAIT_L(0); MMA(0, 0, At, B0); BAR;
;       LDB(B1, 0, 1); BAR; WAIT_L(0); MMA(0, 1, At, B1); BAR;
;       LDA(At, 0, 1); WAIT_V(4); BAR; WAIT_L(0); MMA(1, 0, At, B0); MMA(1, 1, At, B1); BAR; }
;     { LDB(B0, 1, 0); LDA(At, 1, 0); WAIT_V(2); BAR; WAIT_L(0); MMA(0, 0, At, B0); BAR;
;       LDB(B1, 1, 1); WAIT_V(0); BAR; WAIT_L(0); MMA(0, 1, At, B1); BAR;
;       LDA(At, 1, 1); BAR; WAIT_L(0); MMA(1, 0, At, B0); MMA(1, 1, At, B1); BAR; }
;     if (wr == 0) BAR;
;     const int ntix = tix + gridDim.x;
;     int nbrow = 0, nbcol = 0, npn = 0;
;     if (ntix < nwg) {
;       TILE_MAP(ntix, nbrow, nbcol, npn);
;       TILE_PREFETCH(nbrow, nbcol, par ^ 1);
	v_mfma_f32_16x16x32_bf16 v[120:123], v[128:131], v[194:197], v[120:123]
	v_mfma_f32_16x16x32_bf16 v[112:115], v[128:131], v[202:205], v[112:115]
	ds_read_b128 v[218:221], v235 offset:49152
	v_mfma_f32_16x16x32_bf16 v[104:107], v[136:139], v[194:197], v[104:107]
	ds_read_b128 v[222:225], v235 offset:50176
	v_mfma_f32_16x16x32_bf16 v[96:99], v[136:139], v[202:205], v[96:99]
	ds_read_b128 v[226:229], v235 offset:51200
	s_add_u32 m0, s40, 0x18000
	v_mfma_f32_16x16x32_bf16 v[88:91], v[144:147], v[194:197], v[88:91]
	ds_read_b128 v[230:233], v235 offset:52224
	v_mfma_f32_16x16x32_bf16 v[80:83], v[144:147], v[202:205], v[80:83]
	global_load_lds_dwordx4 v236, s[26:27]
	v_mfma_f32_16x16x32_bf16 v[72:75], v[152:155], v[194:197], v[72:75]
	v_mfma_f32_16x16x32_bf16 v[64:67], v[152:155], v[202:205], v[64:67]
	s_add_u32 m0, s40, 0x1a000
	v_mfma_f32_16x16x32_bf16 v[120:123], v[132:135], v[198:201], v[120:123]
	v_mfma_f32_16x16x32_bf16 v[112:115], v[132:135], v[206:209], v[112:115]
	global_load_lds_dwordx4 v237, s[26:27]
	v_mfma_f32_16x16x32_bf16 v[104:107], v[140:143], v[198:201], v[104:107]
	v_mfma_f32_16x16x32_bf16 v[96:99], v[140:143], v[206:209], v[96:99]
	s_add_u32 s26, s26, 0x80
	s_addc_u32 s27, s27, 0
	v_mfma_f32_16x16x32_bf16 v[88:91], v[148:151], v[198:201], v[88:91]
	v_mfma_f32_16x16x32_bf16 v[80:83], v[148:151], v[206:209], v[80:83]
	v_mfma_f32_16x16x32_bf16 v[72:75], v[156:159], v[198:201], v[72:75]
	v_mfma_f32_16x16x32_bf16 v[64:67], v[156:159], v[206:209], v[64:67]
	s_waitcnt vmcnt(12) lgkmcnt(0)
	s_barrier
	v_mfma_f32_16x16x32_bf16 v[124:127], v[128:131], v[218:221], v[124:127]
	v_mfma_f32_16x16x32_bf16 v[116:119], v[128:131], v[226:229], v[116:119]
	ds_read_b128 v[160:163], v234 offset:49152
	v_mfma_f32_16x16x32_bf16 v[108:111], v[136:139], v[218:221], v[108:111]
	ds_read_b128 v[164:167], v234 offset:50176
	v_mfma_f32_16x16x32_bf16 v[100:103], v[136:139], v[226:229], v[100:103]
	ds_read_b128 v[168:171], v234 offset:51200
	s_add_u32 m0, s40, 0x1c000
	v_mfma_f32_16x16x32_bf16 v[92:95], v[144:147], v[218:221], v[92:95]
	ds_read_b128 v[172:175], v234 offset:52224
	v_mfma_f32_16x16x32_bf16 v[84:87], v[144:147], v[226:229], v[84:87]
	ds_read_b128 v[176:179], v234 offset:53248
	global_load_lds_dwordx4 v236, s[38:39]
	v_mfma_f32_16x16x32_bf16 v[76:79], v[152:155], v[218:221], v[76:79]
	ds_read_b128 v[180:183], v234 offset:54272
	v_mfma_f32_16x16x32_bf16 v[68:71], v[152:155], v[226:229], v[68:71]
	ds_read_b128 v[184:187], v234 offset:55296
	s_add_u32 m0, s40, 0x1e000
	v_mfma_f32_16x16x32_bf16 v[124:127], v[132:135], v[222:225], v[124:127]
	ds_read_b128 v[188:191], v234 offset:56320
	v_mfma_f32_16x16x32_bf16 v[116:119], v[132:135], v[230:233], v[116:119]
	global_load_lds_dwordx4 v237, s[38:39]
	v_mfma_f32_16x16x32_bf16 v[108:111], v[140:143], v[222:225], v[108:111]
	v_mfma_f32_16x16x32_bf16 v[100:103], v[140:143], v[230:233], v[100:103]
	s_add_u32 s38, s38, 0x80
	s_addc_u32 s39, s39, 0
	v_mfma_f32_16x16x32_bf16 v[92:95], v[148:151], v[222:225], v[92:95]
	v_mfma_f32_16x16x32_bf16 v[84:87], v[148:151], v[230:233], v[84:87]
	v_mfma_f32_16x16x32_bf16 v[76:79], v[156:159], v[222:225], v[76:79]
	v_mfma_f32_16x16x32_bf16 v[68:71], v[156:159], v[230:233], v[68:71]
	s_waitcnt lgkmcnt(0)
	s_barrier
	v_mfma_f32_16x16x32_bf16 v[56:59], v[160:163], v[194:197], v[56:59]
	v_mfma_f32_16x16x32_bf16 v[48:51], v[160:163], v[202:205], v[48:51]
	v_mfma_f32_16x16x32_bf16 v[40:43], v[168:171], v[194:197], v[40:43]
	v_mfma_f32_16x16x32_bf16 v[32:35], v[168:171], v[202:205], v[32:35]
	s_add_u32 m0, s40, 0xc000
	v_mfma_f32_16x16x32_bf16 v[24:27], v[176:179], v[194:197], v[24:27]
	v_mfma_f32_16x16x32_bf16 v[16:19], v[176:179], v[202:205], v[16:19]
	global_load_lds_dwordx4 v236, s[8:9]
	v_mfma_f32_16x16x32_bf16 v[8:11], v[184:187], v[194:197], v[8:11]
	v_mfma_f32_16x16x32_bf16 v[0:3], v[184:187], v[202:205], v[0:3]
	s_add_u32 m0, s40, 0xe000
	v_mfma_f32_16x16x32_bf16 v[56:59], v[164:167], v[198:201], v[56:59]
	v_mfma_f32_16x16x32_bf16 v[48:51], v[164:167], v[206:209], v[48:51]
	global_load_lds_dwordx4 v237, s[8:9]
	v_mfma_f32_16x16x32_bf16 v[40:43], v[172:175], v[198:201], v[40:43]
	v_mfma_f32_16x16x32_bf16 v[32:35], v[172:175], v[206:209], v[32:35]
	s_add_u32 s8, s8, 0x80
	s_addc_u32 s9, s9, 0
	v_mfma_f32_16x16x32_bf16 v[24:27], v[180:183], v[198:201], v[24:27]
	v_mfma_f32_16x16x32_bf16 v[16:19], v[180:183], v[206:209], v[16:19]
	v_mfma_f32_16x16x32_bf16 v[8:11], v[188:191], v[198:201], v[8:11]
	v_mfma_f32_16x16x32_bf16 v[0:3], v[188:191], v[206:209], v[0:3]
	v_mfma_f32_16x16x32_bf16 v[60:63], v[160:163], v[218:221], v[60:63]
	v_mfma_f32_16x16x32_bf16 v[52:55], v[160:163], v[226:229], v[52:55]
	v_mfma_f32_16x16x32_bf16 v[44:47], v[168:171], v[218:221], v[44:47]
	v_mfma_f32_16x16x32_bf16 v[36:39], v[168:171], v[226:229], v[36:39]
	v_mfma_f32_16x16x32_bf16 v[28:31], v[176:179], v[218:221], v[28:31]
	v_mfma_f32_16x16x32_bf16 v[20:23], v[176:179], v[226:229], v[20:23]
	v_mfma_f32_16x16x32_bf16 v[12:15], v[184:187], v[218:221], v[12:15]
	v_mfma_f32_16x16x32_bf16 v[4:7], v[184:187], v[226:229], v[4:7]
	v_mfma_f32_16x16x32_bf16 v[60:63], v[164:167], v[222:225], v[60:63]
	v_mfma_f32_16x16x32_bf16 v[52:55], v[164:167], v[230:233], v[52:55]
	v_mfma_f32_16x16x32_bf16 v[44:47], v[172:175], v[222:225], v[44:47]
	v_mfma_f32_16x16x32_bf16 v[36:39], v[172:175], v[230:233], v[36:39]
	v_mfma_f32_16x16x32_bf16 v[28:31], v[180:183], v[222:225], v[28:31]
	v_mfma_f32_16x16x32_bf16 v[20:23], v[180:183], v[230:233], v[20:23]
	v_mfma_f32_16x16x32_bf16 v[12:15], v[188:191], v[222:225], v[12:15]
	v_mfma_f32_16x16x32_bf16 v[4:7], v[188:191], v[230:233], v[4:7]
	s_branch .Lmy_kloop_sw_end
; #define STAGE(P, BASE, br, kt) do { const u16* _gb = (BASE) + ((size_t)(br) * K + (size_t)(kt) * BK); \
;     __builtin_amdgcn_global_load_lds((const unsigned*)(_gb + goff0), (unsigned*)((char*)(P) + tid * 16), 16, 0, 0); \
;     __builtin_amdgcn_global_load_lds((const unsigned*)(_gb + (size_t)64 * K + goff0), (unsigned*)((char*)(P) + tid * 16 + 8192), 16, 0, 0); } while (0)
; #define LDA(dst, b, h) _Pragma("unroll") for (int m = 0; m < 4; ++m) _Pragma("unroll") for (int k = 0; k < 2; ++k) \
;     dst[m][k] = *reinterpret_cast<const bf16x8*>((char*)SA(b, h) + lds_byte(wr * 64 + m * 16 + fr, k * 32 + fq * 8))
; #define LDB(dst, b, h) _Pragma("unroll") for (int n = 0; n < 2; ++n) _Pragma("unroll") for (int k = 0; k < 2; ++k) \
;     dst[n][k] = *reinterpret_cast<const bf16x8*>((char*)SB(b, h) + lds_byte(wc * 32 + n * 16 + fr, k * 32 + fq * 8))
; #define MMA(ai, bj, At, Bt_) do { __builtin_amdgcn_s_setprio(1); \
;     _Pragma("unroll") for (int m = 0; m < 4; ++m) _Pragma("unroll") for (int n = 0; n < 2; ++n) _Pragma("unroll") for (int k = 0; k < 2; ++k) \
;       acc[ai][bj][m][n] = __builtin_amdgcn_mfma_f32_16x16x32_bf16(Bt_[n][k], At[m][k], acc[ai][bj][m][n], 0, 0, 0); \
;     __builtin_amdgcn_s_setprio(0); } while (0)
; #define WAIT_V(n) asm volatile("s_waitcnt vmcnt(" #n ")" ::: "memory")
; #define WAIT_L(n) asm volatile("s_waitcnt lgkmcnt(" #n ")" ::: "memory")
; #define BAR __builtin_amdgcn_s_barrier()
; __device__ __forceinline__ void gemm_phase(KP p, char* shmc, const u16* __restrict__ A,
;                                            const u16* __restrict__ Bt, const int N, const int K, const int mode,
;                                            const float* __restrict__ xin, const float resw) {
;     ...
;     { LDB(B0, 0, 0); LDA(At, 0, 0); STAGE(SA(1, 1), A, brow + HALF, nt - 1);
;       BAR; WAIT_L(0); MMA(0, 0, At, B0); BAR;
;       LDB(B1, 0, 1); BAR; WAIT_L(0); MMA(0, 1, At, B1); BAR;
;       LDA(At, 0, 1); WAIT_V(4); BAR; WAIT_L(0); MMA(1, 0, At, B0); MMA(1, 1, At, B1); BAR; }
;     { LDB(B0, 1, 0); LDA(At, 1, 0); WAIT_V(2); BAR; WAIT_L(0); MMA(0, 0, At, B0); BAR;
;       LDB(B1, 1, 1); WAIT_V(0); BAR; WAIT_L(0); MMA(0, 1, At, B1); BAR;
;       LDA(At, 1, 1); BAR; WAIT_L(0); MMA(1, 0, At, B0); MMA(1, 1, At, B1); BAR; }
.Lmy_kloop_sw_t2plain:
	s_waitcnt vmcnt(10) lgkmcnt(0)
	s_barrier
	v_mfma_f32_16x16x32_bf16 v[120:123], v[128:131], v[194:197], v[120:123]
	v_mfma_f32_16x16x32_bf16 v[112:115], v[128:131], v[202:205], v[112:115]
	ds_read_b128 v[218:221], v235 offset:16384
	v_mfma_f32_16x16x32_bf16 v[104:107], v[136:139], v[194:197], v[104:107]
	ds_read_b128 v[222:225], v235 offset:17408
	v_mfma_f32_16x16x32_bf16 v[96:99], v[136:139], v[202:205], v[96:99]
	ds_read_b128 v[226:229], v235 offset:18432
	v_mfma_f32_16x16x32_bf16 v[88:91], v[144:147], v[194:197], v[88:91]
	ds_read_b128 v[230:233], v235 offset:19456
	v_mfma_f32_16x16x32_bf16 v[80:83], v[144:147], v[202:205], v[80:83]
	v_mfma_f32_16x16x32_bf16 v[72:75], v[152:155], v[194:197], v[72:75]
	v_mfma_f32_16x16x32_bf16 v[64:67], v[152:155], v[202:205], v[64:67]
	v_mfma_f32_16x16x32_bf16 v[120:123], v[132:135], v[198:201], v[120:123]
	v_mfma_f32_16x16x32_bf16 v[112:115], v[132:135], v[206:209], v[112:115]
	v_mfma_f32_16x16x32_bf16 v[104:107], v[140:143], v[198:201], v[104:107]
	v_mfma_f32_16x16x32_bf16 v[96:99], v[140:143], v[206:209], v[96:99]
	v_mfma_f32_16x16x32_bf16 v[88:91], v[148:151], v[198:201], v[88:91]
	v_mfma_f32_16x16x32_bf16 v[80:83], v[148:151], v[206:209], v[80:83]
	v_mfma_f32_16x16x32_bf16 v[72:75], v[156:159], v[198:201], v[72:75]
	v_mfma_f32_16x16x32_bf16 v[64:67], v[156:159], v[206:209], v[64:67]
	s_waitcnt vmcnt(8) lgkmcnt(0)
	s_barrier
	v_mfma_f32_16x16x32_bf16 v[124:127], v[128:131], v[218:221], v[124:127]
	v_mfma_f32_16x16x32_bf16 v[116:119], v[128:131], v[226:229], v[116:119]
	ds_read_b128 v[160:163], v234 offset:16384
	v_mfma_f32_16x16x32_bf16 v[108:111], v[136:139], v[218:221], v[108:111]
	ds_read_b128 v[164:167], v234 offset:17408
	v_mfma_f32_16x16x32_bf16 v[100:103], v[136:139], v[226:229], v[100:103]
	ds_read_b128 v[168:171], v234 offset:18432
	v_mfma_f32_16x16x32_bf16 v[92:95], v[144:147], v[218:221], v[92:95]
	ds_read_b128 v[172:175], v234 offset:19456
	v_mfma_f32_16x16x32_bf16 v[84:87], v[144:147], v[226:229], v[84:87]
	ds_read_b128 v[176:179], v234 offset:20480
	v_mfma_f32_16x16x32_bf16 v[76:79], v[152:155], v[218:221], v[76:79]
	ds_read_b128 v[180:183], v234 offset:21504
	v_mfma_f32_16x16x32_bf16 v[68:71], v[152:155], v[226:229], v[68:71]
	ds_read_b128 v[184:187], v234 offset:22528
	v_mfma_f32_16x16x32_bf16 v[124:127], v[132:135], v[222:225], v[124:127]
	ds_read_b128 v[188:191], v234 offset:23552
	v_mfma_f32_16x16x32_bf16 v[116:119], v[132:135], v[230:233], v[116:119]
	v_mfma_f32_16x16x32_bf16 v[108:111], v[140:143], v[222:225], v[108:111]
	v_mfma_f32_16x16x32_bf16 v[100:103], v[140:143], v[230:233], v[100:103]
	v_mfma_f32_16x16x32_bf16 v[92:95], v[148:151], v[222:225], v[92:95]
	v_mfma_f32_16x16x32_bf16 v[84:87], v[148:151], v[230:233], v[84:87]
	v_mfma_f32_16x16x32_bf16 v[76:79], v[156:159], v[222:225], v[76:79]
	v_mfma_f32_16x16x32_bf16 v[68:71], v[156:159], v[230:233], v[68:71]
	s_waitcnt vmcnt(6) lgkmcnt(0)
	s_barrier
	v_mfma_f32_16x16x32_bf16 v[56:59], v[160:163], v[194:197], v[56:59]
	v_mfma_f32_16x16x32_bf16 v[48:51], v[160:163], v[202:205], v[48:51]
	ds_read_b128 v[128:131], v234 offset:32768
	v_mfma_f32_16x16x32_bf16 v[40:43], v[168:171], v[194:197], v[40:43]
	ds_read_b128 v[132:135], v234 offset:33792
	v_mfma_f32_16x16x32_bf16 v[32:35], v[168:171], v[202:205], v[32:35]
	ds_read_b128 v[136:139], v234 offset:34816
	v_mfma_f32_16x16x32_bf16 v[24:27], v[176:179], v[194:197], v[24:27]
	ds_read_b128 v[140:143], v234 offset:35840
	v_mfma_f32_16x16x32_bf16 v[16:19], v[176:179], v[202:205], v[16:19]
	ds_read_b128 v[144:147], v234 offset:36864
	v_mfma_f32_16x16x32_bf16 v[8:11], v[184:187], v[194:197], v[8:11]
	ds_read_b128 v[148:151], v234 offset:37888
	v_mfma_f32_16x16x32_bf16 v[0:3], v[184:187], v[202:205], v[0:3]
	ds_read_b128 v[152:155], v234 offset:38912
	v_mfma_f32_16x16x32_bf16 v[56:59], v[164:167], v[198:201], v[56:59]
	ds_read_b128 v[156:159], v234 offset:39936
	v_mfma_f32_16x16x32_bf16 v[48:51], v[164:167], v[206:209], v[48:51]
	v_mfma_f32_16x16x32_bf16 v[40:43], v[172:175], v[198:201], v[40:43]
	v_mfma_f32_16x16x32_bf16 v[32:35], v[172:175], v[206:209], v[32:35]
	v_mfma_f32_16x16x32_bf16 v[24:27], v[180:183], v[198:201], v[24:27]
	v_mfma_f32_16x16x32_bf16 v[16:19], v[180:183], v[206:209], v[16:19]
	v_mfma_f32_16x16x32_bf16 v[8:11], v[188:191], v[198:201], v[8:11]
	v_mfma_f32_16x16x32_bf16 v[0:3], v[188:191], v[206:209], v[0:3]
	s_waitcnt vmcnt(4) lgkmcnt(0)
	s_barrier
	v_mfma_f32_16x16x32_bf16 v[60:63], v[160:163], v[218:221], v[60:63]
	v_mfma_f32_16x16x32_bf16 v[52:55], v[160:163], v[226:229], v[52:55]
	ds_read_b128 v[194:197], v235 offset:32768
	v_mfma_f32_16x16x32_bf16 v[44:47], v[168:171], v[218:221], v[44:47]
	ds_read_b128 v[198:201], v235 offset:33792
	v_mfma_f32_16x16x32_bf16 v[36:39], v[168:171], v[226:229], v[36:39]
	ds_read_b128 v[202:205], v235 offset:34816
	v_mfma_f32_16x16x32_bf16 v[28:31], v[176:179], v[218:221], v[28:31]
	ds_read_b128 v[206:209], v235 offset:35840
	v_mfma_f32_16x16x32_bf16 v[20:23], v[176:179], v[226:229], v[20:23]
	v_mfma_f32_16x16x32_bf16 v[12:15], v[184:187], v[218:221], v[12:15]
	v_mfma_f32_16x16x32_bf16 v[4:7], v[184:187], v[226:229], v[4:7]
	v_mfma_f32_16x16x32_bf16 v[60:63], v[164:167], v[222:225], v[60:63]
	v_mfma_f32_16x16x32_bf16 v[52:55], v[164:167], v[230:233], v[52:55]
	v_mfma_f32_16x16x32_bf16 v[44:47], v[172:175], v[222:225], v[44:47]
	v_mfma_f32_16x16x32_bf16 v[36:39], v[172:175], v[230:233], v[36:39]
	v_mfma_f32_16x16x32_bf16 v[28:31], v[180:183], v[222:225], v[28:31]
	v_mfma_f32_16x16x32_bf16 v[20:23], v[180:183], v[230:233], v[20:23]
	v_mfma_f32_16x16x32_bf16 v[12:15], v[188:191], v[222:225], v[12:15]
	v_mfma_f32_16x16x32_bf16 v[4:7], v[188:191], v[230:233], v[4:7]
	s_waitcnt vmcnt(2) lgkmcnt(0)
	s_barrier
; #define LDA(dst, b, h) _Pragma("unroll") for (int m = 0; m < 4; ++m) _Pragma("unroll") for (int k = 0; k < 2; ++k) \
;     dst[m][k] = *reinterpret_cast<const bf16x8*>((char*)SA(b, h) + lds_byte(wr * 64 + m * 16 + fr, k * 32 + fq * 8))
; #define LDB(dst, b, h) _Pragma("unroll") for (int n = 0; n < 2; ++n) _Pragma("unroll") for (int k = 0; k < 2; ++k) \
;     dst[n][k] = *reinterpret_cast<const bf16x8*>((char*)SB(b, h) + lds_byte(wc * 32 + n * 16 + fr, k * 32 + fq * 8))
; #define MMA(ai, bj, At, Bt_) do { __builtin_amdgcn_s_setprio(1); \
;     _Pragma("unroll") for (int m = 0; m < 4; ++m) _Pragma("unroll") for (int n = 0; n < 2; ++n) _Pragma("unroll") for (int k = 0; k < 2; ++k) \
;       acc[ai][bj][m][n] = __builtin_amdgcn_mfma_f32_16x16x32_bf16(Bt_[n][k], At[m][k], acc[ai][bj][m][n], 0, 0, 0); \
;     __builtin_amdgcn_s_setprio(0); } while (0)
; #define WAIT_V(n) asm volatile("s_waitcnt vmcnt(" #n ")" ::: "memory")
; #define WAIT_L(n) asm volatile("s_waitcnt lgkmcnt(" #n ")" ::: "memory")
; #define BAR __builtin_amdgcn_s_barrier()
; #define TILE_PREFETCH(brow_, bcol_, par_) do { \
;     STAGE(SB(0, 0), Bt, bcol_, 0); STAGE(SA(0, 0), A, brow_, 0); \
;     STAGE(SB(0, 1), Bt, (bcol_) + HALF, 0); STAGE(SA(0, 1), A, (brow_) + HALF, 0); \
;     STAGE(SB(1, 0), Bt, bcol_, 1); STAGE(SA(1, 0), A, brow_, 1); STAGE(SB(1, 1), Bt, (bcol_) + HALF, 1); } while (0)
; __device__ __forceinline__ void gemm_phase(KP p, char* shmc, const u16* __restrict__ A,
;                                            const u16* __restrict__ Bt, const int N, const int K, const int mode,
;                                            const float* __restrict__ xin, const float resw) {
;     ...
;     { LDB(B0, 1, 0); LDA(At, 1, 0); WAIT_V(2); BAR; WAIT_L(0); MMA(0, 0, At, B0); BAR;
;       LDB(B1, 1, 1); WAIT_V(0); BAR; WAIT_L(0); MMA(0, 1, At, B1); BAR;
;       LDA(At, 1, 1); BAR; WAIT_L(0); MMA(1, 0, At, B0); MMA(1, 1, At, B1); BAR; }
;     if (wr == 0) BAR;
;     const int ntix = tix + gridDim.x;
;     int nbrow = 0, nbcol = 0, npn = 0;
;     if (ntix < nwg) {
;       TILE_MAP(ntix, nbrow, nbcol, npn);
;       TILE_PREFETCH(nbrow, nbcol, par ^ 1);
;     }
;     float pv[16];
;     SINV_ISSUE(ntix < nwg, nbrow);
	v_mfma_f32_16x16x32_bf16 v[120:123], v[128:131], v[194:197], v[120:123]
	v_mfma_f32_16x16x32_bf16 v[112:115], v[128:131], v[202:205], v[112:115]
	ds_read_b128 v[218:221], v235 offset:49152
	v_mfma_f32_16x16x32_bf16 v[104:107], v[136:139], v[194:197], v[104:107]
	ds_read_b128 v[222:225], v235 offset:50176
	v_mfma_f32_16x16x32_bf16 v[96:99], v[136:139], v[202:205], v[96:99]
	ds_read_b128 v[226:229], v235 offset:51200
	v_mfma_f32_16x16x32_bf16 v[88:91], v[144:147], v[194:197], v[88:91]
	ds_read_b128 v[230:233], v235 offset:52224
	v_mfma_f32_16x16x32_bf16 v[80:83], v[144:147], v[202:205], v[80:83]
	v_mfma_f32_16x16x32_bf16 v[72:75], v[152:155], v[194:197], v[72:75]
	v_mfma_f32_16x16x32_bf16 v[64:67], v[152:155], v[202:205], v[64:67]
	v_mfma_f32_16x16x32_bf16 v[120:123], v[132:135], v[198:201], v[120:123]
	v_mfma_f32_16x16x32_bf16 v[112:115], v[132:135], v[206:209], v[112:115]
	v_mfma_f32_16x16x32_bf16 v[104:107], v[140:143], v[198:201], v[104:107]
	v_mfma_f32_16x16x32_bf16 v[96:99], v[140:143], v[206:209], v[96:99]
	v_mfma_f32_16x16x32_bf16 v[88:91], v[148:151], v[198:201], v[88:91]
	v_mfma_f32_16x16x32_bf16 v[80:83], v[148:151], v[206:209], v[80:83]
	v_mfma_f32_16x16x32_bf16 v[72:75], v[156:159], v[198:201], v[72:75]
	v_mfma_f32_16x16x32_bf16 v[64:67], v[156:159], v[206:209], v[64:67]
	s_waitcnt vmcnt(0) lgkmcnt(0)
	s_barrier
	v_mfma_f32_16x16x32_bf16 v[124:127], v[128:131], v[218:221], v[124:127]
	v_mfma_f32_16x16x32_bf16 v[116:119], v[128:131], v[226:229], v[116:119]
	ds_read_b128 v[160:163], v234 offset:49152
	v_mfma_f32_16x16x32_bf16 v[108:111], v[136:139], v[218:221], v[108:111]
	ds_read_b128 v[164:167], v234 offset:50176
	v_mfma_f32_16x16x32_bf16 v[100:103], v[136:139], v[226:229], v[100:103]
	ds_read_b128 v[168:171], v234 offset:51200
	v_mfma_f32_16x16x32_bf16 v[92:95], v[144:147], v[218:221], v[92:95]
	ds_read_b128 v[172:175], v234 offset:52224
	v_mfma_f32_16x16x32_bf16 v[84:87], v[144:147], v[226:229], v[84:87]
	ds_read_b128 v[176:179], v234 offset:53248
	v_mfma_f32_16x16x32_bf16 v[76:79], v[152:155], v[218:221], v[76:79]
	ds_read_b128 v[180:183], v234 offset:54272
	v_mfma_f32_16x16x32_bf16 v[68:71], v[152:155], v[226:229], v[68:71]
	ds_read_b128 v[184:187], v234 offset:55296
	v_mfma_f32_16x16x32_bf16 v[124:127], v[132:135], v[222:225], v[124:127]
	ds_read_b128 v[188:191], v234 offset:56320
	v_mfma_f32_16x16x32_bf16 v[116:119], v[132:135], v[230:233], v[116:119]
	v_mfma_f32_16x16x32_bf16 v[108:111], v[140:143], v[222:225], v[108:111]
	v_mfma_f32_16x16x32_bf16 v[100:103], v[140:143], v[230:233], v[100:103]
	v_mfma_f32_16x16x32_bf16 v[92:95], v[148:151], v[222:225], v[92:95]
	v_mfma_f32_16x16x32_bf16 v[84:87], v[148:151], v[230:233], v[84:87]
	v_mfma_f32_16x16x32_bf16 v[76:79], v[156:159], v[222:225], v[76:79]
	v_mfma_f32_16x16x32_bf16 v[68:71], v[156:159], v[230:233], v[68:71]
	s_waitcnt lgkmcnt(0)
	s_barrier
	v_mfma_f32_16x16x32_bf16 v[56:59], v[160:163], v[194:197], v[56:59]
	v_mfma_f32_16x16x32_bf16 v[48:51], v[160:163], v[202:205], v[48:51]
	v_mfma_f32_16x16x32_bf16 v[40:43], v[168:171], v[194:197], v[40:43]
	v_mfma_f32_16x16x32_bf16 v[32:35], v[168:171], v[202:205], v[32:35]
	v_mfma_f32_16x16x32_bf16 v[24:27], v[176:179], v[194:197], v[24:27]
	v_mfma_f32_16x16x32_bf16 v[16:19], v[176:179], v[202:205], v[16:19]
	v_mfma_f32_16x16x32_bf16 v[8:11], v[184:187], v[194:197], v[8:11]
	v_mfma_f32_16x16x32_bf16 v[0:3], v[184:187], v[202:205], v[0:3]
	v_mfma_f32_16x16x32_bf16 v[56:59], v[164:167], v[198:201], v[56:59]
	v_mfma_f32_16x16x32_bf16 v[48:51], v[164:167], v[206:209], v[48:51]
	v_mfma_f32_16x16x32_bf16 v[40:43], v[172:175], v[198:201], v[40:43]
	v_mfma_f32_16x16x32_bf16 v[32:35], v[172:175], v[206:209], v[32:35]
	v_mfma_f32_16x16x32_bf16 v[24:27], v[180:183], v[198:201], v[24:27]
	v_mfma_f32_16x16x32_bf16 v[16:19], v[180:183], v[206:209], v[16:19]
	v_mfma_f32_16x16x32_bf16 v[8:11], v[188:191], v[198:201], v[8:11]
	v_mfma_f32_16x16x32_bf16 v[0:3], v[188:191], v[206:209], v[0:3]
	v_mfma_f32_16x16x32_bf16 v[60:63], v[160:163], v[218:221], v[60:63]
	v_mfma_f32_16x16x32_bf16 v[52:55], v[160:163], v[226:229], v[52:55]
	v_mfma_f32_16x16x32_bf16 v[44:47], v[168:171], v[218:221], v[44:47]
	v_mfma_f32_16x16x32_bf16 v[36:39], v[168:171], v[226:229], v[36:39]
	v_mfma_f32_16x16x32_bf16 v[28:31], v[176:179], v[218:221], v[28:31]
	v_mfma_f32_16x16x32_bf16 v[20:23], v[176:179], v[226:229], v[20:23]
	v_mfma_f32_16x16x32_bf16 v[12:15], v[184:187], v[218:221], v[12:15]
	v_mfma_f32_16x16x32_bf16 v[4:7], v[184:187], v[226:229], v[4:7]
	v_mfma_f32_16x16x32_bf16 v[60:63], v[164:167], v[222:225], v[60:63]
	v_mfma_f32_16x16x32_bf16 v[52:55], v[164:167], v[230:233], v[52:55]
	v_mfma_f32_16x16x32_bf16 v[44:47], v[172:175], v[222:225], v[44:47]
	v_mfma_f32_16x16x32_bf16 v[36:39], v[172:175], v[230:233], v[36:39]
	v_mfma_f32_16x16x32_bf16 v[28:31], v[180:183], v[222:225], v[28:31]
	v_mfma_f32_16x16x32_bf16 v[20:23], v[180:183], v[230:233], v[20:23]
	v_mfma_f32_16x16x32_bf16 v[12:15], v[188:191], v[222:225], v[12:15]
	v_mfma_f32_16x16x32_bf16 v[4:7], v[188:191], v[230:233], v[4:7]
.Lmy_kloop_sw_end:
.Lmy_join:
	s_nop 7
	s_nop 7
	s_mov_b32 s26, s43
	s_mov_b32 s45, s46
	s_mov_b32 s44, s47
	s_cmp_ge_i32 s66, s51
	s_cselect_b64 s[6:7], -1, 0
